# GEMM K-loop: B0 fragment ds_reads issued one phase earlier (ph4/ph8 load segment) with counted vmcnt(10) one phase earlier; balances 12/4/8/0 reads to 8/4/8/4
# speedup vs baseline: 1.0147x; 1.0141x over previous
.LBB0_296:
	s_ashr_i32 s9, s8, 31
	v_cmp_lt_i64_e32 vcc, s[12:13], v[180:181]
	s_lshl_b64 s[12:13], s[8:9], 19
	s_add_u32 s12, s29, s12
	s_addc_u32 s13, s30, s13
	s_and_b64 s[14:15], vcc, exec
	s_cselect_b32 s9, s13, s21
	s_cselect_b32 s44, s12, s20
	s_ashr_i32 s7, s6, 31
	s_lshl_b64 s[14:15], s[6:7], 19
	s_add_u32 s14, s31, s14
	s_addc_u32 s15, s33, s15
	s_and_b64 s[24:25], vcc, exec
	s_cselect_b32 s7, s15, s23
	s_cselect_b32 s45, s14, s22
	s_add_u32 s20, s20, 0x40080
	s_addc_u32 s21, s21, 0
	s_add_u32 s46, s22, 0x100
	s_addc_u32 s47, s23, 0
	s_mov_b32 s48, -2
	s_add_u32 s22, s20, 0xfffc0080
	s_addc_u32 s23, s21, -1
	s_add_i32 s49, 0, 0x10000
	v_add_u32_e32 v145, s49, v142
	ds_read_b128 v[146:149], v145
	ds_read_b128 v[150:153], v145 offset:1024
	ds_read_b128 v[154:157], v145 offset:2048
	ds_read_b128 v[158:161], v145 offset:3072
	s_cmp_eq_u32 s48, 12
	s_cselect_b32 s25, s9, s23
	s_cselect_b32 s24, s44, s22
	s_cselect_b32 s23, s7, s47
	s_cselect_b32 s22, s45, s46
	s_add_i32 m0, s19, 0xc000
	ds_read_b128 v[162:165], v144
	ds_read_b128 v[166:169], v144 offset:1024
	ds_read_b128 v[170:173], v144 offset:2048
	ds_read_b128 v[174:177], v144 offset:3072
	ds_read_b128 v[190:193], v144 offset:4096
	ds_read_b128 v[194:197], v144 offset:5120
	ds_read_b128 v[198:201], v144 offset:6144
	ds_read_b128 v[202:205], v144 offset:7168
	global_load_lds_dwordx4 v138, s[20:21]
	s_add_i32 m0, s19, 0xe000
	s_nop 0
	global_load_lds_dwordx4 v140, s[20:21]
	s_waitcnt lgkmcnt(8)
	s_barrier
	s_waitcnt lgkmcnt(0)
	s_waitcnt lgkmcnt(0)
	v_mfma_f32_16x16x32_bf16 v[126:129], v[146:149], v[162:165], 0
	v_mfma_f32_16x16x32_bf16 v[118:121], v[154:157], v[162:165], 0
	v_mfma_f32_16x16x32_bf16 v[110:113], v[146:149], v[170:173], 0
	v_mfma_f32_16x16x32_bf16 v[102:105], v[154:157], v[170:173], 0
	v_mfma_f32_16x16x32_bf16 v[94:97], v[146:149], v[190:193], 0
	v_mfma_f32_16x16x32_bf16 v[86:89], v[154:157], v[190:193], 0
	v_mfma_f32_16x16x32_bf16 v[78:81], v[146:149], v[198:201], 0
	v_mfma_f32_16x16x32_bf16 v[70:73], v[154:157], v[198:201], 0
	v_mfma_f32_16x16x32_bf16 v[126:129], v[150:153], v[166:169], v[126:129]
	v_mfma_f32_16x16x32_bf16 v[118:121], v[158:161], v[166:169], v[118:121]
	v_mfma_f32_16x16x32_bf16 v[110:113], v[150:153], v[174:177], v[110:113]
	v_mfma_f32_16x16x32_bf16 v[102:105], v[158:161], v[174:177], v[102:105]
	v_mfma_f32_16x16x32_bf16 v[94:97], v[150:153], v[194:197], v[94:97]
	v_mfma_f32_16x16x32_bf16 v[86:89], v[158:161], v[194:197], v[86:89]
	v_mfma_f32_16x16x32_bf16 v[78:81], v[150:153], v[202:205], v[78:81]
	v_mfma_f32_16x16x32_bf16 v[70:73], v[158:161], v[202:205], v[70:73]
	s_barrier
	s_add_i32 s54, 0, 0x14000
	s_add_i32 s49, s49, s35
	v_add_u32_e32 v145, s54, v142
	s_add_u32 s64, s22, 0x80
	s_addc_u32 s65, s23, 0
	s_mov_b32 m0, s49
	ds_read_b128 v[206:209], v145
	ds_read_b128 v[210:213], v145 offset:1024
	ds_read_b128 v[214:217], v145 offset:2048
	ds_read_b128 v[218:221], v145 offset:3072
	global_load_lds_dwordx4 v134, s[22:23]
	s_add_i32 m0, s49, 0x2000
	s_nop 0
	global_load_lds_dwordx4 v130, s[22:23]
	s_barrier
	s_waitcnt lgkmcnt(0)
	s_waitcnt lgkmcnt(0)
	v_mfma_f32_16x16x32_bf16 v[122:125], v[206:209], v[162:165], 0
	v_mfma_f32_16x16x32_bf16 v[114:117], v[214:217], v[162:165], 0
	v_mfma_f32_16x16x32_bf16 v[106:109], v[206:209], v[170:173], 0
	v_mfma_f32_16x16x32_bf16 v[98:101], v[214:217], v[170:173], 0
	v_mfma_f32_16x16x32_bf16 v[90:93], v[206:209], v[190:193], 0
	v_mfma_f32_16x16x32_bf16 v[82:85], v[214:217], v[190:193], 0
	v_mfma_f32_16x16x32_bf16 v[74:77], v[206:209], v[198:201], 0
	v_mfma_f32_16x16x32_bf16 v[66:69], v[214:217], v[198:201], 0
	v_mfma_f32_16x16x32_bf16 v[122:125], v[210:213], v[166:169], v[122:125]
	v_mfma_f32_16x16x32_bf16 v[114:117], v[218:221], v[166:169], v[114:117]
	v_mfma_f32_16x16x32_bf16 v[106:109], v[210:213], v[174:177], v[106:109]
	v_mfma_f32_16x16x32_bf16 v[98:101], v[218:221], v[174:177], v[98:101]
	v_mfma_f32_16x16x32_bf16 v[90:93], v[210:213], v[194:197], v[90:93]
	v_mfma_f32_16x16x32_bf16 v[82:85], v[218:221], v[194:197], v[82:85]
	v_mfma_f32_16x16x32_bf16 v[74:77], v[210:213], v[202:205], v[74:77]
	v_mfma_f32_16x16x32_bf16 v[66:69], v[218:221], v[202:205], v[66:69]
	s_barrier
	s_mov_b32 m0, s19
	s_add_u32 s62, s24, 0x80
	s_addc_u32 s63, s25, 0
	ds_read_b128 v[162:165], v144 offset:16384
	ds_read_b128 v[166:169], v144 offset:17408
	ds_read_b128 v[170:173], v144 offset:18432
	ds_read_b128 v[174:177], v144 offset:19456
	ds_read_b128 v[190:193], v144 offset:20480
	ds_read_b128 v[194:197], v144 offset:21504
	ds_read_b128 v[198:201], v144 offset:22528
	ds_read_b128 v[202:205], v144 offset:23552
	global_load_lds_dwordx4 v136, s[24:25]
	s_mov_b32 m0, s36
	s_nop 0
	global_load_lds_dwordx4 v132, s[24:25]
	s_waitcnt vmcnt(10)
	s_barrier
	s_waitcnt lgkmcnt(0)
	s_waitcnt lgkmcnt(0)
	v_mfma_f32_16x16x32_bf16 v[62:65], v[146:149], v[162:165], 0
	v_mfma_f32_16x16x32_bf16 v[54:57], v[154:157], v[162:165], 0
	v_mfma_f32_16x16x32_bf16 v[46:49], v[146:149], v[170:173], 0
	v_mfma_f32_16x16x32_bf16 v[38:41], v[154:157], v[170:173], 0
	v_mfma_f32_16x16x32_bf16 v[30:33], v[146:149], v[190:193], 0
	v_mfma_f32_16x16x32_bf16 v[22:25], v[154:157], v[190:193], 0
	v_mfma_f32_16x16x32_bf16 v[14:17], v[146:149], v[198:201], 0
	v_mfma_f32_16x16x32_bf16 v[6:9], v[154:157], v[198:201], 0
	v_mfma_f32_16x16x32_bf16 v[62:65], v[150:153], v[166:169], v[62:65]
	v_mfma_f32_16x16x32_bf16 v[54:57], v[158:161], v[166:169], v[54:57]
	v_mfma_f32_16x16x32_bf16 v[46:49], v[150:153], v[174:177], v[46:49]
	v_mfma_f32_16x16x32_bf16 v[38:41], v[158:161], v[174:177], v[38:41]
	v_mfma_f32_16x16x32_bf16 v[30:33], v[150:153], v[194:197], v[30:33]
	v_mfma_f32_16x16x32_bf16 v[22:25], v[158:161], v[194:197], v[22:25]
	v_mfma_f32_16x16x32_bf16 v[14:17], v[150:153], v[202:205], v[14:17]
	v_mfma_f32_16x16x32_bf16 v[6:9], v[158:161], v[202:205], v[6:9]
	s_barrier
	v_add_u32_e32 v158, 0x18000, v142
	ds_read_b128 v[146:149], v158
	ds_read_b128 v[150:153], v158 offset:1024
	ds_read_b128 v[154:157], v158 offset:2048
	ds_read_b128 v[158:161], v158 offset:3072
	s_add_u32 s50, s22, 0x40000
	s_addc_u32 s51, s23, 0
	s_add_i32 s49, s54, s35
	s_mov_b32 m0, s49
	s_nop 0
	global_load_lds_dwordx4 v134, s[50:51]
	s_add_i32 m0, s49, 0x2000
	s_nop 0
	global_load_lds_dwordx4 v130, s[50:51]
	s_waitcnt vmcnt(6)
	s_barrier
	v_mfma_f32_16x16x32_bf16 v[58:61], v[206:209], v[162:165], 0
	v_mfma_f32_16x16x32_bf16 v[50:53], v[214:217], v[162:165], 0
	v_mfma_f32_16x16x32_bf16 v[42:45], v[206:209], v[170:173], 0
	v_mfma_f32_16x16x32_bf16 v[34:37], v[214:217], v[170:173], 0
	v_mfma_f32_16x16x32_bf16 v[26:29], v[206:209], v[190:193], 0
	v_mfma_f32_16x16x32_bf16 v[18:21], v[214:217], v[190:193], 0
	v_mfma_f32_16x16x32_bf16 v[10:13], v[206:209], v[198:201], 0
	v_mfma_f32_16x16x32_bf16 v[2:5], v[214:217], v[198:201], 0
	v_mfma_f32_16x16x32_bf16 v[58:61], v[210:213], v[166:169], v[58:61]
	v_mfma_f32_16x16x32_bf16 v[50:53], v[218:221], v[166:169], v[50:53]
	v_mfma_f32_16x16x32_bf16 v[42:45], v[210:213], v[174:177], v[42:45]
	v_mfma_f32_16x16x32_bf16 v[34:37], v[218:221], v[174:177], v[34:37]
	v_mfma_f32_16x16x32_bf16 v[26:29], v[210:213], v[194:197], v[26:29]
	v_mfma_f32_16x16x32_bf16 v[18:21], v[218:221], v[194:197], v[18:21]
	v_mfma_f32_16x16x32_bf16 v[10:13], v[210:213], v[202:205], v[10:13]
	v_mfma_f32_16x16x32_bf16 v[2:5], v[218:221], v[202:205], v[2:5]
	s_barrier
	s_add_i32 s49, 0, 0x18000
	v_add_u32_e32 v145, s49, v142
	s_add_u32 s24, s24, 0x40000
	s_addc_u32 s25, s25, 0
	s_mov_b32 m0, s37
	ds_read_b128 v[162:165], v144 offset:32768
	ds_read_b128 v[166:169], v144 offset:33792
	ds_read_b128 v[170:173], v144 offset:34816
	ds_read_b128 v[174:177], v144 offset:35840
	ds_read_b128 v[190:193], v144 offset:36864
	ds_read_b128 v[194:197], v144 offset:37888
	ds_read_b128 v[198:201], v144 offset:38912
	ds_read_b128 v[202:205], v144 offset:39936
	global_load_lds_dwordx4 v136, s[24:25]
	s_mov_b32 m0, s38
	s_nop 0
	global_load_lds_dwordx4 v132, s[24:25]
	s_waitcnt lgkmcnt(8)
	s_barrier
	s_waitcnt lgkmcnt(0)
	s_waitcnt lgkmcnt(0)
	v_mfma_f32_16x16x32_bf16 v[126:129], v[146:149], v[162:165], v[126:129]
	v_mfma_f32_16x16x32_bf16 v[118:121], v[154:157], v[162:165], v[118:121]
	v_mfma_f32_16x16x32_bf16 v[110:113], v[146:149], v[170:173], v[110:113]
	v_mfma_f32_16x16x32_bf16 v[102:105], v[154:157], v[170:173], v[102:105]
	v_mfma_f32_16x16x32_bf16 v[94:97], v[146:149], v[190:193], v[94:97]
	v_mfma_f32_16x16x32_bf16 v[86:89], v[154:157], v[190:193], v[86:89]
	v_mfma_f32_16x16x32_bf16 v[78:81], v[146:149], v[198:201], v[78:81]
	v_mfma_f32_16x16x32_bf16 v[70:73], v[154:157], v[198:201], v[70:73]
	v_mfma_f32_16x16x32_bf16 v[126:129], v[150:153], v[166:169], v[126:129]
	v_mfma_f32_16x16x32_bf16 v[118:121], v[158:161], v[166:169], v[118:121]
	v_mfma_f32_16x16x32_bf16 v[110:113], v[150:153], v[174:177], v[110:113]
	v_mfma_f32_16x16x32_bf16 v[102:105], v[158:161], v[174:177], v[102:105]
	v_mfma_f32_16x16x32_bf16 v[94:97], v[150:153], v[194:197], v[94:97]
	v_mfma_f32_16x16x32_bf16 v[86:89], v[158:161], v[194:197], v[86:89]
	v_mfma_f32_16x16x32_bf16 v[78:81], v[150:153], v[202:205], v[78:81]
	v_mfma_f32_16x16x32_bf16 v[70:73], v[158:161], v[202:205], v[70:73]
	s_barrier
	s_add_i32 s24, 0, 0x1c000
	s_add_i32 s25, s49, s35
	v_add_u32_e32 v145, s24, v142
	s_mov_b32 m0, s25
	ds_read_b128 v[206:209], v145
	ds_read_b128 v[210:213], v145 offset:1024
	ds_read_b128 v[214:217], v145 offset:2048
	ds_read_b128 v[218:221], v145 offset:3072
	global_load_lds_dwordx4 v134, s[64:65]
	s_add_i32 m0, s25, 0x2000
	s_nop 0
	global_load_lds_dwordx4 v130, s[64:65]
	s_barrier
	s_waitcnt lgkmcnt(0)
	s_waitcnt lgkmcnt(0)
	v_mfma_f32_16x16x32_bf16 v[122:125], v[206:209], v[162:165], v[122:125]
	v_mfma_f32_16x16x32_bf16 v[114:117], v[214:217], v[162:165], v[114:117]
	v_mfma_f32_16x16x32_bf16 v[106:109], v[206:209], v[170:173], v[106:109]
	v_mfma_f32_16x16x32_bf16 v[98:101], v[214:217], v[170:173], v[98:101]
	v_mfma_f32_16x16x32_bf16 v[90:93], v[206:209], v[190:193], v[90:93]
	v_mfma_f32_16x16x32_bf16 v[82:85], v[214:217], v[190:193], v[82:85]
	v_mfma_f32_16x16x32_bf16 v[74:77], v[206:209], v[198:201], v[74:77]
	v_mfma_f32_16x16x32_bf16 v[66:69], v[214:217], v[198:201], v[66:69]
	v_mfma_f32_16x16x32_bf16 v[122:125], v[210:213], v[166:169], v[122:125]
	v_mfma_f32_16x16x32_bf16 v[114:117], v[218:221], v[166:169], v[114:117]
	v_mfma_f32_16x16x32_bf16 v[106:109], v[210:213], v[174:177], v[106:109]
	v_mfma_f32_16x16x32_bf16 v[98:101], v[218:221], v[174:177], v[98:101]
	v_mfma_f32_16x16x32_bf16 v[90:93], v[210:213], v[194:197], v[90:93]
	v_mfma_f32_16x16x32_bf16 v[82:85], v[218:221], v[194:197], v[82:85]
	v_mfma_f32_16x16x32_bf16 v[74:77], v[210:213], v[202:205], v[74:77]
	v_mfma_f32_16x16x32_bf16 v[66:69], v[218:221], v[202:205], v[66:69]
	s_barrier
	s_mov_b32 m0, s39
	ds_read_b128 v[162:165], v144 offset:49152
	ds_read_b128 v[166:169], v144 offset:50176
	ds_read_b128 v[170:173], v144 offset:51200
	ds_read_b128 v[174:177], v144 offset:52224
	ds_read_b128 v[190:193], v144 offset:53248
	ds_read_b128 v[194:197], v144 offset:54272
	ds_read_b128 v[198:201], v144 offset:55296
	ds_read_b128 v[202:205], v144 offset:56320
	global_load_lds_dwordx4 v136, s[62:63]
	s_mov_b32 m0, s40
	s_nop 0
	global_load_lds_dwordx4 v132, s[62:63]
	s_waitcnt vmcnt(10)
	s_barrier
	s_waitcnt lgkmcnt(0)
	s_waitcnt lgkmcnt(0)
	v_mfma_f32_16x16x32_bf16 v[62:65], v[146:149], v[162:165], v[62:65]
	v_mfma_f32_16x16x32_bf16 v[54:57], v[154:157], v[162:165], v[54:57]
	v_mfma_f32_16x16x32_bf16 v[46:49], v[146:149], v[170:173], v[46:49]
	v_mfma_f32_16x16x32_bf16 v[38:41], v[154:157], v[170:173], v[38:41]
	v_mfma_f32_16x16x32_bf16 v[30:33], v[146:149], v[190:193], v[30:33]
	v_mfma_f32_16x16x32_bf16 v[22:25], v[154:157], v[190:193], v[22:25]
	v_mfma_f32_16x16x32_bf16 v[14:17], v[146:149], v[198:201], v[14:17]
	v_mfma_f32_16x16x32_bf16 v[6:9], v[154:157], v[198:201], v[6:9]
	v_mfma_f32_16x16x32_bf16 v[62:65], v[150:153], v[166:169], v[62:65]
	v_mfma_f32_16x16x32_bf16 v[54:57], v[158:161], v[166:169], v[54:57]
	v_mfma_f32_16x16x32_bf16 v[46:49], v[150:153], v[174:177], v[46:49]
	v_mfma_f32_16x16x32_bf16 v[38:41], v[158:161], v[174:177], v[38:41]
	v_mfma_f32_16x16x32_bf16 v[30:33], v[150:153], v[194:197], v[30:33]
	v_mfma_f32_16x16x32_bf16 v[22:25], v[158:161], v[194:197], v[22:25]
	v_mfma_f32_16x16x32_bf16 v[14:17], v[150:153], v[202:205], v[14:17]
	v_mfma_f32_16x16x32_bf16 v[6:9], v[158:161], v[202:205], v[6:9]
	s_barrier
	v_add_u32_e32 v158, 0x10000, v142
	ds_read_b128 v[146:149], v158
	ds_read_b128 v[150:153], v158 offset:1024
	ds_read_b128 v[154:157], v158 offset:2048
	ds_read_b128 v[158:161], v158 offset:3072
	s_add_u32 s22, s22, 0x40080
	s_addc_u32 s23, s23, 0
	s_add_i32 s24, s24, s35
	s_mov_b32 m0, s24
	s_nop 0
	global_load_lds_dwordx4 v134, s[22:23]
	s_add_i32 m0, s24, 0x2000
	s_nop 0
	global_load_lds_dwordx4 v130, s[22:23]
	s_waitcnt vmcnt(6)
	s_barrier
	v_mfma_f32_16x16x32_bf16 v[58:61], v[206:209], v[162:165], v[58:61]
	v_mfma_f32_16x16x32_bf16 v[50:53], v[214:217], v[162:165], v[50:53]
	v_mfma_f32_16x16x32_bf16 v[42:45], v[206:209], v[170:173], v[42:45]
	v_mfma_f32_16x16x32_bf16 v[34:37], v[214:217], v[170:173], v[34:37]
	v_mfma_f32_16x16x32_bf16 v[26:29], v[206:209], v[190:193], v[26:29]
	v_mfma_f32_16x16x32_bf16 v[18:21], v[214:217], v[190:193], v[18:21]
	v_mfma_f32_16x16x32_bf16 v[10:13], v[206:209], v[198:201], v[10:13]
	v_mfma_f32_16x16x32_bf16 v[2:5], v[214:217], v[198:201], v[2:5]
	v_mfma_f32_16x16x32_bf16 v[58:61], v[210:213], v[166:169], v[58:61]
	v_mfma_f32_16x16x32_bf16 v[50:53], v[218:221], v[166:169], v[50:53]
	v_mfma_f32_16x16x32_bf16 v[42:45], v[210:213], v[174:177], v[42:45]
	v_mfma_f32_16x16x32_bf16 v[34:37], v[218:221], v[174:177], v[34:37]
	v_mfma_f32_16x16x32_bf16 v[26:29], v[210:213], v[194:197], v[26:29]
	v_mfma_f32_16x16x32_bf16 v[18:21], v[218:221], v[194:197], v[18:21]
	v_mfma_f32_16x16x32_bf16 v[10:13], v[210:213], v[202:205], v[10:13]
	v_mfma_f32_16x16x32_bf16 v[2:5], v[218:221], v[202:205], v[2:5]
	s_barrier
	s_add_i32 s48, s48, 2
	s_add_u32 s20, s20, 0x100
	s_addc_u32 s21, s21, 0
	s_add_u32 s46, s46, 0x100
	s_addc_u32 s47, s47, 0
.LBB0_297:
	s_add_u32 s22, s20, 0xfffc0080
	s_addc_u32 s23, s21, -1
	s_add_i32 s49, 0, 0x10000
	v_add_u32_e32 v145, s49, v142
	s_cmp_eq_u32 s48, 12
	s_cselect_b32 s25, s9, s23
	s_cselect_b32 s24, s44, s22
	s_cselect_b32 s23, s7, s47
	s_cselect_b32 s22, s45, s46
	s_add_i32 m0, s19, 0xc000
	ds_read_b128 v[162:165], v144
	ds_read_b128 v[166:169], v144 offset:1024
	ds_read_b128 v[170:173], v144 offset:2048
	ds_read_b128 v[174:177], v144 offset:3072
	ds_read_b128 v[190:193], v144 offset:4096
	ds_read_b128 v[194:197], v144 offset:5120
	ds_read_b128 v[198:201], v144 offset:6144
	ds_read_b128 v[202:205], v144 offset:7168
	global_load_lds_dwordx4 v138, s[20:21]
	s_add_i32 m0, s19, 0xe000
	s_nop 0
	global_load_lds_dwordx4 v140, s[20:21]
	s_waitcnt lgkmcnt(8)
	s_barrier
	s_waitcnt lgkmcnt(0)
	s_waitcnt lgkmcnt(0)
	v_mfma_f32_16x16x32_bf16 v[126:129], v[146:149], v[162:165], v[126:129]
	v_mfma_f32_16x16x32_bf16 v[118:121], v[154:157], v[162:165], v[118:121]
	v_mfma_f32_16x16x32_bf16 v[110:113], v[146:149], v[170:173], v[110:113]
	v_mfma_f32_16x16x32_bf16 v[102:105], v[154:157], v[170:173], v[102:105]
	v_mfma_f32_16x16x32_bf16 v[94:97], v[146:149], v[190:193], v[94:97]
	v_mfma_f32_16x16x32_bf16 v[86:89], v[154:157], v[190:193], v[86:89]
	v_mfma_f32_16x16x32_bf16 v[78:81], v[146:149], v[198:201], v[78:81]
	v_mfma_f32_16x16x32_bf16 v[70:73], v[154:157], v[198:201], v[70:73]
	v_mfma_f32_16x16x32_bf16 v[126:129], v[150:153], v[166:169], v[126:129]
	v_mfma_f32_16x16x32_bf16 v[118:121], v[158:161], v[166:169], v[118:121]
	v_mfma_f32_16x16x32_bf16 v[110:113], v[150:153], v[174:177], v[110:113]
	v_mfma_f32_16x16x32_bf16 v[102:105], v[158:161], v[174:177], v[102:105]
	v_mfma_f32_16x16x32_bf16 v[94:97], v[150:153], v[194:197], v[94:97]
	v_mfma_f32_16x16x32_bf16 v[86:89], v[158:161], v[194:197], v[86:89]
	v_mfma_f32_16x16x32_bf16 v[78:81], v[150:153], v[202:205], v[78:81]
	v_mfma_f32_16x16x32_bf16 v[70:73], v[158:161], v[202:205], v[70:73]
	s_barrier
	s_add_i32 s54, 0, 0x14000
	s_add_i32 s49, s49, s35
	v_add_u32_e32 v145, s54, v142
	s_add_u32 s64, s22, 0x80
	s_addc_u32 s65, s23, 0
	s_mov_b32 m0, s49
	ds_read_b128 v[206:209], v145
	ds_read_b128 v[210:213], v145 offset:1024
	ds_read_b128 v[214:217], v145 offset:2048
	ds_read_b128 v[218:221], v145 offset:3072
	global_load_lds_dwordx4 v134, s[22:23]
	s_add_i32 m0, s49, 0x2000
	s_nop 0
	global_load_lds_dwordx4 v130, s[22:23]
	s_barrier
	s_waitcnt lgkmcnt(0)
	s_waitcnt lgkmcnt(0)
	v_mfma_f32_16x16x32_bf16 v[122:125], v[206:209], v[162:165], v[122:125]
	v_mfma_f32_16x16x32_bf16 v[114:117], v[214:217], v[162:165], v[114:117]
	v_mfma_f32_16x16x32_bf16 v[106:109], v[206:209], v[170:173], v[106:109]
	v_mfma_f32_16x16x32_bf16 v[98:101], v[214:217], v[170:173], v[98:101]
	v_mfma_f32_16x16x32_bf16 v[90:93], v[206:209], v[190:193], v[90:93]
	v_mfma_f32_16x16x32_bf16 v[82:85], v[214:217], v[190:193], v[82:85]
	v_mfma_f32_16x16x32_bf16 v[74:77], v[206:209], v[198:201], v[74:77]
	v_mfma_f32_16x16x32_bf16 v[66:69], v[214:217], v[198:201], v[66:69]
	v_mfma_f32_16x16x32_bf16 v[122:125], v[210:213], v[166:169], v[122:125]
	v_mfma_f32_16x16x32_bf16 v[114:117], v[218:221], v[166:169], v[114:117]
	v_mfma_f32_16x16x32_bf16 v[106:109], v[210:213], v[174:177], v[106:109]
	v_mfma_f32_16x16x32_bf16 v[98:101], v[218:221], v[174:177], v[98:101]
	v_mfma_f32_16x16x32_bf16 v[90:93], v[210:213], v[194:197], v[90:93]
	v_mfma_f32_16x16x32_bf16 v[82:85], v[218:221], v[194:197], v[82:85]
	v_mfma_f32_16x16x32_bf16 v[74:77], v[210:213], v[202:205], v[74:77]
	v_mfma_f32_16x16x32_bf16 v[66:69], v[218:221], v[202:205], v[66:69]
	s_barrier
	s_mov_b32 m0, s19
	s_add_u32 s62, s24, 0x80
	s_addc_u32 s63, s25, 0
	ds_read_b128 v[162:165], v144 offset:16384
	ds_read_b128 v[166:169], v144 offset:17408
	ds_read_b128 v[170:173], v144 offset:18432
	ds_read_b128 v[174:177], v144 offset:19456
	ds_read_b128 v[190:193], v144 offset:20480
	ds_read_b128 v[194:197], v144 offset:21504
	ds_read_b128 v[198:201], v144 offset:22528
	ds_read_b128 v[202:205], v144 offset:23552
	global_load_lds_dwordx4 v136, s[24:25]
	s_mov_b32 m0, s36
	s_nop 0
	global_load_lds_dwordx4 v132, s[24:25]
	s_waitcnt vmcnt(10)
	s_barrier
	s_waitcnt lgkmcnt(0)
	s_waitcnt lgkmcnt(0)
	v_mfma_f32_16x16x32_bf16 v[62:65], v[146:149], v[162:165], v[62:65]
	v_mfma_f32_16x16x32_bf16 v[54:57], v[154:157], v[162:165], v[54:57]
	v_mfma_f32_16x16x32_bf16 v[46:49], v[146:149], v[170:173], v[46:49]
	v_mfma_f32_16x16x32_bf16 v[38:41], v[154:157], v[170:173], v[38:41]
	v_mfma_f32_16x16x32_bf16 v[30:33], v[146:149], v[190:193], v[30:33]
	v_mfma_f32_16x16x32_bf16 v[22:25], v[154:157], v[190:193], v[22:25]
	v_mfma_f32_16x16x32_bf16 v[14:17], v[146:149], v[198:201], v[14:17]
	v_mfma_f32_16x16x32_bf16 v[6:9], v[154:157], v[198:201], v[6:9]
	v_mfma_f32_16x16x32_bf16 v[62:65], v[150:153], v[166:169], v[62:65]
	v_mfma_f32_16x16x32_bf16 v[54:57], v[158:161], v[166:169], v[54:57]
	v_mfma_f32_16x16x32_bf16 v[46:49], v[150:153], v[174:177], v[46:49]
	v_mfma_f32_16x16x32_bf16 v[38:41], v[158:161], v[174:177], v[38:41]
	v_mfma_f32_16x16x32_bf16 v[30:33], v[150:153], v[194:197], v[30:33]
	v_mfma_f32_16x16x32_bf16 v[22:25], v[158:161], v[194:197], v[22:25]
	v_mfma_f32_16x16x32_bf16 v[14:17], v[150:153], v[202:205], v[14:17]
	v_mfma_f32_16x16x32_bf16 v[6:9], v[158:161], v[202:205], v[6:9]
	s_barrier
	v_add_u32_e32 v158, 0x18000, v142
	ds_read_b128 v[146:149], v158
	ds_read_b128 v[150:153], v158 offset:1024
	ds_read_b128 v[154:157], v158 offset:2048
	ds_read_b128 v[158:161], v158 offset:3072
	s_add_u32 s50, s22, 0x40000
	s_addc_u32 s51, s23, 0
	s_add_i32 s49, s54, s35
	s_mov_b32 m0, s49
	s_nop 0
	global_load_lds_dwordx4 v134, s[50:51]
	s_add_i32 m0, s49, 0x2000
	s_nop 0
	global_load_lds_dwordx4 v130, s[50:51]
	s_waitcnt vmcnt(6)
	s_barrier
	v_mfma_f32_16x16x32_bf16 v[58:61], v[206:209], v[162:165], v[58:61]
	v_mfma_f32_16x16x32_bf16 v[50:53], v[214:217], v[162:165], v[50:53]
	v_mfma_f32_16x16x32_bf16 v[42:45], v[206:209], v[170:173], v[42:45]
	v_mfma_f32_16x16x32_bf16 v[34:37], v[214:217], v[170:173], v[34:37]
	v_mfma_f32_16x16x32_bf16 v[26:29], v[206:209], v[190:193], v[26:29]
	v_mfma_f32_16x16x32_bf16 v[18:21], v[214:217], v[190:193], v[18:21]
	v_mfma_f32_16x16x32_bf16 v[10:13], v[206:209], v[198:201], v[10:13]
	v_mfma_f32_16x16x32_bf16 v[2:5], v[214:217], v[198:201], v[2:5]
	v_mfma_f32_16x16x32_bf16 v[58:61], v[210:213], v[166:169], v[58:61]
	v_mfma_f32_16x16x32_bf16 v[50:53], v[218:221], v[166:169], v[50:53]
	v_mfma_f32_16x16x32_bf16 v[42:45], v[210:213], v[174:177], v[42:45]
	v_mfma_f32_16x16x32_bf16 v[34:37], v[218:221], v[174:177], v[34:37]
	v_mfma_f32_16x16x32_bf16 v[26:29], v[210:213], v[194:197], v[26:29]
	v_mfma_f32_16x16x32_bf16 v[18:21], v[218:221], v[194:197], v[18:21]
	v_mfma_f32_16x16x32_bf16 v[10:13], v[210:213], v[202:205], v[10:13]
	v_mfma_f32_16x16x32_bf16 v[2:5], v[218:221], v[202:205], v[2:5]
	s_barrier
	s_add_i32 s49, 0, 0x18000
	v_add_u32_e32 v145, s49, v142
	s_add_u32 s24, s24, 0x40000
	s_addc_u32 s25, s25, 0
	s_mov_b32 m0, s37
	ds_read_b128 v[162:165], v144 offset:32768
	ds_read_b128 v[166:169], v144 offset:33792
	ds_read_b128 v[170:173], v144 offset:34816
	ds_read_b128 v[174:177], v144 offset:35840
	ds_read_b128 v[190:193], v144 offset:36864
	ds_read_b128 v[194:197], v144 offset:37888
	ds_read_b128 v[198:201], v144 offset:38912
	ds_read_b128 v[202:205], v144 offset:39936
	global_load_lds_dwordx4 v136, s[24:25]
	s_mov_b32 m0, s38
	s_nop 0
	global_load_lds_dwordx4 v132, s[24:25]
	s_waitcnt lgkmcnt(8)
	s_barrier
	s_waitcnt lgkmcnt(0)
	s_waitcnt lgkmcnt(0)
	v_mfma_f32_16x16x32_bf16 v[126:129], v[146:149], v[162:165], v[126:129]
	v_mfma_f32_16x16x32_bf16 v[118:121], v[154:157], v[162:165], v[118:121]
	v_mfma_f32_16x16x32_bf16 v[110:113], v[146:149], v[170:173], v[110:113]
	v_mfma_f32_16x16x32_bf16 v[102:105], v[154:157], v[170:173], v[102:105]
	v_mfma_f32_16x16x32_bf16 v[94:97], v[146:149], v[190:193], v[94:97]
	v_mfma_f32_16x16x32_bf16 v[86:89], v[154:157], v[190:193], v[86:89]
	v_mfma_f32_16x16x32_bf16 v[78:81], v[146:149], v[198:201], v[78:81]
	v_mfma_f32_16x16x32_bf16 v[70:73], v[154:157], v[198:201], v[70:73]
	v_mfma_f32_16x16x32_bf16 v[126:129], v[150:153], v[166:169], v[126:129]
	v_mfma_f32_16x16x32_bf16 v[118:121], v[158:161], v[166:169], v[118:121]
	v_mfma_f32_16x16x32_bf16 v[110:113], v[150:153], v[174:177], v[110:113]
	v_mfma_f32_16x16x32_bf16 v[102:105], v[158:161], v[174:177], v[102:105]
	v_mfma_f32_16x16x32_bf16 v[94:97], v[150:153], v[194:197], v[94:97]
	v_mfma_f32_16x16x32_bf16 v[86:89], v[158:161], v[194:197], v[86:89]
	v_mfma_f32_16x16x32_bf16 v[78:81], v[150:153], v[202:205], v[78:81]
	v_mfma_f32_16x16x32_bf16 v[70:73], v[158:161], v[202:205], v[70:73]
	s_barrier
	s_add_i32 s24, 0, 0x1c000
	s_add_i32 s25, s49, s35
	v_add_u32_e32 v145, s24, v142
	s_mov_b32 m0, s25
	ds_read_b128 v[206:209], v145
	ds_read_b128 v[210:213], v145 offset:1024
	ds_read_b128 v[214:217], v145 offset:2048
	ds_read_b128 v[218:221], v145 offset:3072
	global_load_lds_dwordx4 v134, s[64:65]
	s_add_i32 m0, s25, 0x2000
	s_nop 0
	global_load_lds_dwordx4 v130, s[64:65]
	s_barrier
	s_waitcnt lgkmcnt(0)
	s_waitcnt lgkmcnt(0)
	v_mfma_f32_16x16x32_bf16 v[122:125], v[206:209], v[162:165], v[122:125]
	v_mfma_f32_16x16x32_bf16 v[114:117], v[214:217], v[162:165], v[114:117]
	v_mfma_f32_16x16x32_bf16 v[106:109], v[206:209], v[170:173], v[106:109]
	v_mfma_f32_16x16x32_bf16 v[98:101], v[214:217], v[170:173], v[98:101]
	v_mfma_f32_16x16x32_bf16 v[90:93], v[206:209], v[190:193], v[90:93]
	v_mfma_f32_16x16x32_bf16 v[82:85], v[214:217], v[190:193], v[82:85]
	v_mfma_f32_16x16x32_bf16 v[74:77], v[206:209], v[198:201], v[74:77]
	v_mfma_f32_16x16x32_bf16 v[66:69], v[214:217], v[198:201], v[66:69]
	v_mfma_f32_16x16x32_bf16 v[122:125], v[210:213], v[166:169], v[122:125]
	v_mfma_f32_16x16x32_bf16 v[114:117], v[218:221], v[166:169], v[114:117]
	v_mfma_f32_16x16x32_bf16 v[106:109], v[210:213], v[174:177], v[106:109]
	v_mfma_f32_16x16x32_bf16 v[98:101], v[218:221], v[174:177], v[98:101]
	v_mfma_f32_16x16x32_bf16 v[90:93], v[210:213], v[194:197], v[90:93]
	v_mfma_f32_16x16x32_bf16 v[82:85], v[218:221], v[194:197], v[82:85]
	v_mfma_f32_16x16x32_bf16 v[74:77], v[210:213], v[202:205], v[74:77]
	v_mfma_f32_16x16x32_bf16 v[66:69], v[218:221], v[202:205], v[66:69]
	s_barrier
	s_mov_b32 m0, s39
	ds_read_b128 v[162:165], v144 offset:49152
	ds_read_b128 v[166:169], v144 offset:50176
	ds_read_b128 v[170:173], v144 offset:51200
	ds_read_b128 v[174:177], v144 offset:52224
	ds_read_b128 v[190:193], v144 offset:53248
	ds_read_b128 v[194:197], v144 offset:54272
	ds_read_b128 v[198:201], v144 offset:55296
	ds_read_b128 v[202:205], v144 offset:56320
	global_load_lds_dwordx4 v136, s[62:63]
	s_mov_b32 m0, s40
	s_nop 0
	global_load_lds_dwordx4 v132, s[62:63]
	s_waitcnt vmcnt(10)
	s_barrier
	s_waitcnt lgkmcnt(0)
	s_waitcnt lgkmcnt(0)
	v_mfma_f32_16x16x32_bf16 v[62:65], v[146:149], v[162:165], v[62:65]
	v_mfma_f32_16x16x32_bf16 v[54:57], v[154:157], v[162:165], v[54:57]
	v_mfma_f32_16x16x32_bf16 v[46:49], v[146:149], v[170:173], v[46:49]
	v_mfma_f32_16x16x32_bf16 v[38:41], v[154:157], v[170:173], v[38:41]
	v_mfma_f32_16x16x32_bf16 v[30:33], v[146:149], v[190:193], v[30:33]
	v_mfma_f32_16x16x32_bf16 v[22:25], v[154:157], v[190:193], v[22:25]
	v_mfma_f32_16x16x32_bf16 v[14:17], v[146:149], v[198:201], v[14:17]
	v_mfma_f32_16x16x32_bf16 v[6:9], v[154:157], v[198:201], v[6:9]
	v_mfma_f32_16x16x32_bf16 v[62:65], v[150:153], v[166:169], v[62:65]
	v_mfma_f32_16x16x32_bf16 v[54:57], v[158:161], v[166:169], v[54:57]
	v_mfma_f32_16x16x32_bf16 v[46:49], v[150:153], v[174:177], v[46:49]
	v_mfma_f32_16x16x32_bf16 v[38:41], v[158:161], v[174:177], v[38:41]
	v_mfma_f32_16x16x32_bf16 v[30:33], v[150:153], v[194:197], v[30:33]
	v_mfma_f32_16x16x32_bf16 v[22:25], v[158:161], v[194:197], v[22:25]
	v_mfma_f32_16x16x32_bf16 v[14:17], v[150:153], v[202:205], v[14:17]
	v_mfma_f32_16x16x32_bf16 v[6:9], v[158:161], v[202:205], v[6:9]
	s_barrier
	v_add_u32_e32 v158, 0x10000, v142
	ds_read_b128 v[146:149], v158
	ds_read_b128 v[150:153], v158 offset:1024
	ds_read_b128 v[154:157], v158 offset:2048
	ds_read_b128 v[158:161], v158 offset:3072
	s_add_u32 s22, s22, 0x40080
	s_addc_u32 s23, s23, 0
	s_add_i32 s24, s24, s35
	s_mov_b32 m0, s24
	s_nop 0
	global_load_lds_dwordx4 v134, s[22:23]
	s_add_i32 m0, s24, 0x2000
	s_nop 0
	global_load_lds_dwordx4 v130, s[22:23]
	s_waitcnt vmcnt(6)
	s_barrier
	v_mfma_f32_16x16x32_bf16 v[58:61], v[206:209], v[162:165], v[58:61]
	v_mfma_f32_16x16x32_bf16 v[50:53], v[214:217], v[162:165], v[50:53]
	v_mfma_f32_16x16x32_bf16 v[42:45], v[206:209], v[170:173], v[42:45]
	v_mfma_f32_16x16x32_bf16 v[34:37], v[214:217], v[170:173], v[34:37]
	v_mfma_f32_16x16x32_bf16 v[26:29], v[206:209], v[190:193], v[26:29]
	v_mfma_f32_16x16x32_bf16 v[18:21], v[214:217], v[190:193], v[18:21]
	v_mfma_f32_16x16x32_bf16 v[10:13], v[206:209], v[198:201], v[10:13]
	v_mfma_f32_16x16x32_bf16 v[2:5], v[214:217], v[198:201], v[2:5]
	v_mfma_f32_16x16x32_bf16 v[58:61], v[210:213], v[166:169], v[58:61]
	v_mfma_f32_16x16x32_bf16 v[50:53], v[218:221], v[166:169], v[50:53]
	v_mfma_f32_16x16x32_bf16 v[42:45], v[210:213], v[174:177], v[42:45]
	v_mfma_f32_16x16x32_bf16 v[34:37], v[218:221], v[174:177], v[34:37]
	v_mfma_f32_16x16x32_bf16 v[26:29], v[210:213], v[194:197], v[26:29]
	v_mfma_f32_16x16x32_bf16 v[18:21], v[218:221], v[194:197], v[18:21]
	v_mfma_f32_16x16x32_bf16 v[10:13], v[210:213], v[202:205], v[10:13]
	v_mfma_f32_16x16x32_bf16 v[2:5], v[218:221], v[202:205], v[2:5]
	s_barrier
	s_add_i32 s48, s48, 2
	s_add_u32 s20, s20, 0x100
	s_addc_u32 s21, s21, 0
	s_add_u32 s46, s46, 0x100
	s_addc_u32 s47, s47, 0
	s_cmp_gt_u32 s48, 13
	s_cbranch_scc0 .LBB0_297
	s_waitcnt lgkmcnt(0)
	v_mov_b32_e32 v226, 0xbfb8aa3b
	v_mov_b32_e32 v227, 0xbfb8aa3b
	v_mov_b32_e32 v228, 1.0
	v_mov_b32_e32 v229, 1.0
	v_pk_mul_f32 v[222:223], v[126:127], v[226:227]
	v_exp_f32_e32 v222, v222
	v_exp_f32_e32 v223, v223
	s_nop 0
	v_pk_add_f32 v[222:223], v[222:223], v[228:229]
	v_rcp_f32_e32 v222, v222
	v_rcp_f32_e32 v223, v223
	v_pk_mul_f32 v[224:225], v[128:129], v[226:227]
	v_exp_f32_e32 v224, v224
	v_exp_f32_e32 v225, v225
	v_pk_mul_f32 v[222:223], v[126:127], v[222:223]
	v_pk_add_f32 v[224:225], v[224:225], v[228:229]
	v_rcp_f32_e32 v224, v224
	v_rcp_f32_e32 v225, v225
	v_pk_mul_f32 v[122:123], v[222:223], v[122:123]
	v_pk_mul_f32 v[222:223], v[118:119], v[226:227]
	v_exp_f32_e32 v222, v222
	v_exp_f32_e32 v223, v223
	v_pk_mul_f32 v[224:225], v[128:129], v[224:225]
	v_pk_add_f32 v[222:223], v[222:223], v[228:229]
	v_rcp_f32_e32 v222, v222
	v_rcp_f32_e32 v223, v223
	v_pk_mul_f32 v[124:125], v[224:225], v[124:125]
	v_pk_mul_f32 v[224:225], v[120:121], v[226:227]
	v_exp_f32_e32 v224, v224
	v_exp_f32_e32 v225, v225
	v_pk_mul_f32 v[222:223], v[118:119], v[222:223]
	v_pk_add_f32 v[224:225], v[224:225], v[228:229]
	v_rcp_f32_e32 v224, v224
	v_rcp_f32_e32 v225, v225
	v_pk_mul_f32 v[114:115], v[222:223], v[114:115]
	v_pk_mul_f32 v[222:223], v[110:111], v[226:227]
	v_exp_f32_e32 v222, v222
	v_exp_f32_e32 v223, v223
	v_pk_mul_f32 v[224:225], v[120:121], v[224:225]
	v_pk_add_f32 v[222:223], v[222:223], v[228:229]
	v_rcp_f32_e32 v222, v222
	v_rcp_f32_e32 v223, v223
	v_pk_mul_f32 v[116:117], v[224:225], v[116:117]
	v_lshl_or_b32 v146, s43, 7, v143
	v_lshl_add_u32 v145, s18, 8, v1
	v_ashrrev_i32_e32 v147, 31, v146
	s_movk_i32 s7, 0x1700
	s_and_b64 vcc, exec, s[4:5]
	s_mov_b32 s43, s6
	s_mov_b32 s18, s8
	s_mov_b64 s[22:23], s[14:15]
	v_cvt_pk_bf16_f32 v120, v114, v115
	v_mov_b64_e32 v[114:115], s[2:3]
	v_cvt_pk_bf16_f32 v118, v122, v123
	v_cvt_pk_bf16_f32 v121, v116, v117
	v_mad_i64_i32 v[122:123], s[20:21], v145, s7, v[114:115]
	v_lshlrev_b64 v[116:117], 1, v[146:147]
	v_cvt_pk_bf16_f32 v119, v124, v125
	v_lshl_add_u64 v[122:123], v[122:123], 0, v[116:117]
	global_store_dwordx4 v[122:123], v[118:121], off
	s_nop 1
	v_pk_mul_f32 v[224:225], v[112:113], v[226:227]
	v_exp_f32_e32 v224, v224
	v_exp_f32_e32 v225, v225
	v_pk_mul_f32 v[222:223], v[110:111], v[222:223]
	v_pk_add_f32 v[224:225], v[224:225], v[228:229]
	v_rcp_f32_e32 v224, v224
	v_rcp_f32_e32 v225, v225
	v_pk_mul_f32 v[106:107], v[222:223], v[106:107]
	v_pk_mul_f32 v[222:223], v[102:103], v[226:227]
	v_exp_f32_e32 v222, v222
	v_exp_f32_e32 v223, v223
	v_pk_mul_f32 v[224:225], v[112:113], v[224:225]
	v_pk_add_f32 v[222:223], v[222:223], v[228:229]
	v_rcp_f32_e32 v222, v222
	v_rcp_f32_e32 v223, v223
	v_pk_mul_f32 v[108:109], v[224:225], v[108:109]
	v_pk_mul_f32 v[224:225], v[104:105], v[226:227]
	v_exp_f32_e32 v224, v224
	v_exp_f32_e32 v225, v225
	v_pk_mul_f32 v[222:223], v[102:103], v[222:223]
	v_pk_add_f32 v[224:225], v[224:225], v[228:229]
	v_rcp_f32_e32 v224, v224
	v_rcp_f32_e32 v225, v225
	v_pk_mul_f32 v[102:103], v[222:223], v[98:99]
	v_pk_mul_f32 v[222:223], v[94:95], v[226:227]
	v_exp_f32_e32 v222, v222
	v_exp_f32_e32 v223, v223
	v_pk_mul_f32 v[224:225], v[104:105], v[224:225]
	v_pk_add_f32 v[222:223], v[222:223], v[228:229]
	v_rcp_f32_e32 v222, v222
	v_rcp_f32_e32 v223, v223
	v_pk_mul_f32 v[104:105], v[224:225], v[100:101]
	v_cvt_pk_bf16_f32 v100, v102, v103
	v_or_b32_e32 v102, 16, v145
	v_mad_i64_i32 v[102:103], s[20:21], v102, s7, v[114:115]
	v_cvt_pk_bf16_f32 v98, v106, v107
	v_cvt_pk_bf16_f32 v99, v108, v109
	v_cvt_pk_bf16_f32 v101, v104, v105
	v_lshl_add_u64 v[102:103], v[102:103], 0, v[116:117]
	global_store_dwordx4 v[102:103], v[98:101], off
	s_nop 1
	v_pk_mul_f32 v[224:225], v[96:97], v[226:227]
	v_exp_f32_e32 v224, v224
	v_exp_f32_e32 v225, v225
	v_pk_mul_f32 v[222:223], v[94:95], v[222:223]
	v_pk_add_f32 v[224:225], v[224:225], v[228:229]
	v_rcp_f32_e32 v224, v224
	v_rcp_f32_e32 v225, v225
	v_pk_mul_f32 v[90:91], v[222:223], v[90:91]
	v_pk_mul_f32 v[222:223], v[86:87], v[226:227]
	v_exp_f32_e32 v222, v222
	v_exp_f32_e32 v223, v223
	v_pk_mul_f32 v[224:225], v[96:97], v[224:225]
	v_pk_add_f32 v[222:223], v[222:223], v[228:229]
	v_rcp_f32_e32 v222, v222
	v_rcp_f32_e32 v223, v223
	v_pk_mul_f32 v[92:93], v[224:225], v[92:93]
	v_pk_mul_f32 v[224:225], v[88:89], v[226:227]
	v_exp_f32_e32 v224, v224
	v_exp_f32_e32 v225, v225
	v_pk_mul_f32 v[222:223], v[86:87], v[222:223]
	v_pk_add_f32 v[224:225], v[224:225], v[228:229]
	v_rcp_f32_e32 v224, v224
	v_rcp_f32_e32 v225, v225
	v_pk_mul_f32 v[86:87], v[222:223], v[82:83]
	v_pk_mul_f32 v[222:223], v[78:79], v[226:227]
	v_exp_f32_e32 v222, v222
	v_exp_f32_e32 v223, v223
	v_pk_mul_f32 v[224:225], v[88:89], v[224:225]
	v_pk_add_f32 v[222:223], v[222:223], v[228:229]
	v_rcp_f32_e32 v222, v222
	v_rcp_f32_e32 v223, v223
	v_pk_mul_f32 v[88:89], v[224:225], v[84:85]
	v_cvt_pk_bf16_f32 v84, v86, v87
	v_or_b32_e32 v86, 32, v145
	v_mad_i64_i32 v[86:87], s[20:21], v86, s7, v[114:115]
	v_cvt_pk_bf16_f32 v82, v90, v91
	v_cvt_pk_bf16_f32 v83, v92, v93
	v_cvt_pk_bf16_f32 v85, v88, v89
	v_lshl_add_u64 v[86:87], v[86:87], 0, v[116:117]
	global_store_dwordx4 v[86:87], v[82:85], off
	s_nop 1
	v_pk_mul_f32 v[224:225], v[80:81], v[226:227]
	v_exp_f32_e32 v224, v224
	v_exp_f32_e32 v225, v225
	v_pk_mul_f32 v[222:223], v[78:79], v[222:223]
	v_pk_add_f32 v[224:225], v[224:225], v[228:229]
	v_rcp_f32_e32 v224, v224
	v_rcp_f32_e32 v225, v225
	v_pk_mul_f32 v[74:75], v[222:223], v[74:75]
	v_pk_mul_f32 v[222:223], v[70:71], v[226:227]
	v_exp_f32_e32 v222, v222
	v_exp_f32_e32 v223, v223
	v_pk_mul_f32 v[224:225], v[80:81], v[224:225]
	v_pk_add_f32 v[222:223], v[222:223], v[228:229]
	v_rcp_f32_e32 v222, v222
	v_rcp_f32_e32 v223, v223
	v_pk_mul_f32 v[76:77], v[224:225], v[76:77]
	v_pk_mul_f32 v[224:225], v[72:73], v[226:227]
	v_exp_f32_e32 v224, v224
	v_exp_f32_e32 v225, v225
	v_pk_mul_f32 v[222:223], v[70:71], v[222:223]
	v_pk_add_f32 v[224:225], v[224:225], v[228:229]
	v_rcp_f32_e32 v224, v224
	v_rcp_f32_e32 v225, v225
	v_pk_mul_f32 v[70:71], v[222:223], v[66:67]
	v_pk_mul_f32 v[222:223], v[62:63], v[226:227]
	v_exp_f32_e32 v222, v222
	v_exp_f32_e32 v223, v223
	v_pk_mul_f32 v[224:225], v[72:73], v[224:225]
	v_pk_add_f32 v[222:223], v[222:223], v[228:229]
	v_rcp_f32_e32 v222, v222
	v_rcp_f32_e32 v223, v223
	v_pk_mul_f32 v[72:73], v[224:225], v[68:69]
	v_cvt_pk_bf16_f32 v68, v70, v71
	v_or_b32_e32 v70, 48, v145
	v_mad_i64_i32 v[70:71], s[20:21], v70, s7, v[114:115]
	v_cvt_pk_bf16_f32 v66, v74, v75
	v_cvt_pk_bf16_f32 v67, v76, v77
	v_cvt_pk_bf16_f32 v69, v72, v73
	v_lshl_add_u64 v[70:71], v[70:71], 0, v[116:117]
	global_store_dwordx4 v[70:71], v[66:69], off
	s_nop 1
	v_pk_mul_f32 v[224:225], v[64:65], v[226:227]
	v_exp_f32_e32 v224, v224
	v_exp_f32_e32 v225, v225
	v_pk_mul_f32 v[222:223], v[62:63], v[222:223]
	v_pk_add_f32 v[224:225], v[224:225], v[228:229]
	v_rcp_f32_e32 v224, v224
	v_rcp_f32_e32 v225, v225
	v_pk_mul_f32 v[58:59], v[222:223], v[58:59]
	v_pk_mul_f32 v[222:223], v[54:55], v[226:227]
	v_exp_f32_e32 v222, v222
	v_exp_f32_e32 v223, v223
	v_pk_mul_f32 v[224:225], v[64:65], v[224:225]
	v_pk_add_f32 v[222:223], v[222:223], v[228:229]
	v_rcp_f32_e32 v222, v222
	v_rcp_f32_e32 v223, v223
	v_pk_mul_f32 v[60:61], v[224:225], v[60:61]
	v_pk_mul_f32 v[224:225], v[56:57], v[226:227]
	v_exp_f32_e32 v224, v224
	v_exp_f32_e32 v225, v225
	v_pk_mul_f32 v[222:223], v[54:55], v[222:223]
	v_pk_add_f32 v[224:225], v[224:225], v[228:229]
	v_rcp_f32_e32 v224, v224
	v_rcp_f32_e32 v225, v225
	v_pk_mul_f32 v[54:55], v[222:223], v[50:51]
	v_pk_mul_f32 v[222:223], v[46:47], v[226:227]
	v_exp_f32_e32 v222, v222
	v_exp_f32_e32 v223, v223
	v_pk_mul_f32 v[224:225], v[56:57], v[224:225]
	v_pk_add_f32 v[222:223], v[222:223], v[228:229]
	v_rcp_f32_e32 v222, v222
	v_rcp_f32_e32 v223, v223
	v_pk_mul_f32 v[56:57], v[224:225], v[52:53]
	v_add_u32_e32 v68, 0x80, v145
	v_cvt_pk_bf16_f32 v52, v54, v55
	v_mad_i64_i32 v[54:55], s[20:21], v68, s7, v[114:115]
	v_cvt_pk_bf16_f32 v50, v58, v59
	v_cvt_pk_bf16_f32 v51, v60, v61
	v_cvt_pk_bf16_f32 v53, v56, v57
	v_lshl_add_u64 v[54:55], v[54:55], 0, v[116:117]
	global_store_dwordx4 v[54:55], v[50:53], off
	s_nop 1
	v_pk_mul_f32 v[224:225], v[48:49], v[226:227]
	v_exp_f32_e32 v224, v224
	v_exp_f32_e32 v225, v225
	v_pk_mul_f32 v[222:223], v[46:47], v[222:223]
	v_pk_add_f32 v[224:225], v[224:225], v[228:229]
	v_rcp_f32_e32 v224, v224
	v_rcp_f32_e32 v225, v225
	v_pk_mul_f32 v[42:43], v[222:223], v[42:43]
	v_pk_mul_f32 v[222:223], v[38:39], v[226:227]
	v_exp_f32_e32 v222, v222
	v_exp_f32_e32 v223, v223
	v_pk_mul_f32 v[224:225], v[48:49], v[224:225]
	v_pk_add_f32 v[222:223], v[222:223], v[228:229]
	v_rcp_f32_e32 v222, v222
	v_rcp_f32_e32 v223, v223
	v_pk_mul_f32 v[44:45], v[224:225], v[44:45]
	v_pk_mul_f32 v[224:225], v[40:41], v[226:227]
	v_exp_f32_e32 v224, v224
	v_exp_f32_e32 v225, v225
	v_pk_mul_f32 v[222:223], v[38:39], v[222:223]
	v_pk_add_f32 v[224:225], v[224:225], v[228:229]
	v_rcp_f32_e32 v224, v224
	v_rcp_f32_e32 v225, v225
	v_pk_mul_f32 v[38:39], v[222:223], v[34:35]
	v_pk_mul_f32 v[222:223], v[30:31], v[226:227]
	v_exp_f32_e32 v222, v222
	v_exp_f32_e32 v223, v223
	v_pk_mul_f32 v[224:225], v[40:41], v[224:225]
	v_pk_add_f32 v[222:223], v[222:223], v[228:229]
	v_rcp_f32_e32 v222, v222
	v_rcp_f32_e32 v223, v223
	v_pk_mul_f32 v[40:41], v[224:225], v[36:37]
	v_cvt_pk_bf16_f32 v36, v38, v39
	v_add_u32_e32 v38, 0x90, v145
	v_mad_i64_i32 v[38:39], s[20:21], v38, s7, v[114:115]
	v_cvt_pk_bf16_f32 v34, v42, v43
	v_cvt_pk_bf16_f32 v35, v44, v45
	v_cvt_pk_bf16_f32 v37, v40, v41
	v_lshl_add_u64 v[38:39], v[38:39], 0, v[116:117]
	global_store_dwordx4 v[38:39], v[34:37], off
	s_nop 1
	v_pk_mul_f32 v[224:225], v[32:33], v[226:227]
	v_exp_f32_e32 v224, v224
	v_exp_f32_e32 v225, v225
	v_pk_mul_f32 v[222:223], v[30:31], v[222:223]
	v_pk_add_f32 v[224:225], v[224:225], v[228:229]
	v_rcp_f32_e32 v224, v224
	v_rcp_f32_e32 v225, v225
	v_pk_mul_f32 v[26:27], v[222:223], v[26:27]
	v_pk_mul_f32 v[222:223], v[22:23], v[226:227]
	v_exp_f32_e32 v222, v222
	v_exp_f32_e32 v223, v223
	v_pk_mul_f32 v[224:225], v[32:33], v[224:225]
	v_pk_add_f32 v[222:223], v[222:223], v[228:229]
	v_rcp_f32_e32 v222, v222
	v_rcp_f32_e32 v223, v223
	v_pk_mul_f32 v[28:29], v[224:225], v[28:29]
	v_pk_mul_f32 v[224:225], v[24:25], v[226:227]
	v_exp_f32_e32 v224, v224
	v_exp_f32_e32 v225, v225
	v_pk_mul_f32 v[222:223], v[22:23], v[222:223]
	v_pk_add_f32 v[224:225], v[224:225], v[228:229]
	v_rcp_f32_e32 v224, v224
	v_rcp_f32_e32 v225, v225
	v_pk_mul_f32 v[22:23], v[222:223], v[18:19]
	v_pk_mul_f32 v[222:223], v[14:15], v[226:227]
	v_exp_f32_e32 v222, v222
	v_exp_f32_e32 v223, v223
	v_pk_mul_f32 v[224:225], v[24:25], v[224:225]
	v_pk_add_f32 v[222:223], v[222:223], v[228:229]
	v_rcp_f32_e32 v222, v222
	v_rcp_f32_e32 v223, v223
	v_pk_mul_f32 v[24:25], v[224:225], v[20:21]
	v_cvt_pk_bf16_f32 v20, v22, v23
	v_add_u32_e32 v22, 0xa0, v145
	v_mad_i64_i32 v[22:23], s[20:21], v22, s7, v[114:115]
	v_cvt_pk_bf16_f32 v18, v26, v27
	v_cvt_pk_bf16_f32 v19, v28, v29
	v_cvt_pk_bf16_f32 v21, v24, v25
	v_lshl_add_u64 v[22:23], v[22:23], 0, v[116:117]
	global_store_dwordx4 v[22:23], v[18:21], off
	s_nop 1
	v_pk_mul_f32 v[224:225], v[16:17], v[226:227]
	v_exp_f32_e32 v224, v224
	v_exp_f32_e32 v225, v225
	v_pk_mul_f32 v[222:223], v[14:15], v[222:223]
	v_pk_add_f32 v[224:225], v[224:225], v[228:229]
	v_rcp_f32_e32 v224, v224
	v_rcp_f32_e32 v225, v225
	v_pk_mul_f32 v[10:11], v[222:223], v[10:11]
	v_pk_mul_f32 v[222:223], v[6:7], v[226:227]
	v_exp_f32_e32 v222, v222
	v_exp_f32_e32 v223, v223
	v_pk_mul_f32 v[224:225], v[16:17], v[224:225]
	v_pk_add_f32 v[222:223], v[222:223], v[228:229]
	v_rcp_f32_e32 v222, v222
	v_rcp_f32_e32 v223, v223
	v_pk_mul_f32 v[12:13], v[224:225], v[12:13]
	v_pk_mul_f32 v[224:225], v[8:9], v[226:227]
	v_exp_f32_e32 v224, v224
	v_exp_f32_e32 v225, v225
	v_pk_mul_f32 v[222:223], v[6:7], v[222:223]
	v_pk_add_f32 v[224:225], v[224:225], v[228:229]
	v_rcp_f32_e32 v224, v224
	v_rcp_f32_e32 v225, v225
	v_pk_mul_f32 v[6:7], v[222:223], v[2:3]
	v_pk_mul_f32 v[224:225], v[8:9], v[224:225]
	v_pk_mul_f32 v[8:9], v[224:225], v[4:5]
	v_cvt_pk_bf16_f32 v4, v6, v7
	v_add_u32_e32 v6, 0xb0, v145
	v_mad_i64_i32 v[6:7], s[20:21], v6, s7, v[114:115]
	v_cvt_pk_bf16_f32 v2, v10, v11
	v_cvt_pk_bf16_f32 v3, v12, v13
	v_cvt_pk_bf16_f32 v5, v8, v9
	v_lshl_add_u64 v[6:7], v[6:7], 0, v[116:117]
	s_mov_b64 s[20:21], s[12:13]
	global_store_dwordx4 v[6:7], v[2:5], off
	s_cbranch_vccz .LBB0_294
	s_waitcnt vmcnt(0)
	s_cmpk_gt_u32 s28, 0xff
	s_cbranch_scc1 .LBB0_301
	s_barrier

.LBB0_373:
	s_add_u32 s46, s16, 0x100
	s_addc_u32 s47, s17, 0
	s_mov_b32 s48, -2
	s_add_u32 s16, s14, 0x100
	s_addc_u32 s17, s15, 0
	s_add_i32 s49, 0, 0x10000
	v_add_u32_e32 v154, s49, v164
	ds_read_b128 v[142:145], v154
	ds_read_b128 v[146:149], v154 offset:1024
	ds_read_b128 v[150:153], v154 offset:2048
	ds_read_b128 v[154:157], v154 offset:3072
	s_cmp_eq_u32 s48, 40
	s_cselect_b32 s21, s7, s17
	s_cselect_b32 s20, s6, s16
	s_cselect_b32 s19, s9, s47
	s_cselect_b32 s18, s8, s46
	v_lshl_add_u64 v[162:163], s[14:15], 0, v[138:139]
	s_add_i32 m0, s35, 0xc000
	ds_read_b128 v[158:161], v166
	ds_read_b128 v[168:171], v166 offset:1024
	ds_read_b128 v[172:175], v166 offset:2048
	ds_read_b128 v[190:193], v166 offset:3072
	ds_read_b128 v[194:197], v166 offset:4096
	ds_read_b128 v[198:201], v166 offset:5120
	ds_read_b128 v[202:205], v166 offset:6144
	ds_read_b128 v[206:209], v166 offset:7168
	global_load_lds_dwordx4 v[162:163], off
	v_lshl_add_u64 v[162:163], s[14:15], 0, v[140:141]
	s_add_i32 m0, s35, 0xe000
	s_nop 0
	global_load_lds_dwordx4 v[162:163], off
	s_waitcnt lgkmcnt(8)
	s_barrier
	s_waitcnt lgkmcnt(0)
	s_waitcnt lgkmcnt(0)
	v_mfma_f32_16x16x32_bf16 v[126:129], v[142:145], v[158:161], 0
	v_mfma_f32_16x16x32_bf16 v[122:125], v[150:153], v[158:161], 0
	v_mfma_f32_16x16x32_bf16 v[110:113], v[142:145], v[172:175], 0
	v_mfma_f32_16x16x32_bf16 v[106:109], v[150:153], v[172:175], 0
	v_mfma_f32_16x16x32_bf16 v[94:97], v[142:145], v[194:197], 0
	v_mfma_f32_16x16x32_bf16 v[90:93], v[150:153], v[194:197], 0
	v_mfma_f32_16x16x32_bf16 v[78:81], v[142:145], v[202:205], 0
	v_mfma_f32_16x16x32_bf16 v[74:77], v[150:153], v[202:205], 0
	v_mfma_f32_16x16x32_bf16 v[126:129], v[146:149], v[168:171], v[126:129]
	v_mfma_f32_16x16x32_bf16 v[122:125], v[154:157], v[168:171], v[122:125]
	v_mfma_f32_16x16x32_bf16 v[110:113], v[146:149], v[190:193], v[110:113]
	v_mfma_f32_16x16x32_bf16 v[106:109], v[154:157], v[190:193], v[106:109]
	v_mfma_f32_16x16x32_bf16 v[94:97], v[146:149], v[198:201], v[94:97]
	v_mfma_f32_16x16x32_bf16 v[90:93], v[154:157], v[198:201], v[90:93]
	v_mfma_f32_16x16x32_bf16 v[78:81], v[146:149], v[206:209], v[78:81]
	v_mfma_f32_16x16x32_bf16 v[74:77], v[154:157], v[206:209], v[74:77]
	s_barrier
	s_add_i32 s50, 0, 0x14000
	v_add_u32_e32 v162, s50, v164
	s_add_i32 s14, s49, s34
	ds_read_b128 v[210:213], v162
	ds_read_b128 v[214:217], v162 offset:1024
	ds_read_b128 v[218:221], v162 offset:2048
	ds_read_b128 v[222:225], v162 offset:3072
	s_add_u32 s64, s18, 0x80
	s_addc_u32 s65, s19, 0
	s_mov_b32 m0, s14
	s_nop 0
	global_load_lds_dwordx4 v132, s[18:19]
	s_add_i32 m0, s14, 0x2000
	s_nop 0
	global_load_lds_dwordx4 v136, s[18:19]
	s_barrier
	s_waitcnt lgkmcnt(0)
	s_waitcnt lgkmcnt(0)
	v_mfma_f32_16x16x32_bf16 v[118:121], v[210:213], v[158:161], 0
	v_mfma_f32_16x16x32_bf16 v[114:117], v[218:221], v[158:161], 0
	v_mfma_f32_16x16x32_bf16 v[102:105], v[210:213], v[172:175], 0
	v_mfma_f32_16x16x32_bf16 v[98:101], v[218:221], v[172:175], 0
	v_mfma_f32_16x16x32_bf16 v[86:89], v[210:213], v[194:197], 0
	v_mfma_f32_16x16x32_bf16 v[82:85], v[218:221], v[194:197], 0
	v_mfma_f32_16x16x32_bf16 v[70:73], v[210:213], v[202:205], 0
	v_mfma_f32_16x16x32_bf16 v[66:69], v[218:221], v[202:205], 0
	v_mfma_f32_16x16x32_bf16 v[118:121], v[214:217], v[168:171], v[118:121]
	v_mfma_f32_16x16x32_bf16 v[114:117], v[222:225], v[168:171], v[114:117]
	v_mfma_f32_16x16x32_bf16 v[102:105], v[214:217], v[190:193], v[102:105]
	v_mfma_f32_16x16x32_bf16 v[98:101], v[222:225], v[190:193], v[98:101]
	v_mfma_f32_16x16x32_bf16 v[86:89], v[214:217], v[198:201], v[86:89]
	v_mfma_f32_16x16x32_bf16 v[82:85], v[222:225], v[198:201], v[82:85]
	v_mfma_f32_16x16x32_bf16 v[70:73], v[214:217], v[206:209], v[70:73]
	v_mfma_f32_16x16x32_bf16 v[66:69], v[222:225], v[206:209], v[66:69]
	s_barrier
	s_mov_b32 m0, s35
	s_add_u32 s62, s20, 0x80
	s_addc_u32 s63, s21, 0
	ds_read_b128 v[158:161], v166 offset:16384
	ds_read_b128 v[168:171], v166 offset:17408
	ds_read_b128 v[172:175], v166 offset:18432
	ds_read_b128 v[190:193], v166 offset:19456
	ds_read_b128 v[194:197], v166 offset:20480
	ds_read_b128 v[198:201], v166 offset:21504
	ds_read_b128 v[202:205], v166 offset:22528
	ds_read_b128 v[206:209], v166 offset:23552
	global_load_lds_dwordx4 v130, s[20:21]
	s_mov_b32 m0, s36
	s_nop 0
	global_load_lds_dwordx4 v134, s[20:21]
	s_waitcnt vmcnt(10)
	s_barrier
	s_waitcnt lgkmcnt(0)
	s_waitcnt lgkmcnt(0)
	v_mfma_f32_16x16x32_bf16 v[62:65], v[142:145], v[158:161], 0
	v_mfma_f32_16x16x32_bf16 v[58:61], v[150:153], v[158:161], 0
	v_mfma_f32_16x16x32_bf16 v[46:49], v[142:145], v[172:175], 0
	v_mfma_f32_16x16x32_bf16 v[42:45], v[150:153], v[172:175], 0
	v_mfma_f32_16x16x32_bf16 v[30:33], v[142:145], v[194:197], 0
	v_mfma_f32_16x16x32_bf16 v[26:29], v[150:153], v[194:197], 0
	v_mfma_f32_16x16x32_bf16 v[14:17], v[142:145], v[202:205], 0
	v_mfma_f32_16x16x32_bf16 v[10:13], v[150:153], v[202:205], 0
	v_mfma_f32_16x16x32_bf16 v[62:65], v[146:149], v[168:171], v[62:65]
	v_mfma_f32_16x16x32_bf16 v[58:61], v[154:157], v[168:171], v[58:61]
	v_mfma_f32_16x16x32_bf16 v[46:49], v[146:149], v[190:193], v[46:49]
	v_mfma_f32_16x16x32_bf16 v[42:45], v[154:157], v[190:193], v[42:45]
	v_mfma_f32_16x16x32_bf16 v[30:33], v[146:149], v[198:201], v[30:33]
	v_mfma_f32_16x16x32_bf16 v[26:29], v[154:157], v[198:201], v[26:29]
	v_mfma_f32_16x16x32_bf16 v[14:17], v[146:149], v[206:209], v[14:17]
	v_mfma_f32_16x16x32_bf16 v[10:13], v[154:157], v[206:209], v[10:13]
	s_barrier
	v_add_u32_e32 v154, 0x18000, v164
	ds_read_b128 v[142:145], v154
	ds_read_b128 v[146:149], v154 offset:1024
	ds_read_b128 v[150:153], v154 offset:2048
	ds_read_b128 v[154:157], v154 offset:3072
	s_add_u32 s14, s18, 0xb0000
	s_addc_u32 s15, s19, 0
	s_add_i32 s49, s50, s34
	s_mov_b32 m0, s49
	s_nop 0
	global_load_lds_dwordx4 v132, s[14:15]
	s_add_i32 m0, s49, 0x2000
	s_nop 0
	global_load_lds_dwordx4 v136, s[14:15]
	s_waitcnt vmcnt(6)
	s_barrier
	v_mfma_f32_16x16x32_bf16 v[54:57], v[210:213], v[158:161], 0
	v_mfma_f32_16x16x32_bf16 v[50:53], v[218:221], v[158:161], 0
	v_mfma_f32_16x16x32_bf16 v[38:41], v[210:213], v[172:175], 0
	v_mfma_f32_16x16x32_bf16 v[34:37], v[218:221], v[172:175], 0
	v_mfma_f32_16x16x32_bf16 v[22:25], v[210:213], v[194:197], 0
	v_mfma_f32_16x16x32_bf16 v[18:21], v[218:221], v[194:197], 0
	v_mfma_f32_16x16x32_bf16 v[6:9], v[210:213], v[202:205], 0
	v_mfma_f32_16x16x32_bf16 v[2:5], v[218:221], v[202:205], 0
	v_mfma_f32_16x16x32_bf16 v[54:57], v[214:217], v[168:171], v[54:57]
	v_mfma_f32_16x16x32_bf16 v[50:53], v[222:225], v[168:171], v[50:53]
	v_mfma_f32_16x16x32_bf16 v[38:41], v[214:217], v[190:193], v[38:41]
	v_mfma_f32_16x16x32_bf16 v[34:37], v[222:225], v[190:193], v[34:37]
	v_mfma_f32_16x16x32_bf16 v[22:25], v[214:217], v[198:201], v[22:25]
	v_mfma_f32_16x16x32_bf16 v[18:21], v[222:225], v[198:201], v[18:21]
	v_mfma_f32_16x16x32_bf16 v[6:9], v[214:217], v[206:209], v[6:9]
	v_mfma_f32_16x16x32_bf16 v[2:5], v[222:225], v[206:209], v[2:5]
	s_barrier
	s_add_i32 s49, 0, 0x18000
	s_add_u32 s14, s20, 0xb8000
	s_addc_u32 s15, s21, 0
	s_mov_b32 m0, s37
	ds_read_b128 v[158:161], v166 offset:32768
	ds_read_b128 v[168:171], v166 offset:33792
	ds_read_b128 v[172:175], v166 offset:34816
	ds_read_b128 v[190:193], v166 offset:35840
	ds_read_b128 v[194:197], v166 offset:36864
	ds_read_b128 v[198:201], v166 offset:37888
	ds_read_b128 v[202:205], v166 offset:38912
	ds_read_b128 v[206:209], v166 offset:39936
	global_load_lds_dwordx4 v130, s[14:15]
	s_mov_b32 m0, s38
	s_nop 0
	global_load_lds_dwordx4 v134, s[14:15]
	s_waitcnt lgkmcnt(8)
	s_barrier
	s_waitcnt lgkmcnt(0)
	s_waitcnt lgkmcnt(0)
	v_mfma_f32_16x16x32_bf16 v[126:129], v[142:145], v[158:161], v[126:129]
	v_mfma_f32_16x16x32_bf16 v[122:125], v[150:153], v[158:161], v[122:125]
	v_mfma_f32_16x16x32_bf16 v[110:113], v[142:145], v[172:175], v[110:113]
	v_mfma_f32_16x16x32_bf16 v[106:109], v[150:153], v[172:175], v[106:109]
	v_mfma_f32_16x16x32_bf16 v[94:97], v[142:145], v[194:197], v[94:97]
	v_mfma_f32_16x16x32_bf16 v[90:93], v[150:153], v[194:197], v[90:93]
	v_mfma_f32_16x16x32_bf16 v[78:81], v[142:145], v[202:205], v[78:81]
	v_mfma_f32_16x16x32_bf16 v[74:77], v[150:153], v[202:205], v[74:77]
	v_mfma_f32_16x16x32_bf16 v[126:129], v[146:149], v[168:171], v[126:129]
	v_mfma_f32_16x16x32_bf16 v[122:125], v[154:157], v[168:171], v[122:125]
	v_mfma_f32_16x16x32_bf16 v[110:113], v[146:149], v[190:193], v[110:113]
	v_mfma_f32_16x16x32_bf16 v[106:109], v[154:157], v[190:193], v[106:109]
	v_mfma_f32_16x16x32_bf16 v[94:97], v[146:149], v[198:201], v[94:97]
	v_mfma_f32_16x16x32_bf16 v[90:93], v[154:157], v[198:201], v[90:93]
	v_mfma_f32_16x16x32_bf16 v[78:81], v[146:149], v[206:209], v[78:81]
	v_mfma_f32_16x16x32_bf16 v[74:77], v[154:157], v[206:209], v[74:77]
	s_barrier
	s_add_i32 s20, 0, 0x1c000
	s_add_i32 s14, s49, s34
	v_add_u32_e32 v167, s20, v164
	s_mov_b32 m0, s14
	ds_read_b128 v[210:213], v167
	ds_read_b128 v[214:217], v167 offset:1024
	ds_read_b128 v[218:221], v167 offset:2048
	ds_read_b128 v[222:225], v167 offset:3072
	global_load_lds_dwordx4 v132, s[64:65]
	s_add_i32 m0, s14, 0x2000
	s_nop 0
	global_load_lds_dwordx4 v136, s[64:65]
	s_barrier
	s_waitcnt lgkmcnt(0)
	s_waitcnt lgkmcnt(0)
	v_mfma_f32_16x16x32_bf16 v[118:121], v[210:213], v[158:161], v[118:121]
	v_mfma_f32_16x16x32_bf16 v[114:117], v[218:221], v[158:161], v[114:117]
	v_mfma_f32_16x16x32_bf16 v[102:105], v[210:213], v[172:175], v[102:105]
	v_mfma_f32_16x16x32_bf16 v[98:101], v[218:221], v[172:175], v[98:101]
	v_mfma_f32_16x16x32_bf16 v[86:89], v[210:213], v[194:197], v[86:89]
	v_mfma_f32_16x16x32_bf16 v[82:85], v[218:221], v[194:197], v[82:85]
	v_mfma_f32_16x16x32_bf16 v[70:73], v[210:213], v[202:205], v[70:73]
	v_mfma_f32_16x16x32_bf16 v[66:69], v[218:221], v[202:205], v[66:69]
	v_mfma_f32_16x16x32_bf16 v[118:121], v[214:217], v[168:171], v[118:121]
	v_mfma_f32_16x16x32_bf16 v[114:117], v[222:225], v[168:171], v[114:117]
	v_mfma_f32_16x16x32_bf16 v[102:105], v[214:217], v[190:193], v[102:105]
	v_mfma_f32_16x16x32_bf16 v[98:101], v[222:225], v[190:193], v[98:101]
	v_mfma_f32_16x16x32_bf16 v[86:89], v[214:217], v[198:201], v[86:89]
	v_mfma_f32_16x16x32_bf16 v[82:85], v[222:225], v[198:201], v[82:85]
	v_mfma_f32_16x16x32_bf16 v[70:73], v[214:217], v[206:209], v[70:73]
	v_mfma_f32_16x16x32_bf16 v[66:69], v[222:225], v[206:209], v[66:69]
	s_barrier
	s_mov_b32 m0, s39
	ds_read_b128 v[158:161], v166 offset:49152
	ds_read_b128 v[168:171], v166 offset:50176
	ds_read_b128 v[172:175], v166 offset:51200
	ds_read_b128 v[190:193], v166 offset:52224
	ds_read_b128 v[194:197], v166 offset:53248
	ds_read_b128 v[198:201], v166 offset:54272
	ds_read_b128 v[202:205], v166 offset:55296
	ds_read_b128 v[206:209], v166 offset:56320
	global_load_lds_dwordx4 v130, s[62:63]
	s_mov_b32 m0, s40
	s_nop 0
	global_load_lds_dwordx4 v134, s[62:63]
	s_waitcnt vmcnt(10)
	s_barrier
	s_waitcnt lgkmcnt(0)
	s_waitcnt lgkmcnt(0)
	v_mfma_f32_16x16x32_bf16 v[62:65], v[142:145], v[158:161], v[62:65]
	v_mfma_f32_16x16x32_bf16 v[58:61], v[150:153], v[158:161], v[58:61]
	v_mfma_f32_16x16x32_bf16 v[46:49], v[142:145], v[172:175], v[46:49]
	v_mfma_f32_16x16x32_bf16 v[42:45], v[150:153], v[172:175], v[42:45]
	v_mfma_f32_16x16x32_bf16 v[30:33], v[142:145], v[194:197], v[30:33]
	v_mfma_f32_16x16x32_bf16 v[26:29], v[150:153], v[194:197], v[26:29]
	v_mfma_f32_16x16x32_bf16 v[14:17], v[142:145], v[202:205], v[14:17]
	v_mfma_f32_16x16x32_bf16 v[10:13], v[150:153], v[202:205], v[10:13]
	v_mfma_f32_16x16x32_bf16 v[62:65], v[146:149], v[168:171], v[62:65]
	v_mfma_f32_16x16x32_bf16 v[58:61], v[154:157], v[168:171], v[58:61]
	v_mfma_f32_16x16x32_bf16 v[46:49], v[146:149], v[190:193], v[46:49]
	v_mfma_f32_16x16x32_bf16 v[42:45], v[154:157], v[190:193], v[42:45]
	v_mfma_f32_16x16x32_bf16 v[30:33], v[146:149], v[198:201], v[30:33]
	v_mfma_f32_16x16x32_bf16 v[26:29], v[154:157], v[198:201], v[26:29]
	v_mfma_f32_16x16x32_bf16 v[14:17], v[146:149], v[206:209], v[14:17]
	v_mfma_f32_16x16x32_bf16 v[10:13], v[154:157], v[206:209], v[10:13]
	s_barrier
	v_add_u32_e32 v154, 0x10000, v164
	ds_read_b128 v[142:145], v154
	ds_read_b128 v[146:149], v154 offset:1024
	ds_read_b128 v[150:153], v154 offset:2048
	ds_read_b128 v[154:157], v154 offset:3072
	s_add_u32 s14, s18, 0xb0080
	s_addc_u32 s15, s19, 0
	s_add_i32 s18, s20, s34
	s_mov_b32 m0, s18
	s_nop 0
	global_load_lds_dwordx4 v132, s[14:15]
	s_add_i32 m0, s18, 0x2000
	s_nop 0
	global_load_lds_dwordx4 v136, s[14:15]
	s_waitcnt vmcnt(6)
	s_barrier
	v_mfma_f32_16x16x32_bf16 v[54:57], v[210:213], v[158:161], v[54:57]
	v_mfma_f32_16x16x32_bf16 v[50:53], v[218:221], v[158:161], v[50:53]
	v_mfma_f32_16x16x32_bf16 v[38:41], v[210:213], v[172:175], v[38:41]
	v_mfma_f32_16x16x32_bf16 v[34:37], v[218:221], v[172:175], v[34:37]
	v_mfma_f32_16x16x32_bf16 v[22:25], v[210:213], v[194:197], v[22:25]
	v_mfma_f32_16x16x32_bf16 v[18:21], v[218:221], v[194:197], v[18:21]
	v_mfma_f32_16x16x32_bf16 v[6:9], v[210:213], v[202:205], v[6:9]
	v_mfma_f32_16x16x32_bf16 v[2:5], v[218:221], v[202:205], v[2:5]
	v_mfma_f32_16x16x32_bf16 v[54:57], v[214:217], v[168:171], v[54:57]
	v_mfma_f32_16x16x32_bf16 v[50:53], v[222:225], v[168:171], v[50:53]
	v_mfma_f32_16x16x32_bf16 v[38:41], v[214:217], v[190:193], v[38:41]
	v_mfma_f32_16x16x32_bf16 v[34:37], v[222:225], v[190:193], v[34:37]
	v_mfma_f32_16x16x32_bf16 v[22:25], v[214:217], v[198:201], v[22:25]
	v_mfma_f32_16x16x32_bf16 v[18:21], v[222:225], v[198:201], v[18:21]
	v_mfma_f32_16x16x32_bf16 v[6:9], v[214:217], v[206:209], v[6:9]
	v_mfma_f32_16x16x32_bf16 v[2:5], v[222:225], v[206:209], v[2:5]
	s_barrier
	s_add_i32 s48, s48, 2
	s_add_u32 s46, s46, 0x100
	s_addc_u32 s47, s47, 0
	s_mov_b64 s[14:15], s[16:17]
.LBB0_374:
	s_add_u32 s16, s14, 0x100
	s_addc_u32 s17, s15, 0
	s_add_i32 s49, 0, 0x10000
	s_cmp_eq_u32 s48, 40
	s_cselect_b32 s21, s7, s17
	s_cselect_b32 s20, s6, s16
	s_cselect_b32 s19, s9, s47
	s_cselect_b32 s18, s8, s46
	v_lshl_add_u64 v[162:163], s[14:15], 0, v[138:139]
	s_add_i32 m0, s35, 0xc000
	ds_read_b128 v[158:161], v166
	ds_read_b128 v[168:171], v166 offset:1024
	ds_read_b128 v[172:175], v166 offset:2048
	ds_read_b128 v[190:193], v166 offset:3072
	ds_read_b128 v[194:197], v166 offset:4096
	ds_read_b128 v[198:201], v166 offset:5120
	ds_read_b128 v[202:205], v166 offset:6144
	ds_read_b128 v[206:209], v166 offset:7168
	global_load_lds_dwordx4 v[162:163], off
	v_lshl_add_u64 v[162:163], s[14:15], 0, v[140:141]
	s_add_i32 m0, s35, 0xe000
	s_nop 0
	global_load_lds_dwordx4 v[162:163], off
	s_waitcnt lgkmcnt(8)
	s_barrier
	s_waitcnt lgkmcnt(0)
	s_waitcnt lgkmcnt(0)
	v_mfma_f32_16x16x32_bf16 v[126:129], v[142:145], v[158:161], v[126:129]
	v_mfma_f32_16x16x32_bf16 v[122:125], v[150:153], v[158:161], v[122:125]
	v_mfma_f32_16x16x32_bf16 v[110:113], v[142:145], v[172:175], v[110:113]
	v_mfma_f32_16x16x32_bf16 v[106:109], v[150:153], v[172:175], v[106:109]
	v_mfma_f32_16x16x32_bf16 v[94:97], v[142:145], v[194:197], v[94:97]
	v_mfma_f32_16x16x32_bf16 v[90:93], v[150:153], v[194:197], v[90:93]
	v_mfma_f32_16x16x32_bf16 v[78:81], v[142:145], v[202:205], v[78:81]
	v_mfma_f32_16x16x32_bf16 v[74:77], v[150:153], v[202:205], v[74:77]
	v_mfma_f32_16x16x32_bf16 v[126:129], v[146:149], v[168:171], v[126:129]
	v_mfma_f32_16x16x32_bf16 v[122:125], v[154:157], v[168:171], v[122:125]
	v_mfma_f32_16x16x32_bf16 v[110:113], v[146:149], v[190:193], v[110:113]
	v_mfma_f32_16x16x32_bf16 v[106:109], v[154:157], v[190:193], v[106:109]
	v_mfma_f32_16x16x32_bf16 v[94:97], v[146:149], v[198:201], v[94:97]
	v_mfma_f32_16x16x32_bf16 v[90:93], v[154:157], v[198:201], v[90:93]
	v_mfma_f32_16x16x32_bf16 v[78:81], v[146:149], v[206:209], v[78:81]
	v_mfma_f32_16x16x32_bf16 v[74:77], v[154:157], v[206:209], v[74:77]
	s_barrier
	s_add_i32 s50, 0, 0x14000
	v_add_u32_e32 v162, s50, v164
	s_add_i32 s14, s49, s34
	ds_read_b128 v[210:213], v162
	ds_read_b128 v[214:217], v162 offset:1024
	ds_read_b128 v[218:221], v162 offset:2048
	ds_read_b128 v[222:225], v162 offset:3072
	s_add_u32 s64, s18, 0x80
	s_addc_u32 s65, s19, 0
	s_mov_b32 m0, s14
	s_nop 0
	global_load_lds_dwordx4 v132, s[18:19]
	s_add_i32 m0, s14, 0x2000
	s_nop 0
	global_load_lds_dwordx4 v136, s[18:19]
	s_barrier
	s_waitcnt lgkmcnt(0)
	s_waitcnt lgkmcnt(0)
	v_mfma_f32_16x16x32_bf16 v[118:121], v[210:213], v[158:161], v[118:121]
	v_mfma_f32_16x16x32_bf16 v[114:117], v[218:221], v[158:161], v[114:117]
	v_mfma_f32_16x16x32_bf16 v[102:105], v[210:213], v[172:175], v[102:105]
	v_mfma_f32_16x16x32_bf16 v[98:101], v[218:221], v[172:175], v[98:101]
	v_mfma_f32_16x16x32_bf16 v[86:89], v[210:213], v[194:197], v[86:89]
	v_mfma_f32_16x16x32_bf16 v[82:85], v[218:221], v[194:197], v[82:85]
	v_mfma_f32_16x16x32_bf16 v[70:73], v[210:213], v[202:205], v[70:73]
	v_mfma_f32_16x16x32_bf16 v[66:69], v[218:221], v[202:205], v[66:69]
	v_mfma_f32_16x16x32_bf16 v[118:121], v[214:217], v[168:171], v[118:121]
	v_mfma_f32_16x16x32_bf16 v[114:117], v[222:225], v[168:171], v[114:117]
	v_mfma_f32_16x16x32_bf16 v[102:105], v[214:217], v[190:193], v[102:105]
	v_mfma_f32_16x16x32_bf16 v[98:101], v[222:225], v[190:193], v[98:101]
	v_mfma_f32_16x16x32_bf16 v[86:89], v[214:217], v[198:201], v[86:89]
	v_mfma_f32_16x16x32_bf16 v[82:85], v[222:225], v[198:201], v[82:85]
	v_mfma_f32_16x16x32_bf16 v[70:73], v[214:217], v[206:209], v[70:73]
	v_mfma_f32_16x16x32_bf16 v[66:69], v[222:225], v[206:209], v[66:69]
	s_barrier
	s_mov_b32 m0, s35
	s_add_u32 s62, s20, 0x80
	s_addc_u32 s63, s21, 0
	ds_read_b128 v[158:161], v166 offset:16384
	ds_read_b128 v[168:171], v166 offset:17408
	ds_read_b128 v[172:175], v166 offset:18432
	ds_read_b128 v[190:193], v166 offset:19456
	ds_read_b128 v[194:197], v166 offset:20480
	ds_read_b128 v[198:201], v166 offset:21504
	ds_read_b128 v[202:205], v166 offset:22528
	ds_read_b128 v[206:209], v166 offset:23552
	global_load_lds_dwordx4 v130, s[20:21]
	s_mov_b32 m0, s36
	s_nop 0
	global_load_lds_dwordx4 v134, s[20:21]
	s_waitcnt vmcnt(10)
	s_barrier
	s_waitcnt lgkmcnt(0)
	s_waitcnt lgkmcnt(0)
	v_mfma_f32_16x16x32_bf16 v[62:65], v[142:145], v[158:161], v[62:65]
	v_mfma_f32_16x16x32_bf16 v[58:61], v[150:153], v[158:161], v[58:61]
	v_mfma_f32_16x16x32_bf16 v[46:49], v[142:145], v[172:175], v[46:49]
	v_mfma_f32_16x16x32_bf16 v[42:45], v[150:153], v[172:175], v[42:45]
	v_mfma_f32_16x16x32_bf16 v[30:33], v[142:145], v[194:197], v[30:33]
	v_mfma_f32_16x16x32_bf16 v[26:29], v[150:153], v[194:197], v[26:29]
	v_mfma_f32_16x16x32_bf16 v[14:17], v[142:145], v[202:205], v[14:17]
	v_mfma_f32_16x16x32_bf16 v[10:13], v[150:153], v[202:205], v[10:13]
	v_mfma_f32_16x16x32_bf16 v[62:65], v[146:149], v[168:171], v[62:65]
	v_mfma_f32_16x16x32_bf16 v[58:61], v[154:157], v[168:171], v[58:61]
	v_mfma_f32_16x16x32_bf16 v[46:49], v[146:149], v[190:193], v[46:49]
	v_mfma_f32_16x16x32_bf16 v[42:45], v[154:157], v[190:193], v[42:45]
	v_mfma_f32_16x16x32_bf16 v[30:33], v[146:149], v[198:201], v[30:33]
	v_mfma_f32_16x16x32_bf16 v[26:29], v[154:157], v[198:201], v[26:29]
	v_mfma_f32_16x16x32_bf16 v[14:17], v[146:149], v[206:209], v[14:17]
	v_mfma_f32_16x16x32_bf16 v[10:13], v[154:157], v[206:209], v[10:13]
	s_barrier
	v_add_u32_e32 v154, 0x18000, v164
	ds_read_b128 v[142:145], v154
	ds_read_b128 v[146:149], v154 offset:1024
	ds_read_b128 v[150:153], v154 offset:2048
	ds_read_b128 v[154:157], v154 offset:3072
	s_add_u32 s14, s18, 0xb0000
	s_addc_u32 s15, s19, 0
	s_add_i32 s49, s50, s34
	s_mov_b32 m0, s49
	s_nop 0
	global_load_lds_dwordx4 v132, s[14:15]
	s_add_i32 m0, s49, 0x2000
	s_nop 0
	global_load_lds_dwordx4 v136, s[14:15]
	s_waitcnt vmcnt(6)
	s_barrier
	v_mfma_f32_16x16x32_bf16 v[54:57], v[210:213], v[158:161], v[54:57]
	v_mfma_f32_16x16x32_bf16 v[50:53], v[218:221], v[158:161], v[50:53]
	v_mfma_f32_16x16x32_bf16 v[38:41], v[210:213], v[172:175], v[38:41]
	v_mfma_f32_16x16x32_bf16 v[34:37], v[218:221], v[172:175], v[34:37]
	v_mfma_f32_16x16x32_bf16 v[22:25], v[210:213], v[194:197], v[22:25]
	v_mfma_f32_16x16x32_bf16 v[18:21], v[218:221], v[194:197], v[18:21]
	v_mfma_f32_16x16x32_bf16 v[6:9], v[210:213], v[202:205], v[6:9]
	v_mfma_f32_16x16x32_bf16 v[2:5], v[218:221], v[202:205], v[2:5]
	v_mfma_f32_16x16x32_bf16 v[54:57], v[214:217], v[168:171], v[54:57]
	v_mfma_f32_16x16x32_bf16 v[50:53], v[222:225], v[168:171], v[50:53]
	v_mfma_f32_16x16x32_bf16 v[38:41], v[214:217], v[190:193], v[38:41]
	v_mfma_f32_16x16x32_bf16 v[34:37], v[222:225], v[190:193], v[34:37]
	v_mfma_f32_16x16x32_bf16 v[22:25], v[214:217], v[198:201], v[22:25]
	v_mfma_f32_16x16x32_bf16 v[18:21], v[222:225], v[198:201], v[18:21]
	v_mfma_f32_16x16x32_bf16 v[6:9], v[214:217], v[206:209], v[6:9]
	v_mfma_f32_16x16x32_bf16 v[2:5], v[222:225], v[206:209], v[2:5]
	s_barrier
	s_add_i32 s49, 0, 0x18000
	s_add_u32 s14, s20, 0xb8000
	s_addc_u32 s15, s21, 0
	s_mov_b32 m0, s37
	ds_read_b128 v[158:161], v166 offset:32768
	ds_read_b128 v[168:171], v166 offset:33792
	ds_read_b128 v[172:175], v166 offset:34816
	ds_read_b128 v[190:193], v166 offset:35840
	ds_read_b128 v[194:197], v166 offset:36864
	ds_read_b128 v[198:201], v166 offset:37888
	ds_read_b128 v[202:205], v166 offset:38912
	ds_read_b128 v[206:209], v166 offset:39936
	global_load_lds_dwordx4 v130, s[14:15]
	s_mov_b32 m0, s38
	s_nop 0
	global_load_lds_dwordx4 v134, s[14:15]
	s_waitcnt lgkmcnt(8)
	s_barrier
	s_waitcnt lgkmcnt(0)
	s_waitcnt lgkmcnt(0)
	v_mfma_f32_16x16x32_bf16 v[126:129], v[142:145], v[158:161], v[126:129]
	v_mfma_f32_16x16x32_bf16 v[122:125], v[150:153], v[158:161], v[122:125]
	v_mfma_f32_16x16x32_bf16 v[110:113], v[142:145], v[172:175], v[110:113]
	v_mfma_f32_16x16x32_bf16 v[106:109], v[150:153], v[172:175], v[106:109]
	v_mfma_f32_16x16x32_bf16 v[94:97], v[142:145], v[194:197], v[94:97]
	v_mfma_f32_16x16x32_bf16 v[90:93], v[150:153], v[194:197], v[90:93]
	v_mfma_f32_16x16x32_bf16 v[78:81], v[142:145], v[202:205], v[78:81]
	v_mfma_f32_16x16x32_bf16 v[74:77], v[150:153], v[202:205], v[74:77]
	v_mfma_f32_16x16x32_bf16 v[126:129], v[146:149], v[168:171], v[126:129]
	v_mfma_f32_16x16x32_bf16 v[122:125], v[154:157], v[168:171], v[122:125]
	v_mfma_f32_16x16x32_bf16 v[110:113], v[146:149], v[190:193], v[110:113]
	v_mfma_f32_16x16x32_bf16 v[106:109], v[154:157], v[190:193], v[106:109]
	v_mfma_f32_16x16x32_bf16 v[94:97], v[146:149], v[198:201], v[94:97]
	v_mfma_f32_16x16x32_bf16 v[90:93], v[154:157], v[198:201], v[90:93]
	v_mfma_f32_16x16x32_bf16 v[78:81], v[146:149], v[206:209], v[78:81]
	v_mfma_f32_16x16x32_bf16 v[74:77], v[154:157], v[206:209], v[74:77]
	s_barrier
	s_add_i32 s20, 0, 0x1c000
	s_add_i32 s14, s49, s34
	v_add_u32_e32 v167, s20, v164
	s_mov_b32 m0, s14
	ds_read_b128 v[210:213], v167
	ds_read_b128 v[214:217], v167 offset:1024
	ds_read_b128 v[218:221], v167 offset:2048
	ds_read_b128 v[222:225], v167 offset:3072
	global_load_lds_dwordx4 v132, s[64:65]
	s_add_i32 m0, s14, 0x2000
	s_nop 0
	global_load_lds_dwordx4 v136, s[64:65]
	s_barrier
	s_waitcnt lgkmcnt(0)
	s_waitcnt lgkmcnt(0)
	v_mfma_f32_16x16x32_bf16 v[118:121], v[210:213], v[158:161], v[118:121]
	v_mfma_f32_16x16x32_bf16 v[114:117], v[218:221], v[158:161], v[114:117]
	v_mfma_f32_16x16x32_bf16 v[102:105], v[210:213], v[172:175], v[102:105]
	v_mfma_f32_16x16x32_bf16 v[98:101], v[218:221], v[172:175], v[98:101]
	v_mfma_f32_16x16x32_bf16 v[86:89], v[210:213], v[194:197], v[86:89]
	v_mfma_f32_16x16x32_bf16 v[82:85], v[218:221], v[194:197], v[82:85]
	v_mfma_f32_16x16x32_bf16 v[70:73], v[210:213], v[202:205], v[70:73]
	v_mfma_f32_16x16x32_bf16 v[66:69], v[218:221], v[202:205], v[66:69]
	v_mfma_f32_16x16x32_bf16 v[118:121], v[214:217], v[168:171], v[118:121]
	v_mfma_f32_16x16x32_bf16 v[114:117], v[222:225], v[168:171], v[114:117]
	v_mfma_f32_16x16x32_bf16 v[102:105], v[214:217], v[190:193], v[102:105]
	v_mfma_f32_16x16x32_bf16 v[98:101], v[222:225], v[190:193], v[98:101]
	v_mfma_f32_16x16x32_bf16 v[86:89], v[214:217], v[198:201], v[86:89]
	v_mfma_f32_16x16x32_bf16 v[82:85], v[222:225], v[198:201], v[82:85]
	v_mfma_f32_16x16x32_bf16 v[70:73], v[214:217], v[206:209], v[70:73]
	v_mfma_f32_16x16x32_bf16 v[66:69], v[222:225], v[206:209], v[66:69]
	s_barrier
	s_mov_b32 m0, s39
	ds_read_b128 v[158:161], v166 offset:49152
	ds_read_b128 v[168:171], v166 offset:50176
	ds_read_b128 v[172:175], v166 offset:51200
	ds_read_b128 v[190:193], v166 offset:52224
	ds_read_b128 v[194:197], v166 offset:53248
	ds_read_b128 v[198:201], v166 offset:54272
	ds_read_b128 v[202:205], v166 offset:55296
	ds_read_b128 v[206:209], v166 offset:56320
	global_load_lds_dwordx4 v130, s[62:63]
	s_mov_b32 m0, s40
	s_nop 0
	global_load_lds_dwordx4 v134, s[62:63]
	s_waitcnt vmcnt(10)
	s_barrier
	s_waitcnt lgkmcnt(0)
	s_waitcnt lgkmcnt(0)
	v_mfma_f32_16x16x32_bf16 v[62:65], v[142:145], v[158:161], v[62:65]
	v_mfma_f32_16x16x32_bf16 v[58:61], v[150:153], v[158:161], v[58:61]
	v_mfma_f32_16x16x32_bf16 v[46:49], v[142:145], v[172:175], v[46:49]
	v_mfma_f32_16x16x32_bf16 v[42:45], v[150:153], v[172:175], v[42:45]
	v_mfma_f32_16x16x32_bf16 v[30:33], v[142:145], v[194:197], v[30:33]
	v_mfma_f32_16x16x32_bf16 v[26:29], v[150:153], v[194:197], v[26:29]
	v_mfma_f32_16x16x32_bf16 v[14:17], v[142:145], v[202:205], v[14:17]
	v_mfma_f32_16x16x32_bf16 v[10:13], v[150:153], v[202:205], v[10:13]
	v_mfma_f32_16x16x32_bf16 v[62:65], v[146:149], v[168:171], v[62:65]
	v_mfma_f32_16x16x32_bf16 v[58:61], v[154:157], v[168:171], v[58:61]
	v_mfma_f32_16x16x32_bf16 v[46:49], v[146:149], v[190:193], v[46:49]
	v_mfma_f32_16x16x32_bf16 v[42:45], v[154:157], v[190:193], v[42:45]
	v_mfma_f32_16x16x32_bf16 v[30:33], v[146:149], v[198:201], v[30:33]
	v_mfma_f32_16x16x32_bf16 v[26:29], v[154:157], v[198:201], v[26:29]
	v_mfma_f32_16x16x32_bf16 v[14:17], v[146:149], v[206:209], v[14:17]
	v_mfma_f32_16x16x32_bf16 v[10:13], v[154:157], v[206:209], v[10:13]
	s_barrier
	v_add_u32_e32 v154, 0x10000, v164
	ds_read_b128 v[142:145], v154
	ds_read_b128 v[146:149], v154 offset:1024
	ds_read_b128 v[150:153], v154 offset:2048
	ds_read_b128 v[154:157], v154 offset:3072
	s_add_u32 s14, s18, 0xb0080
	s_addc_u32 s15, s19, 0
	s_add_i32 s18, s20, s34
	s_mov_b32 m0, s18
	s_nop 0
	global_load_lds_dwordx4 v132, s[14:15]
	s_add_i32 m0, s18, 0x2000
	s_nop 0
	global_load_lds_dwordx4 v136, s[14:15]
	s_waitcnt vmcnt(6)
	s_barrier
	v_mfma_f32_16x16x32_bf16 v[54:57], v[210:213], v[158:161], v[54:57]
	v_mfma_f32_16x16x32_bf16 v[50:53], v[218:221], v[158:161], v[50:53]
	v_mfma_f32_16x16x32_bf16 v[38:41], v[210:213], v[172:175], v[38:41]
	v_mfma_f32_16x16x32_bf16 v[34:37], v[218:221], v[172:175], v[34:37]
	v_mfma_f32_16x16x32_bf16 v[22:25], v[210:213], v[194:197], v[22:25]
	v_mfma_f32_16x16x32_bf16 v[18:21], v[218:221], v[194:197], v[18:21]
	v_mfma_f32_16x16x32_bf16 v[6:9], v[210:213], v[202:205], v[6:9]
	v_mfma_f32_16x16x32_bf16 v[2:5], v[218:221], v[202:205], v[2:5]
	v_mfma_f32_16x16x32_bf16 v[54:57], v[214:217], v[168:171], v[54:57]
	v_mfma_f32_16x16x32_bf16 v[50:53], v[222:225], v[168:171], v[50:53]
	v_mfma_f32_16x16x32_bf16 v[38:41], v[214:217], v[190:193], v[38:41]
	v_mfma_f32_16x16x32_bf16 v[34:37], v[222:225], v[190:193], v[34:37]
	v_mfma_f32_16x16x32_bf16 v[22:25], v[214:217], v[198:201], v[22:25]
	v_mfma_f32_16x16x32_bf16 v[18:21], v[222:225], v[198:201], v[18:21]
	v_mfma_f32_16x16x32_bf16 v[6:9], v[214:217], v[206:209], v[6:9]
	v_mfma_f32_16x16x32_bf16 v[2:5], v[222:225], v[206:209], v[2:5]
	s_barrier
	s_add_i32 s48, s48, 2
	s_add_u32 s46, s46, 0x100
	s_addc_u32 s47, s47, 0
	s_cmp_gt_u32 s48, 41
	s_mov_b64 s[14:15], s[16:17]
	s_cbranch_scc0 .LBB0_374
	s_waitcnt lgkmcnt(0)
	s_ashr_i32 s14, s33, 5
	s_mul_hi_i32 s15, s14, 0x9000
	s_mul_i32 s14, s14, 0x9000
	v_lshl_or_b32 v158, s45, 8, v165
	s_add_u32 s14, s26, s14
	s_addc_u32 s15, s27, s15
	v_ashrrev_i32_e32 v159, 31, v158
	v_lshl_add_u64 v[160:161], v[158:159], 2, s[14:15]
	global_load_dwordx4 v[142:145], v[160:161], off offset:16
	global_load_dwordx4 v[146:149], v[160:161], off
	v_lshl_add_u32 v162, s33, 8, v1
	v_ashrrev_i32_e32 v163, 31, v162
	v_lshlrev_b64 v[150:151], 12, v[162:163]
	v_lshl_add_u64 v[150:151], s[12:13], 0, v[150:151]
	v_lshl_add_u64 v[150:151], v[158:159], 1, v[150:151]
	v_mov_b32_e32 v152, 0x10000
	v_mov_b32_e32 v153, 0
	global_load_dwordx4 v[174:177], v[150:151], off offset:2048
	global_load_dwordx4 v[186:189], v[150:151], off offset:2304
	v_lshl_add_u64 v[150:151], v[150:151], 0, v[152:153]
	global_load_dwordx4 v[190:193], v[150:151], off offset:2048
	global_load_dwordx4 v[194:197], v[150:151], off offset:2304
	v_lshl_add_u64 v[150:151], v[150:151], 0, v[152:153]
	global_load_dwordx4 v[198:201], v[150:151], off offset:2048
	global_load_dwordx4 v[202:205], v[150:151], off offset:2304
	v_lshl_add_u64 v[150:151], v[150:151], 0, v[152:153]
	global_load_dwordx4 v[206:209], v[150:151], off offset:2048
	global_load_dwordx4 v[210:213], v[150:151], off offset:2304
	v_mov_b32_e32 v152, 0x50000
	v_lshl_add_u64 v[150:151], v[150:151], 0, v[152:153]
	v_mov_b32_e32 v152, 0x10000
	global_load_dwordx4 v[214:217], v[150:151], off offset:2048
	global_load_dwordx4 v[218:221], v[150:151], off offset:2304
	v_lshl_add_u64 v[150:151], v[150:151], 0, v[152:153]
	global_load_dwordx4 v[222:225], v[150:151], off offset:2048
	global_load_dwordx4 v[226:229], v[150:151], off offset:2304
	v_lshl_add_u64 v[150:151], v[150:151], 0, v[152:153]
	global_load_dwordx4 v[230:233], v[150:151], off offset:2048
	global_load_dwordx4 v[236:239], v[150:151], off offset:2304
	v_lshl_add_u64 v[150:151], v[150:151], 0, v[152:153]
	global_load_dwordx4 v[246:249], v[150:151], off offset:2048
	global_load_dwordx4 v[250:253], v[150:151], off offset:2304
	s_mov_b64 s[14:15], 0x80000
	s_and_b64 vcc, exec, s[4:5]
	s_mov_b32 s45, s43
	s_mov_b32 s33, s44
	s_mov_b64 s[16:17], s[8:9]
	s_waitcnt vmcnt(0)
	v_pk_add_f32 v[144:145], v[144:145], 1.0 op_sel_hi:[1,0]
	v_pk_add_f32 v[148:149], v[148:149], 1.0 op_sel_hi:[1,0]
	v_pk_add_f32 v[146:147], v[146:147], 1.0 op_sel_hi:[1,0]
	v_pk_add_f32 v[142:143], v[142:143], 1.0 op_sel_hi:[1,0]
	v_pk_mul_f32 v[152:153], v[148:149], 0.5 op_sel_hi:[1,0]
	v_pk_mul_f32 v[156:157], v[146:147], 0.5 op_sel_hi:[1,0]
	v_pk_mul_f32 v[150:151], v[144:145], 0.5 op_sel_hi:[1,0]
	v_pk_mul_f32 v[154:155], v[142:143], 0.5 op_sel_hi:[1,0]
	global_load_dwordx4 v[142:145], v[160:161], off offset:528
	global_load_dwordx4 v[146:149], v[160:161], off offset:512
	s_waitcnt vmcnt(0)
	v_pk_add_f32 v[144:145], v[144:145], 1.0 op_sel_hi:[1,0]
	v_pk_add_f32 v[148:149], v[148:149], 1.0 op_sel_hi:[1,0]
	v_pk_add_f32 v[160:161], v[146:147], 1.0 op_sel_hi:[1,0]
	v_pk_mul_f32 v[146:147], v[148:149], 0.5 op_sel_hi:[1,0]
	v_pk_mul_f32 v[148:149], v[160:161], 0.5 op_sel_hi:[1,0]
	v_pk_add_f32 v[160:161], v[142:143], 1.0 op_sel_hi:[1,0]
	v_pk_mul_f32 v[142:143], v[144:145], 0.5 op_sel_hi:[1,0]
	v_pk_mul_f32 v[144:145], v[160:161], 0.5 op_sel_hi:[1,0]
	v_lshlrev_b64 v[160:161], 12, v[162:163]
	v_lshl_add_u64 v[168:169], s[12:13], 0, v[160:161]
	v_lshlrev_b64 v[160:161], 1, v[158:159]
	v_lshl_add_u64 v[158:159], v[168:169], 0, v[160:161]
	v_mov_b32_e32 v168, v174
	v_mov_b32_e32 v169, v175
	v_mov_b32_e32 v170, v176
	v_mov_b32_e32 v171, v177
	s_nop 0
	v_lshlrev_b32_e32 v172, 16, v168
	v_and_b32_e32 v173, 0xffff0000, v168
	v_lshlrev_b32_e32 v168, 16, v169
	v_and_b32_e32 v169, 0xffff0000, v169
	v_pk_fma_f32 v[128:129], v[128:129], v[152:153], v[168:169]
	v_lshlrev_b32_e32 v168, 16, v170
	v_and_b32_e32 v169, 0xffff0000, v170
	v_pk_fma_f32 v[168:169], v[122:123], v[154:155], v[168:169]
	v_lshlrev_b32_e32 v122, 16, v171
	v_and_b32_e32 v123, 0xffff0000, v171
	v_pk_fma_f32 v[126:127], v[126:127], v[156:157], v[172:173]
	v_pk_fma_f32 v[170:171], v[124:125], v[150:151], v[122:123]
	v_cvt_pk_bf16_f32 v122, v126, v127
	v_cvt_pk_bf16_f32 v123, v128, v129
	v_cvt_pk_bf16_f32 v124, v168, v169
	v_cvt_pk_bf16_f32 v125, v170, v171
	global_store_dwordx4 v[158:159], v[122:125], off offset:2048
	s_nop 1
	v_mov_b32_e32 v122, v186
	v_mov_b32_e32 v123, v187
	v_mov_b32_e32 v124, v188
	v_mov_b32_e32 v125, v189
	s_nop 0
	v_lshlrev_b32_e32 v126, 16, v122
	v_and_b32_e32 v127, 0xffff0000, v122
	v_lshlrev_b32_e32 v122, 16, v123
	v_and_b32_e32 v123, 0xffff0000, v123
	v_pk_fma_f32 v[120:121], v[120:121], v[146:147], v[122:123]
	v_lshlrev_b32_e32 v122, 16, v124
	v_and_b32_e32 v123, 0xffff0000, v124
	v_pk_fma_f32 v[122:123], v[114:115], v[144:145], v[122:123]
	v_lshlrev_b32_e32 v114, 16, v125
	v_and_b32_e32 v115, 0xffff0000, v125
	v_pk_fma_f32 v[118:119], v[118:119], v[148:149], v[126:127]
	v_pk_fma_f32 v[124:125], v[116:117], v[142:143], v[114:115]
	v_cvt_pk_bf16_f32 v114, v118, v119
	v_cvt_pk_bf16_f32 v115, v120, v121
	v_cvt_pk_bf16_f32 v116, v122, v123
	v_cvt_pk_bf16_f32 v117, v124, v125
	global_store_dwordx4 v[158:159], v[114:117], off offset:2304
	s_nop 1
	v_or_b32_e32 v114, 16, v162
	v_ashrrev_i32_e32 v115, 31, v114
	v_lshlrev_b64 v[114:115], 12, v[114:115]
	v_lshl_add_u64 v[114:115], s[12:13], 0, v[114:115]
	v_lshl_add_u64 v[118:119], v[114:115], 0, v[160:161]
	v_mov_b32_e32 v114, v190
	v_mov_b32_e32 v115, v191
	v_mov_b32_e32 v116, v192
	v_mov_b32_e32 v117, v193
	s_nop 0
	v_lshlrev_b32_e32 v120, 16, v114
	v_and_b32_e32 v121, 0xffff0000, v114
	v_lshlrev_b32_e32 v114, 16, v115
	v_and_b32_e32 v115, 0xffff0000, v115
	v_pk_fma_f32 v[112:113], v[112:113], v[152:153], v[114:115]
	v_lshlrev_b32_e32 v114, 16, v116
	v_and_b32_e32 v115, 0xffff0000, v116
	v_pk_fma_f32 v[114:115], v[106:107], v[154:155], v[114:115]
	v_lshlrev_b32_e32 v106, 16, v117
	v_and_b32_e32 v107, 0xffff0000, v117
	v_pk_fma_f32 v[110:111], v[110:111], v[156:157], v[120:121]
	v_pk_fma_f32 v[116:117], v[108:109], v[150:151], v[106:107]
	v_cvt_pk_bf16_f32 v106, v110, v111
	v_cvt_pk_bf16_f32 v107, v112, v113
	v_cvt_pk_bf16_f32 v108, v114, v115
	v_cvt_pk_bf16_f32 v109, v116, v117
	global_store_dwordx4 v[118:119], v[106:109], off offset:2048
	s_nop 1
	v_mov_b32_e32 v106, v194
	v_mov_b32_e32 v107, v195
	v_mov_b32_e32 v108, v196
	v_mov_b32_e32 v109, v197
	s_nop 0
	v_lshlrev_b32_e32 v110, 16, v106
	v_and_b32_e32 v111, 0xffff0000, v106
	v_lshlrev_b32_e32 v106, 16, v107
	v_and_b32_e32 v107, 0xffff0000, v107
	v_pk_fma_f32 v[104:105], v[104:105], v[146:147], v[106:107]
	v_lshlrev_b32_e32 v106, 16, v108
	v_and_b32_e32 v107, 0xffff0000, v108
	v_pk_fma_f32 v[106:107], v[98:99], v[144:145], v[106:107]
	v_lshlrev_b32_e32 v98, 16, v109
	v_and_b32_e32 v99, 0xffff0000, v109
	v_pk_fma_f32 v[102:103], v[102:103], v[148:149], v[110:111]
	v_pk_fma_f32 v[108:109], v[100:101], v[142:143], v[98:99]
	v_cvt_pk_bf16_f32 v98, v102, v103
	v_cvt_pk_bf16_f32 v99, v104, v105
	v_cvt_pk_bf16_f32 v100, v106, v107
	v_cvt_pk_bf16_f32 v101, v108, v109
	global_store_dwordx4 v[118:119], v[98:101], off offset:2304
	s_nop 1
	v_or_b32_e32 v98, 32, v162
	v_ashrrev_i32_e32 v99, 31, v98
	v_lshlrev_b64 v[98:99], 12, v[98:99]
	v_lshl_add_u64 v[98:99], s[12:13], 0, v[98:99]
	v_lshl_add_u64 v[102:103], v[98:99], 0, v[160:161]
	v_mov_b32_e32 v98, v198
	v_mov_b32_e32 v99, v199
	v_mov_b32_e32 v100, v200
	v_mov_b32_e32 v101, v201
	s_nop 0
	v_lshlrev_b32_e32 v104, 16, v98
	v_and_b32_e32 v105, 0xffff0000, v98
	v_lshlrev_b32_e32 v98, 16, v99
	v_and_b32_e32 v99, 0xffff0000, v99
	v_pk_fma_f32 v[96:97], v[96:97], v[152:153], v[98:99]
	v_lshlrev_b32_e32 v98, 16, v100
	v_and_b32_e32 v99, 0xffff0000, v100
	v_pk_fma_f32 v[98:99], v[90:91], v[154:155], v[98:99]
	v_lshlrev_b32_e32 v90, 16, v101
	v_and_b32_e32 v91, 0xffff0000, v101
	v_pk_fma_f32 v[94:95], v[94:95], v[156:157], v[104:105]
	v_pk_fma_f32 v[100:101], v[92:93], v[150:151], v[90:91]
	v_cvt_pk_bf16_f32 v90, v94, v95
	v_cvt_pk_bf16_f32 v91, v96, v97
	v_cvt_pk_bf16_f32 v92, v98, v99
	v_cvt_pk_bf16_f32 v93, v100, v101
	global_store_dwordx4 v[102:103], v[90:93], off offset:2048
	s_nop 1
	v_mov_b32_e32 v90, v202
	v_mov_b32_e32 v91, v203
	v_mov_b32_e32 v92, v204
	v_mov_b32_e32 v93, v205
	s_nop 0
	v_lshlrev_b32_e32 v94, 16, v90
	v_and_b32_e32 v95, 0xffff0000, v90
	v_lshlrev_b32_e32 v90, 16, v91
	v_and_b32_e32 v91, 0xffff0000, v91
	v_pk_fma_f32 v[88:89], v[88:89], v[146:147], v[90:91]
	v_lshlrev_b32_e32 v90, 16, v92
	v_and_b32_e32 v91, 0xffff0000, v92
	v_pk_fma_f32 v[90:91], v[82:83], v[144:145], v[90:91]
	v_lshlrev_b32_e32 v82, 16, v93
	v_and_b32_e32 v83, 0xffff0000, v93
	v_pk_fma_f32 v[86:87], v[86:87], v[148:149], v[94:95]
	v_pk_fma_f32 v[92:93], v[84:85], v[142:143], v[82:83]
	v_cvt_pk_bf16_f32 v82, v86, v87
	v_cvt_pk_bf16_f32 v83, v88, v89
	v_cvt_pk_bf16_f32 v84, v90, v91
	v_cvt_pk_bf16_f32 v85, v92, v93
	global_store_dwordx4 v[102:103], v[82:85], off offset:2304
	s_nop 1
	v_or_b32_e32 v82, 48, v162
	v_ashrrev_i32_e32 v83, 31, v82
	v_lshlrev_b64 v[82:83], 12, v[82:83]
	v_lshl_add_u64 v[82:83], s[12:13], 0, v[82:83]
	v_lshl_add_u64 v[82:83], v[82:83], 0, v[160:161]
	v_mov_b32_e32 v84, v206
	v_mov_b32_e32 v85, v207
	v_mov_b32_e32 v86, v208
	v_mov_b32_e32 v87, v209
	s_nop 0
	v_lshlrev_b32_e32 v88, 16, v84
	v_and_b32_e32 v89, 0xffff0000, v84
	v_lshlrev_b32_e32 v84, 16, v85
	v_and_b32_e32 v85, 0xffff0000, v85
	v_pk_fma_f32 v[80:81], v[80:81], v[152:153], v[84:85]
	v_lshlrev_b32_e32 v84, 16, v86
	v_and_b32_e32 v85, 0xffff0000, v86
	v_pk_fma_f32 v[84:85], v[74:75], v[154:155], v[84:85]
	v_lshlrev_b32_e32 v74, 16, v87
	v_and_b32_e32 v75, 0xffff0000, v87
	v_pk_fma_f32 v[78:79], v[78:79], v[156:157], v[88:89]
	v_pk_fma_f32 v[86:87], v[76:77], v[150:151], v[74:75]
	v_cvt_pk_bf16_f32 v74, v78, v79
	v_cvt_pk_bf16_f32 v75, v80, v81
	v_cvt_pk_bf16_f32 v76, v84, v85
	v_cvt_pk_bf16_f32 v77, v86, v87
	global_store_dwordx4 v[82:83], v[74:77], off offset:2048
	s_nop 1
	v_mov_b32_e32 v74, v210
	v_mov_b32_e32 v75, v211
	v_mov_b32_e32 v76, v212
	v_mov_b32_e32 v77, v213
	s_nop 0
	v_lshlrev_b32_e32 v78, 16, v74
	v_and_b32_e32 v79, 0xffff0000, v74
	v_lshlrev_b32_e32 v74, 16, v75
	v_and_b32_e32 v75, 0xffff0000, v75
	v_pk_fma_f32 v[72:73], v[72:73], v[146:147], v[74:75]
	v_lshlrev_b32_e32 v74, 16, v76
	v_and_b32_e32 v75, 0xffff0000, v76
	v_pk_fma_f32 v[74:75], v[66:67], v[144:145], v[74:75]
	v_lshlrev_b32_e32 v66, 16, v77
	v_and_b32_e32 v67, 0xffff0000, v77
	v_pk_fma_f32 v[70:71], v[70:71], v[148:149], v[78:79]
	v_pk_fma_f32 v[76:77], v[68:69], v[142:143], v[66:67]
	v_cvt_pk_bf16_f32 v66, v70, v71
	v_cvt_pk_bf16_f32 v67, v72, v73
	v_cvt_pk_bf16_f32 v68, v74, v75
	v_cvt_pk_bf16_f32 v69, v76, v77
	v_lshl_add_u64 v[70:71], v[158:159], 0, s[14:15]
	global_store_dwordx4 v[82:83], v[66:69], off offset:2304
	s_nop 1
	v_mov_b32_e32 v66, v214
	v_mov_b32_e32 v67, v215
	v_mov_b32_e32 v68, v216
	v_mov_b32_e32 v69, v217
	s_mov_b64 s[14:15], 0x90000
	s_nop 0
	v_lshlrev_b32_e32 v72, 16, v66
	v_and_b32_e32 v73, 0xffff0000, v66
	v_lshlrev_b32_e32 v66, 16, v67
	v_and_b32_e32 v67, 0xffff0000, v67
	v_pk_fma_f32 v[64:65], v[64:65], v[152:153], v[66:67]
	v_lshlrev_b32_e32 v66, 16, v68
	v_and_b32_e32 v67, 0xffff0000, v68
	v_pk_fma_f32 v[66:67], v[58:59], v[154:155], v[66:67]
	v_lshlrev_b32_e32 v58, 16, v69
	v_and_b32_e32 v59, 0xffff0000, v69
	v_pk_fma_f32 v[62:63], v[62:63], v[156:157], v[72:73]
	v_pk_fma_f32 v[68:69], v[60:61], v[150:151], v[58:59]
	v_cvt_pk_bf16_f32 v58, v62, v63
	v_cvt_pk_bf16_f32 v59, v64, v65
	v_cvt_pk_bf16_f32 v60, v66, v67
	v_cvt_pk_bf16_f32 v61, v68, v69
	global_store_dwordx4 v[70:71], v[58:61], off offset:2048
	s_nop 1
	v_mov_b32_e32 v58, v218
	v_mov_b32_e32 v59, v219
	v_mov_b32_e32 v60, v220
	v_mov_b32_e32 v61, v221
	s_nop 0
	v_lshlrev_b32_e32 v62, 16, v58
	v_and_b32_e32 v63, 0xffff0000, v58
	v_lshlrev_b32_e32 v58, 16, v59
	v_and_b32_e32 v59, 0xffff0000, v59
	v_pk_fma_f32 v[56:57], v[56:57], v[146:147], v[58:59]
	v_lshlrev_b32_e32 v58, 16, v60
	v_and_b32_e32 v59, 0xffff0000, v60
	v_pk_fma_f32 v[58:59], v[50:51], v[144:145], v[58:59]
	v_lshlrev_b32_e32 v50, 16, v61
	v_and_b32_e32 v51, 0xffff0000, v61
	v_pk_fma_f32 v[54:55], v[54:55], v[148:149], v[62:63]
	v_pk_fma_f32 v[60:61], v[52:53], v[142:143], v[50:51]
	v_cvt_pk_bf16_f32 v50, v54, v55
	v_cvt_pk_bf16_f32 v51, v56, v57
	v_cvt_pk_bf16_f32 v52, v58, v59
	v_cvt_pk_bf16_f32 v53, v60, v61
	v_lshl_add_u64 v[54:55], v[158:159], 0, s[14:15]
	global_store_dwordx4 v[70:71], v[50:53], off offset:2304
	s_nop 1
	v_mov_b32_e32 v50, v222
	v_mov_b32_e32 v51, v223
	v_mov_b32_e32 v52, v224
	v_mov_b32_e32 v53, v225
	s_mov_b64 s[14:15], 0xa0000
	s_nop 0
	v_lshlrev_b32_e32 v56, 16, v50
	v_and_b32_e32 v57, 0xffff0000, v50
	v_lshlrev_b32_e32 v50, 16, v51
	v_and_b32_e32 v51, 0xffff0000, v51
	v_pk_fma_f32 v[48:49], v[48:49], v[152:153], v[50:51]
	v_lshlrev_b32_e32 v50, 16, v52
	v_and_b32_e32 v51, 0xffff0000, v52
	v_pk_fma_f32 v[50:51], v[42:43], v[154:155], v[50:51]
	v_lshlrev_b32_e32 v42, 16, v53
	v_and_b32_e32 v43, 0xffff0000, v53
	v_pk_fma_f32 v[46:47], v[46:47], v[156:157], v[56:57]
	v_pk_fma_f32 v[52:53], v[44:45], v[150:151], v[42:43]
	v_cvt_pk_bf16_f32 v42, v46, v47
	v_cvt_pk_bf16_f32 v43, v48, v49
	v_cvt_pk_bf16_f32 v44, v50, v51
	v_cvt_pk_bf16_f32 v45, v52, v53
	global_store_dwordx4 v[54:55], v[42:45], off offset:2048
	s_nop 1
	v_mov_b32_e32 v42, v226
	v_mov_b32_e32 v43, v227
	v_mov_b32_e32 v44, v228
	v_mov_b32_e32 v45, v229
	s_nop 0
	v_lshlrev_b32_e32 v46, 16, v42
	v_and_b32_e32 v47, 0xffff0000, v42
	v_lshlrev_b32_e32 v42, 16, v43
	v_and_b32_e32 v43, 0xffff0000, v43
	v_pk_fma_f32 v[40:41], v[40:41], v[146:147], v[42:43]
	v_lshlrev_b32_e32 v42, 16, v44
	v_and_b32_e32 v43, 0xffff0000, v44
	v_pk_fma_f32 v[42:43], v[34:35], v[144:145], v[42:43]
	v_lshlrev_b32_e32 v34, 16, v45
	v_and_b32_e32 v35, 0xffff0000, v45
	v_pk_fma_f32 v[38:39], v[38:39], v[148:149], v[46:47]
	v_pk_fma_f32 v[44:45], v[36:37], v[142:143], v[34:35]
	v_cvt_pk_bf16_f32 v34, v38, v39
	v_cvt_pk_bf16_f32 v35, v40, v41
	v_cvt_pk_bf16_f32 v36, v42, v43
	v_cvt_pk_bf16_f32 v37, v44, v45
	v_lshl_add_u64 v[38:39], v[158:159], 0, s[14:15]
	global_store_dwordx4 v[54:55], v[34:37], off offset:2304
	s_nop 1
	v_mov_b32_e32 v34, v230
	v_mov_b32_e32 v35, v231
	v_mov_b32_e32 v36, v232
	v_mov_b32_e32 v37, v233
	s_mov_b64 s[14:15], 0xb0000
	s_nop 0
	v_lshlrev_b32_e32 v40, 16, v34
	v_and_b32_e32 v41, 0xffff0000, v34
	v_lshlrev_b32_e32 v34, 16, v35
	v_and_b32_e32 v35, 0xffff0000, v35
	v_pk_fma_f32 v[32:33], v[32:33], v[152:153], v[34:35]
	v_lshlrev_b32_e32 v34, 16, v36
	v_and_b32_e32 v35, 0xffff0000, v36
	v_pk_fma_f32 v[34:35], v[26:27], v[154:155], v[34:35]
	v_lshlrev_b32_e32 v26, 16, v37
	v_and_b32_e32 v27, 0xffff0000, v37
	v_pk_fma_f32 v[30:31], v[30:31], v[156:157], v[40:41]
	v_pk_fma_f32 v[36:37], v[28:29], v[150:151], v[26:27]
	v_cvt_pk_bf16_f32 v26, v30, v31
	v_cvt_pk_bf16_f32 v27, v32, v33
	v_cvt_pk_bf16_f32 v28, v34, v35
	v_cvt_pk_bf16_f32 v29, v36, v37
	global_store_dwordx4 v[38:39], v[26:29], off offset:2048
	s_nop 1
	v_mov_b32_e32 v26, v236
	v_mov_b32_e32 v27, v237
	v_mov_b32_e32 v28, v238
	v_mov_b32_e32 v29, v239
	s_nop 0
	v_lshlrev_b32_e32 v30, 16, v26
	v_and_b32_e32 v31, 0xffff0000, v26
	v_lshlrev_b32_e32 v26, 16, v27
	v_and_b32_e32 v27, 0xffff0000, v27
	v_pk_fma_f32 v[24:25], v[24:25], v[146:147], v[26:27]
	v_lshlrev_b32_e32 v26, 16, v28
	v_and_b32_e32 v27, 0xffff0000, v28
	v_pk_fma_f32 v[26:27], v[18:19], v[144:145], v[26:27]
	v_lshlrev_b32_e32 v18, 16, v29
	v_and_b32_e32 v19, 0xffff0000, v29
	v_pk_fma_f32 v[22:23], v[22:23], v[148:149], v[30:31]
	v_pk_fma_f32 v[28:29], v[20:21], v[142:143], v[18:19]
	v_cvt_pk_bf16_f32 v18, v22, v23
	v_cvt_pk_bf16_f32 v19, v24, v25
	v_cvt_pk_bf16_f32 v20, v26, v27
	v_cvt_pk_bf16_f32 v21, v28, v29
	global_store_dwordx4 v[38:39], v[18:21], off offset:2304
	s_nop 1
	v_lshl_add_u64 v[18:19], v[158:159], 0, s[14:15]
	v_mov_b32_e32 v20, v246
	v_mov_b32_e32 v21, v247
	v_mov_b32_e32 v22, v248
	v_mov_b32_e32 v23, v249
	s_mov_b64 s[14:15], s[6:7]
	s_nop 0
	v_lshlrev_b32_e32 v24, 16, v20
	v_and_b32_e32 v25, 0xffff0000, v20
	v_lshlrev_b32_e32 v20, 16, v21
	v_and_b32_e32 v21, 0xffff0000, v21
	v_pk_fma_f32 v[16:17], v[16:17], v[152:153], v[20:21]
	v_lshlrev_b32_e32 v20, 16, v22
	v_and_b32_e32 v21, 0xffff0000, v22
	v_pk_fma_f32 v[20:21], v[10:11], v[154:155], v[20:21]
	v_lshlrev_b32_e32 v10, 16, v23
	v_and_b32_e32 v11, 0xffff0000, v23
	v_pk_fma_f32 v[14:15], v[14:15], v[156:157], v[24:25]
	v_pk_fma_f32 v[22:23], v[12:13], v[150:151], v[10:11]
	v_cvt_pk_bf16_f32 v10, v14, v15
	v_cvt_pk_bf16_f32 v11, v16, v17
	v_cvt_pk_bf16_f32 v12, v20, v21
	v_cvt_pk_bf16_f32 v13, v22, v23
	global_store_dwordx4 v[18:19], v[10:13], off offset:2048
	s_nop 1
	v_mov_b32_e32 v10, v250
	v_mov_b32_e32 v11, v251
	v_mov_b32_e32 v12, v252
	v_mov_b32_e32 v13, v253
	s_nop 0
	v_lshlrev_b32_e32 v14, 16, v10
	v_and_b32_e32 v15, 0xffff0000, v10
	v_lshlrev_b32_e32 v10, 16, v11
	v_and_b32_e32 v11, 0xffff0000, v11
	v_pk_fma_f32 v[8:9], v[8:9], v[146:147], v[10:11]
	v_lshlrev_b32_e32 v10, 16, v12
	v_and_b32_e32 v11, 0xffff0000, v12
	v_pk_fma_f32 v[10:11], v[2:3], v[144:145], v[10:11]
	v_lshlrev_b32_e32 v2, 16, v13
	v_and_b32_e32 v3, 0xffff0000, v13
	v_pk_fma_f32 v[6:7], v[6:7], v[148:149], v[14:15]
	v_pk_fma_f32 v[12:13], v[4:5], v[142:143], v[2:3]
	v_cvt_pk_bf16_f32 v2, v6, v7
	v_cvt_pk_bf16_f32 v3, v8, v9
	v_cvt_pk_bf16_f32 v4, v10, v11
	v_cvt_pk_bf16_f32 v5, v12, v13
	global_store_dwordx4 v[18:19], v[2:5], off offset:2304
	s_cbranch_vccz .LBB0_363
	s_waitcnt vmcnt(0)
	s_cmpk_gt_u32 s30, 0xff
	s_cbranch_scc1 .LBB0_378
	s_barrier

.LBB0_399:
	s_add_u32 s46, s16, 0x100
	s_addc_u32 s47, s17, 0
	s_mov_b32 s48, -2
	s_add_u32 s16, s14, 0x100
	s_addc_u32 s17, s15, 0
	s_add_i32 s49, 0, 0x10000
	v_add_u32_e32 v154, s49, v164
	ds_read_b128 v[142:145], v154
	ds_read_b128 v[146:149], v154 offset:1024
	ds_read_b128 v[150:153], v154 offset:2048
	ds_read_b128 v[154:157], v154 offset:3072
	s_cmp_eq_u32 s48, 40
	s_cselect_b32 s21, s7, s17
	s_cselect_b32 s20, s6, s16
	s_cselect_b32 s19, s9, s47
	s_cselect_b32 s18, s8, s46
	v_lshl_add_u64 v[162:163], s[14:15], 0, v[138:139]
	s_add_i32 m0, s34, 0xc000
	ds_read_b128 v[158:161], v166
	ds_read_b128 v[168:171], v166 offset:1024
	ds_read_b128 v[172:175], v166 offset:2048
	ds_read_b128 v[190:193], v166 offset:3072
	ds_read_b128 v[194:197], v166 offset:4096
	ds_read_b128 v[198:201], v166 offset:5120
	ds_read_b128 v[202:205], v166 offset:6144
	ds_read_b128 v[206:209], v166 offset:7168
	global_load_lds_dwordx4 v[162:163], off
	v_lshl_add_u64 v[162:163], s[14:15], 0, v[140:141]
	s_add_i32 m0, s34, 0xe000
	s_nop 0
	global_load_lds_dwordx4 v[162:163], off
	s_waitcnt lgkmcnt(8)
	s_barrier
	s_waitcnt lgkmcnt(0)
	s_waitcnt lgkmcnt(0)
	v_mfma_f32_16x16x32_bf16 v[126:129], v[142:145], v[158:161], 0
	v_mfma_f32_16x16x32_bf16 v[122:125], v[150:153], v[158:161], 0
	v_mfma_f32_16x16x32_bf16 v[110:113], v[142:145], v[172:175], 0
	v_mfma_f32_16x16x32_bf16 v[106:109], v[150:153], v[172:175], 0
	v_mfma_f32_16x16x32_bf16 v[94:97], v[142:145], v[194:197], 0
	v_mfma_f32_16x16x32_bf16 v[90:93], v[150:153], v[194:197], 0
	v_mfma_f32_16x16x32_bf16 v[78:81], v[142:145], v[202:205], 0
	v_mfma_f32_16x16x32_bf16 v[74:77], v[150:153], v[202:205], 0
	v_mfma_f32_16x16x32_bf16 v[126:129], v[146:149], v[168:171], v[126:129]
	v_mfma_f32_16x16x32_bf16 v[122:125], v[154:157], v[168:171], v[122:125]
	v_mfma_f32_16x16x32_bf16 v[110:113], v[146:149], v[190:193], v[110:113]
	v_mfma_f32_16x16x32_bf16 v[106:109], v[154:157], v[190:193], v[106:109]
	v_mfma_f32_16x16x32_bf16 v[94:97], v[146:149], v[198:201], v[94:97]
	v_mfma_f32_16x16x32_bf16 v[90:93], v[154:157], v[198:201], v[90:93]
	v_mfma_f32_16x16x32_bf16 v[78:81], v[146:149], v[206:209], v[78:81]
	v_mfma_f32_16x16x32_bf16 v[74:77], v[154:157], v[206:209], v[74:77]
	s_barrier
	s_add_i32 s50, 0, 0x14000
	v_add_u32_e32 v162, s50, v164
	s_add_i32 s14, s49, s33
	ds_read_b128 v[210:213], v162
	ds_read_b128 v[214:217], v162 offset:1024
	ds_read_b128 v[218:221], v162 offset:2048
	ds_read_b128 v[222:225], v162 offset:3072
	s_add_u32 s64, s18, 0x80
	s_addc_u32 s65, s19, 0
	s_mov_b32 m0, s14
	s_nop 0
	global_load_lds_dwordx4 v132, s[18:19]
	s_add_i32 m0, s14, 0x2000
	s_nop 0
	global_load_lds_dwordx4 v136, s[18:19]
	s_barrier
	s_waitcnt lgkmcnt(0)
	s_waitcnt lgkmcnt(0)
	v_mfma_f32_16x16x32_bf16 v[118:121], v[210:213], v[158:161], 0
	v_mfma_f32_16x16x32_bf16 v[114:117], v[218:221], v[158:161], 0
	v_mfma_f32_16x16x32_bf16 v[102:105], v[210:213], v[172:175], 0
	v_mfma_f32_16x16x32_bf16 v[98:101], v[218:221], v[172:175], 0
	v_mfma_f32_16x16x32_bf16 v[86:89], v[210:213], v[194:197], 0
	v_mfma_f32_16x16x32_bf16 v[82:85], v[218:221], v[194:197], 0
	v_mfma_f32_16x16x32_bf16 v[70:73], v[210:213], v[202:205], 0
	v_mfma_f32_16x16x32_bf16 v[66:69], v[218:221], v[202:205], 0
	v_mfma_f32_16x16x32_bf16 v[118:121], v[214:217], v[168:171], v[118:121]
	v_mfma_f32_16x16x32_bf16 v[114:117], v[222:225], v[168:171], v[114:117]
	v_mfma_f32_16x16x32_bf16 v[102:105], v[214:217], v[190:193], v[102:105]
	v_mfma_f32_16x16x32_bf16 v[98:101], v[222:225], v[190:193], v[98:101]
	v_mfma_f32_16x16x32_bf16 v[86:89], v[214:217], v[198:201], v[86:89]
	v_mfma_f32_16x16x32_bf16 v[82:85], v[222:225], v[198:201], v[82:85]
	v_mfma_f32_16x16x32_bf16 v[70:73], v[214:217], v[206:209], v[70:73]
	v_mfma_f32_16x16x32_bf16 v[66:69], v[222:225], v[206:209], v[66:69]
	s_barrier
	s_mov_b32 m0, s34
	s_add_u32 s62, s20, 0x80
	s_addc_u32 s63, s21, 0
	ds_read_b128 v[158:161], v166 offset:16384
	ds_read_b128 v[168:171], v166 offset:17408
	ds_read_b128 v[172:175], v166 offset:18432
	ds_read_b128 v[190:193], v166 offset:19456
	ds_read_b128 v[194:197], v166 offset:20480
	ds_read_b128 v[198:201], v166 offset:21504
	ds_read_b128 v[202:205], v166 offset:22528
	ds_read_b128 v[206:209], v166 offset:23552
	global_load_lds_dwordx4 v130, s[20:21]
	s_mov_b32 m0, s35
	s_nop 0
	global_load_lds_dwordx4 v134, s[20:21]
	s_waitcnt vmcnt(10)
	s_barrier
	s_waitcnt lgkmcnt(0)
	s_waitcnt lgkmcnt(0)
	v_mfma_f32_16x16x32_bf16 v[62:65], v[142:145], v[158:161], 0
	v_mfma_f32_16x16x32_bf16 v[58:61], v[150:153], v[158:161], 0
	v_mfma_f32_16x16x32_bf16 v[46:49], v[142:145], v[172:175], 0
	v_mfma_f32_16x16x32_bf16 v[42:45], v[150:153], v[172:175], 0
	v_mfma_f32_16x16x32_bf16 v[30:33], v[142:145], v[194:197], 0
	v_mfma_f32_16x16x32_bf16 v[26:29], v[150:153], v[194:197], 0
	v_mfma_f32_16x16x32_bf16 v[14:17], v[142:145], v[202:205], 0
	v_mfma_f32_16x16x32_bf16 v[10:13], v[150:153], v[202:205], 0
	v_mfma_f32_16x16x32_bf16 v[62:65], v[146:149], v[168:171], v[62:65]
	v_mfma_f32_16x16x32_bf16 v[58:61], v[154:157], v[168:171], v[58:61]
	v_mfma_f32_16x16x32_bf16 v[46:49], v[146:149], v[190:193], v[46:49]
	v_mfma_f32_16x16x32_bf16 v[42:45], v[154:157], v[190:193], v[42:45]
	v_mfma_f32_16x16x32_bf16 v[30:33], v[146:149], v[198:201], v[30:33]
	v_mfma_f32_16x16x32_bf16 v[26:29], v[154:157], v[198:201], v[26:29]
	v_mfma_f32_16x16x32_bf16 v[14:17], v[146:149], v[206:209], v[14:17]
	v_mfma_f32_16x16x32_bf16 v[10:13], v[154:157], v[206:209], v[10:13]
	s_barrier
	v_add_u32_e32 v154, 0x18000, v164
	ds_read_b128 v[142:145], v154
	ds_read_b128 v[146:149], v154 offset:1024
	ds_read_b128 v[150:153], v154 offset:2048
	ds_read_b128 v[154:157], v154 offset:3072
	s_add_u32 s14, s18, 0xb0000
	s_addc_u32 s15, s19, 0
	s_add_i32 s49, s50, s33
	s_mov_b32 m0, s49
	s_nop 0
	global_load_lds_dwordx4 v132, s[14:15]
	s_add_i32 m0, s49, 0x2000
	s_nop 0
	global_load_lds_dwordx4 v136, s[14:15]
	s_waitcnt vmcnt(6)
	s_barrier
	v_mfma_f32_16x16x32_bf16 v[54:57], v[210:213], v[158:161], 0
	v_mfma_f32_16x16x32_bf16 v[50:53], v[218:221], v[158:161], 0
	v_mfma_f32_16x16x32_bf16 v[38:41], v[210:213], v[172:175], 0
	v_mfma_f32_16x16x32_bf16 v[34:37], v[218:221], v[172:175], 0
	v_mfma_f32_16x16x32_bf16 v[22:25], v[210:213], v[194:197], 0
	v_mfma_f32_16x16x32_bf16 v[18:21], v[218:221], v[194:197], 0
	v_mfma_f32_16x16x32_bf16 v[6:9], v[210:213], v[202:205], 0
	v_mfma_f32_16x16x32_bf16 v[2:5], v[218:221], v[202:205], 0
	v_mfma_f32_16x16x32_bf16 v[54:57], v[214:217], v[168:171], v[54:57]
	v_mfma_f32_16x16x32_bf16 v[50:53], v[222:225], v[168:171], v[50:53]
	v_mfma_f32_16x16x32_bf16 v[38:41], v[214:217], v[190:193], v[38:41]
	v_mfma_f32_16x16x32_bf16 v[34:37], v[222:225], v[190:193], v[34:37]
	v_mfma_f32_16x16x32_bf16 v[22:25], v[214:217], v[198:201], v[22:25]
	v_mfma_f32_16x16x32_bf16 v[18:21], v[222:225], v[198:201], v[18:21]
	v_mfma_f32_16x16x32_bf16 v[6:9], v[214:217], v[206:209], v[6:9]
	v_mfma_f32_16x16x32_bf16 v[2:5], v[222:225], v[206:209], v[2:5]
	s_barrier
	s_add_i32 s49, 0, 0x18000
	s_add_u32 s14, s20, 0xb8000
	s_addc_u32 s15, s21, 0
	s_mov_b32 m0, s36
	ds_read_b128 v[158:161], v166 offset:32768
	ds_read_b128 v[168:171], v166 offset:33792
	ds_read_b128 v[172:175], v166 offset:34816
	ds_read_b128 v[190:193], v166 offset:35840
	ds_read_b128 v[194:197], v166 offset:36864
	ds_read_b128 v[198:201], v166 offset:37888
	ds_read_b128 v[202:205], v166 offset:38912
	ds_read_b128 v[206:209], v166 offset:39936
	global_load_lds_dwordx4 v130, s[14:15]
	s_mov_b32 m0, s37
	s_nop 0
	global_load_lds_dwordx4 v134, s[14:15]
	s_waitcnt lgkmcnt(8)
	s_barrier
	s_waitcnt lgkmcnt(0)
	s_waitcnt lgkmcnt(0)
	v_mfma_f32_16x16x32_bf16 v[126:129], v[142:145], v[158:161], v[126:129]
	v_mfma_f32_16x16x32_bf16 v[122:125], v[150:153], v[158:161], v[122:125]
	v_mfma_f32_16x16x32_bf16 v[110:113], v[142:145], v[172:175], v[110:113]
	v_mfma_f32_16x16x32_bf16 v[106:109], v[150:153], v[172:175], v[106:109]
	v_mfma_f32_16x16x32_bf16 v[94:97], v[142:145], v[194:197], v[94:97]
	v_mfma_f32_16x16x32_bf16 v[90:93], v[150:153], v[194:197], v[90:93]
	v_mfma_f32_16x16x32_bf16 v[78:81], v[142:145], v[202:205], v[78:81]
	v_mfma_f32_16x16x32_bf16 v[74:77], v[150:153], v[202:205], v[74:77]
	v_mfma_f32_16x16x32_bf16 v[126:129], v[146:149], v[168:171], v[126:129]
	v_mfma_f32_16x16x32_bf16 v[122:125], v[154:157], v[168:171], v[122:125]
	v_mfma_f32_16x16x32_bf16 v[110:113], v[146:149], v[190:193], v[110:113]
	v_mfma_f32_16x16x32_bf16 v[106:109], v[154:157], v[190:193], v[106:109]
	v_mfma_f32_16x16x32_bf16 v[94:97], v[146:149], v[198:201], v[94:97]
	v_mfma_f32_16x16x32_bf16 v[90:93], v[154:157], v[198:201], v[90:93]
	v_mfma_f32_16x16x32_bf16 v[78:81], v[146:149], v[206:209], v[78:81]
	v_mfma_f32_16x16x32_bf16 v[74:77], v[154:157], v[206:209], v[74:77]
	s_barrier
	s_add_i32 s20, 0, 0x1c000
	s_add_i32 s14, s49, s33
	v_add_u32_e32 v167, s20, v164
	s_mov_b32 m0, s14
	ds_read_b128 v[210:213], v167
	ds_read_b128 v[214:217], v167 offset:1024
	ds_read_b128 v[218:221], v167 offset:2048
	ds_read_b128 v[222:225], v167 offset:3072
	global_load_lds_dwordx4 v132, s[64:65]
	s_add_i32 m0, s14, 0x2000
	s_nop 0
	global_load_lds_dwordx4 v136, s[64:65]
	s_barrier
	s_waitcnt lgkmcnt(0)
	s_waitcnt lgkmcnt(0)
	v_mfma_f32_16x16x32_bf16 v[118:121], v[210:213], v[158:161], v[118:121]
	v_mfma_f32_16x16x32_bf16 v[114:117], v[218:221], v[158:161], v[114:117]
	v_mfma_f32_16x16x32_bf16 v[102:105], v[210:213], v[172:175], v[102:105]
	v_mfma_f32_16x16x32_bf16 v[98:101], v[218:221], v[172:175], v[98:101]
	v_mfma_f32_16x16x32_bf16 v[86:89], v[210:213], v[194:197], v[86:89]
	v_mfma_f32_16x16x32_bf16 v[82:85], v[218:221], v[194:197], v[82:85]
	v_mfma_f32_16x16x32_bf16 v[70:73], v[210:213], v[202:205], v[70:73]
	v_mfma_f32_16x16x32_bf16 v[66:69], v[218:221], v[202:205], v[66:69]
	v_mfma_f32_16x16x32_bf16 v[118:121], v[214:217], v[168:171], v[118:121]
	v_mfma_f32_16x16x32_bf16 v[114:117], v[222:225], v[168:171], v[114:117]
	v_mfma_f32_16x16x32_bf16 v[102:105], v[214:217], v[190:193], v[102:105]
	v_mfma_f32_16x16x32_bf16 v[98:101], v[222:225], v[190:193], v[98:101]
	v_mfma_f32_16x16x32_bf16 v[86:89], v[214:217], v[198:201], v[86:89]
	v_mfma_f32_16x16x32_bf16 v[82:85], v[222:225], v[198:201], v[82:85]
	v_mfma_f32_16x16x32_bf16 v[70:73], v[214:217], v[206:209], v[70:73]
	v_mfma_f32_16x16x32_bf16 v[66:69], v[222:225], v[206:209], v[66:69]
	s_barrier
	s_mov_b32 m0, s38
	ds_read_b128 v[158:161], v166 offset:49152
	ds_read_b128 v[168:171], v166 offset:50176
	ds_read_b128 v[172:175], v166 offset:51200
	ds_read_b128 v[190:193], v166 offset:52224
	ds_read_b128 v[194:197], v166 offset:53248
	ds_read_b128 v[198:201], v166 offset:54272
	ds_read_b128 v[202:205], v166 offset:55296
	ds_read_b128 v[206:209], v166 offset:56320
	global_load_lds_dwordx4 v130, s[62:63]
	s_mov_b32 m0, s39
	s_nop 0
	global_load_lds_dwordx4 v134, s[62:63]
	s_waitcnt vmcnt(10)
	s_barrier
	s_waitcnt lgkmcnt(0)
	s_waitcnt lgkmcnt(0)
	v_mfma_f32_16x16x32_bf16 v[62:65], v[142:145], v[158:161], v[62:65]
	v_mfma_f32_16x16x32_bf16 v[58:61], v[150:153], v[158:161], v[58:61]
	v_mfma_f32_16x16x32_bf16 v[46:49], v[142:145], v[172:175], v[46:49]
	v_mfma_f32_16x16x32_bf16 v[42:45], v[150:153], v[172:175], v[42:45]
	v_mfma_f32_16x16x32_bf16 v[30:33], v[142:145], v[194:197], v[30:33]
	v_mfma_f32_16x16x32_bf16 v[26:29], v[150:153], v[194:197], v[26:29]
	v_mfma_f32_16x16x32_bf16 v[14:17], v[142:145], v[202:205], v[14:17]
	v_mfma_f32_16x16x32_bf16 v[10:13], v[150:153], v[202:205], v[10:13]
	v_mfma_f32_16x16x32_bf16 v[62:65], v[146:149], v[168:171], v[62:65]
	v_mfma_f32_16x16x32_bf16 v[58:61], v[154:157], v[168:171], v[58:61]
	v_mfma_f32_16x16x32_bf16 v[46:49], v[146:149], v[190:193], v[46:49]
	v_mfma_f32_16x16x32_bf16 v[42:45], v[154:157], v[190:193], v[42:45]
	v_mfma_f32_16x16x32_bf16 v[30:33], v[146:149], v[198:201], v[30:33]
	v_mfma_f32_16x16x32_bf16 v[26:29], v[154:157], v[198:201], v[26:29]
	v_mfma_f32_16x16x32_bf16 v[14:17], v[146:149], v[206:209], v[14:17]
	v_mfma_f32_16x16x32_bf16 v[10:13], v[154:157], v[206:209], v[10:13]
	s_barrier
	v_add_u32_e32 v154, 0x10000, v164
	ds_read_b128 v[142:145], v154
	ds_read_b128 v[146:149], v154 offset:1024
	ds_read_b128 v[150:153], v154 offset:2048
	ds_read_b128 v[154:157], v154 offset:3072
	s_add_u32 s14, s18, 0xb0080
	s_addc_u32 s15, s19, 0
	s_add_i32 s18, s20, s33
	s_mov_b32 m0, s18
	s_nop 0
	global_load_lds_dwordx4 v132, s[14:15]
	s_add_i32 m0, s18, 0x2000
	s_nop 0
	global_load_lds_dwordx4 v136, s[14:15]
	s_waitcnt vmcnt(6)
	s_barrier
	v_mfma_f32_16x16x32_bf16 v[54:57], v[210:213], v[158:161], v[54:57]
	v_mfma_f32_16x16x32_bf16 v[50:53], v[218:221], v[158:161], v[50:53]
	v_mfma_f32_16x16x32_bf16 v[38:41], v[210:213], v[172:175], v[38:41]
	v_mfma_f32_16x16x32_bf16 v[34:37], v[218:221], v[172:175], v[34:37]
	v_mfma_f32_16x16x32_bf16 v[22:25], v[210:213], v[194:197], v[22:25]
	v_mfma_f32_16x16x32_bf16 v[18:21], v[218:221], v[194:197], v[18:21]
	v_mfma_f32_16x16x32_bf16 v[6:9], v[210:213], v[202:205], v[6:9]
	v_mfma_f32_16x16x32_bf16 v[2:5], v[218:221], v[202:205], v[2:5]
	v_mfma_f32_16x16x32_bf16 v[54:57], v[214:217], v[168:171], v[54:57]
	v_mfma_f32_16x16x32_bf16 v[50:53], v[222:225], v[168:171], v[50:53]
	v_mfma_f32_16x16x32_bf16 v[38:41], v[214:217], v[190:193], v[38:41]
	v_mfma_f32_16x16x32_bf16 v[34:37], v[222:225], v[190:193], v[34:37]
	v_mfma_f32_16x16x32_bf16 v[22:25], v[214:217], v[198:201], v[22:25]
	v_mfma_f32_16x16x32_bf16 v[18:21], v[222:225], v[198:201], v[18:21]
	v_mfma_f32_16x16x32_bf16 v[6:9], v[214:217], v[206:209], v[6:9]
	v_mfma_f32_16x16x32_bf16 v[2:5], v[222:225], v[206:209], v[2:5]
	s_barrier
	s_add_i32 s48, s48, 2
	s_add_u32 s46, s46, 0x100
	s_addc_u32 s47, s47, 0
	s_mov_b64 s[14:15], s[16:17]
.LBB0_400:
	s_add_u32 s16, s14, 0x100
	s_addc_u32 s17, s15, 0
	s_add_i32 s49, 0, 0x10000
	s_cmp_eq_u32 s48, 40
	s_cselect_b32 s21, s7, s17
	s_cselect_b32 s20, s6, s16
	s_cselect_b32 s19, s9, s47
	s_cselect_b32 s18, s8, s46
	v_lshl_add_u64 v[162:163], s[14:15], 0, v[138:139]
	s_add_i32 m0, s34, 0xc000
	ds_read_b128 v[158:161], v166
	ds_read_b128 v[168:171], v166 offset:1024
	ds_read_b128 v[172:175], v166 offset:2048
	ds_read_b128 v[190:193], v166 offset:3072
	ds_read_b128 v[194:197], v166 offset:4096
	ds_read_b128 v[198:201], v166 offset:5120
	ds_read_b128 v[202:205], v166 offset:6144
	ds_read_b128 v[206:209], v166 offset:7168
	global_load_lds_dwordx4 v[162:163], off
	v_lshl_add_u64 v[162:163], s[14:15], 0, v[140:141]
	s_add_i32 m0, s34, 0xe000
	s_nop 0
	global_load_lds_dwordx4 v[162:163], off
	s_waitcnt lgkmcnt(8)
	s_barrier
	s_waitcnt lgkmcnt(0)
	s_waitcnt lgkmcnt(0)
	v_mfma_f32_16x16x32_bf16 v[126:129], v[142:145], v[158:161], v[126:129]
	v_mfma_f32_16x16x32_bf16 v[122:125], v[150:153], v[158:161], v[122:125]
	v_mfma_f32_16x16x32_bf16 v[110:113], v[142:145], v[172:175], v[110:113]
	v_mfma_f32_16x16x32_bf16 v[106:109], v[150:153], v[172:175], v[106:109]
	v_mfma_f32_16x16x32_bf16 v[94:97], v[142:145], v[194:197], v[94:97]
	v_mfma_f32_16x16x32_bf16 v[90:93], v[150:153], v[194:197], v[90:93]
	v_mfma_f32_16x16x32_bf16 v[78:81], v[142:145], v[202:205], v[78:81]
	v_mfma_f32_16x16x32_bf16 v[74:77], v[150:153], v[202:205], v[74:77]
	v_mfma_f32_16x16x32_bf16 v[126:129], v[146:149], v[168:171], v[126:129]
	v_mfma_f32_16x16x32_bf16 v[122:125], v[154:157], v[168:171], v[122:125]
	v_mfma_f32_16x16x32_bf16 v[110:113], v[146:149], v[190:193], v[110:113]
	v_mfma_f32_16x16x32_bf16 v[106:109], v[154:157], v[190:193], v[106:109]
	v_mfma_f32_16x16x32_bf16 v[94:97], v[146:149], v[198:201], v[94:97]
	v_mfma_f32_16x16x32_bf16 v[90:93], v[154:157], v[198:201], v[90:93]
	v_mfma_f32_16x16x32_bf16 v[78:81], v[146:149], v[206:209], v[78:81]
	v_mfma_f32_16x16x32_bf16 v[74:77], v[154:157], v[206:209], v[74:77]
	s_barrier
	s_add_i32 s50, 0, 0x14000
	v_add_u32_e32 v162, s50, v164
	s_add_i32 s14, s49, s33
	ds_read_b128 v[210:213], v162
	ds_read_b128 v[214:217], v162 offset:1024
	ds_read_b128 v[218:221], v162 offset:2048
	ds_read_b128 v[222:225], v162 offset:3072
	s_add_u32 s64, s18, 0x80
	s_addc_u32 s65, s19, 0
	s_mov_b32 m0, s14
	s_nop 0
	global_load_lds_dwordx4 v132, s[18:19]
	s_add_i32 m0, s14, 0x2000
	s_nop 0
	global_load_lds_dwordx4 v136, s[18:19]
	s_barrier
	s_waitcnt lgkmcnt(0)
	s_waitcnt lgkmcnt(0)
	v_mfma_f32_16x16x32_bf16 v[118:121], v[210:213], v[158:161], v[118:121]
	v_mfma_f32_16x16x32_bf16 v[114:117], v[218:221], v[158:161], v[114:117]
	v_mfma_f32_16x16x32_bf16 v[102:105], v[210:213], v[172:175], v[102:105]
	v_mfma_f32_16x16x32_bf16 v[98:101], v[218:221], v[172:175], v[98:101]
	v_mfma_f32_16x16x32_bf16 v[86:89], v[210:213], v[194:197], v[86:89]
	v_mfma_f32_16x16x32_bf16 v[82:85], v[218:221], v[194:197], v[82:85]
	v_mfma_f32_16x16x32_bf16 v[70:73], v[210:213], v[202:205], v[70:73]
	v_mfma_f32_16x16x32_bf16 v[66:69], v[218:221], v[202:205], v[66:69]
	v_mfma_f32_16x16x32_bf16 v[118:121], v[214:217], v[168:171], v[118:121]
	v_mfma_f32_16x16x32_bf16 v[114:117], v[222:225], v[168:171], v[114:117]
	v_mfma_f32_16x16x32_bf16 v[102:105], v[214:217], v[190:193], v[102:105]
	v_mfma_f32_16x16x32_bf16 v[98:101], v[222:225], v[190:193], v[98:101]
	v_mfma_f32_16x16x32_bf16 v[86:89], v[214:217], v[198:201], v[86:89]
	v_mfma_f32_16x16x32_bf16 v[82:85], v[222:225], v[198:201], v[82:85]
	v_mfma_f32_16x16x32_bf16 v[70:73], v[214:217], v[206:209], v[70:73]
	v_mfma_f32_16x16x32_bf16 v[66:69], v[222:225], v[206:209], v[66:69]
	s_barrier
	s_mov_b32 m0, s34
	s_add_u32 s62, s20, 0x80
	s_addc_u32 s63, s21, 0
	ds_read_b128 v[158:161], v166 offset:16384
	ds_read_b128 v[168:171], v166 offset:17408
	ds_read_b128 v[172:175], v166 offset:18432
	ds_read_b128 v[190:193], v166 offset:19456
	ds_read_b128 v[194:197], v166 offset:20480
	ds_read_b128 v[198:201], v166 offset:21504
	ds_read_b128 v[202:205], v166 offset:22528
	ds_read_b128 v[206:209], v166 offset:23552
	global_load_lds_dwordx4 v130, s[20:21]
	s_mov_b32 m0, s35
	s_nop 0
	global_load_lds_dwordx4 v134, s[20:21]
	s_waitcnt vmcnt(10)
	s_barrier
	s_waitcnt lgkmcnt(0)
	s_waitcnt lgkmcnt(0)
	v_mfma_f32_16x16x32_bf16 v[62:65], v[142:145], v[158:161], v[62:65]
	v_mfma_f32_16x16x32_bf16 v[58:61], v[150:153], v[158:161], v[58:61]
	v_mfma_f32_16x16x32_bf16 v[46:49], v[142:145], v[172:175], v[46:49]
	v_mfma_f32_16x16x32_bf16 v[42:45], v[150:153], v[172:175], v[42:45]
	v_mfma_f32_16x16x32_bf16 v[30:33], v[142:145], v[194:197], v[30:33]
	v_mfma_f32_16x16x32_bf16 v[26:29], v[150:153], v[194:197], v[26:29]
	v_mfma_f32_16x16x32_bf16 v[14:17], v[142:145], v[202:205], v[14:17]
	v_mfma_f32_16x16x32_bf16 v[10:13], v[150:153], v[202:205], v[10:13]
	v_mfma_f32_16x16x32_bf16 v[62:65], v[146:149], v[168:171], v[62:65]
	v_mfma_f32_16x16x32_bf16 v[58:61], v[154:157], v[168:171], v[58:61]
	v_mfma_f32_16x16x32_bf16 v[46:49], v[146:149], v[190:193], v[46:49]
	v_mfma_f32_16x16x32_bf16 v[42:45], v[154:157], v[190:193], v[42:45]
	v_mfma_f32_16x16x32_bf16 v[30:33], v[146:149], v[198:201], v[30:33]
	v_mfma_f32_16x16x32_bf16 v[26:29], v[154:157], v[198:201], v[26:29]
	v_mfma_f32_16x16x32_bf16 v[14:17], v[146:149], v[206:209], v[14:17]
	v_mfma_f32_16x16x32_bf16 v[10:13], v[154:157], v[206:209], v[10:13]
	s_barrier
	v_add_u32_e32 v154, 0x18000, v164
	ds_read_b128 v[142:145], v154
	ds_read_b128 v[146:149], v154 offset:1024
	ds_read_b128 v[150:153], v154 offset:2048
	ds_read_b128 v[154:157], v154 offset:3072
	s_add_u32 s14, s18, 0xb0000
	s_addc_u32 s15, s19, 0
	s_add_i32 s49, s50, s33
	s_mov_b32 m0, s49
	s_nop 0
	global_load_lds_dwordx4 v132, s[14:15]
	s_add_i32 m0, s49, 0x2000
	s_nop 0
	global_load_lds_dwordx4 v136, s[14:15]
	s_waitcnt vmcnt(6)
	s_barrier
	v_mfma_f32_16x16x32_bf16 v[54:57], v[210:213], v[158:161], v[54:57]
	v_mfma_f32_16x16x32_bf16 v[50:53], v[218:221], v[158:161], v[50:53]
	v_mfma_f32_16x16x32_bf16 v[38:41], v[210:213], v[172:175], v[38:41]
	v_mfma_f32_16x16x32_bf16 v[34:37], v[218:221], v[172:175], v[34:37]
	v_mfma_f32_16x16x32_bf16 v[22:25], v[210:213], v[194:197], v[22:25]
	v_mfma_f32_16x16x32_bf16 v[18:21], v[218:221], v[194:197], v[18:21]
	v_mfma_f32_16x16x32_bf16 v[6:9], v[210:213], v[202:205], v[6:9]
	v_mfma_f32_16x16x32_bf16 v[2:5], v[218:221], v[202:205], v[2:5]
	v_mfma_f32_16x16x32_bf16 v[54:57], v[214:217], v[168:171], v[54:57]
	v_mfma_f32_16x16x32_bf16 v[50:53], v[222:225], v[168:171], v[50:53]
	v_mfma_f32_16x16x32_bf16 v[38:41], v[214:217], v[190:193], v[38:41]
	v_mfma_f32_16x16x32_bf16 v[34:37], v[222:225], v[190:193], v[34:37]
	v_mfma_f32_16x16x32_bf16 v[22:25], v[214:217], v[198:201], v[22:25]
	v_mfma_f32_16x16x32_bf16 v[18:21], v[222:225], v[198:201], v[18:21]
	v_mfma_f32_16x16x32_bf16 v[6:9], v[214:217], v[206:209], v[6:9]
	v_mfma_f32_16x16x32_bf16 v[2:5], v[222:225], v[206:209], v[2:5]
	s_barrier
	s_add_i32 s49, 0, 0x18000
	s_add_u32 s14, s20, 0xb8000
	s_addc_u32 s15, s21, 0
	s_mov_b32 m0, s36
	ds_read_b128 v[158:161], v166 offset:32768
	ds_read_b128 v[168:171], v166 offset:33792
	ds_read_b128 v[172:175], v166 offset:34816
	ds_read_b128 v[190:193], v166 offset:35840
	ds_read_b128 v[194:197], v166 offset:36864
	ds_read_b128 v[198:201], v166 offset:37888
	ds_read_b128 v[202:205], v166 offset:38912
	ds_read_b128 v[206:209], v166 offset:39936
	global_load_lds_dwordx4 v130, s[14:15]
	s_mov_b32 m0, s37
	s_nop 0
	global_load_lds_dwordx4 v134, s[14:15]
	s_waitcnt lgkmcnt(8)
	s_barrier
	s_waitcnt lgkmcnt(0)
	s_waitcnt lgkmcnt(0)
	v_mfma_f32_16x16x32_bf16 v[126:129], v[142:145], v[158:161], v[126:129]
	v_mfma_f32_16x16x32_bf16 v[122:125], v[150:153], v[158:161], v[122:125]
	v_mfma_f32_16x16x32_bf16 v[110:113], v[142:145], v[172:175], v[110:113]
	v_mfma_f32_16x16x32_bf16 v[106:109], v[150:153], v[172:175], v[106:109]
	v_mfma_f32_16x16x32_bf16 v[94:97], v[142:145], v[194:197], v[94:97]
	v_mfma_f32_16x16x32_bf16 v[90:93], v[150:153], v[194:197], v[90:93]
	v_mfma_f32_16x16x32_bf16 v[78:81], v[142:145], v[202:205], v[78:81]
	v_mfma_f32_16x16x32_bf16 v[74:77], v[150:153], v[202:205], v[74:77]
	v_mfma_f32_16x16x32_bf16 v[126:129], v[146:149], v[168:171], v[126:129]
	v_mfma_f32_16x16x32_bf16 v[122:125], v[154:157], v[168:171], v[122:125]
	v_mfma_f32_16x16x32_bf16 v[110:113], v[146:149], v[190:193], v[110:113]
	v_mfma_f32_16x16x32_bf16 v[106:109], v[154:157], v[190:193], v[106:109]
	v_mfma_f32_16x16x32_bf16 v[94:97], v[146:149], v[198:201], v[94:97]
	v_mfma_f32_16x16x32_bf16 v[90:93], v[154:157], v[198:201], v[90:93]
	v_mfma_f32_16x16x32_bf16 v[78:81], v[146:149], v[206:209], v[78:81]
	v_mfma_f32_16x16x32_bf16 v[74:77], v[154:157], v[206:209], v[74:77]
	s_barrier
	s_add_i32 s20, 0, 0x1c000
	s_add_i32 s14, s49, s33
	v_add_u32_e32 v167, s20, v164
	s_mov_b32 m0, s14
	ds_read_b128 v[210:213], v167
	ds_read_b128 v[214:217], v167 offset:1024
	ds_read_b128 v[218:221], v167 offset:2048
	ds_read_b128 v[222:225], v167 offset:3072
	global_load_lds_dwordx4 v132, s[64:65]
	s_add_i32 m0, s14, 0x2000
	s_nop 0
	global_load_lds_dwordx4 v136, s[64:65]
	s_barrier
	s_waitcnt lgkmcnt(0)
	s_waitcnt lgkmcnt(0)
	v_mfma_f32_16x16x32_bf16 v[118:121], v[210:213], v[158:161], v[118:121]
	v_mfma_f32_16x16x32_bf16 v[114:117], v[218:221], v[158:161], v[114:117]
	v_mfma_f32_16x16x32_bf16 v[102:105], v[210:213], v[172:175], v[102:105]
	v_mfma_f32_16x16x32_bf16 v[98:101], v[218:221], v[172:175], v[98:101]
	v_mfma_f32_16x16x32_bf16 v[86:89], v[210:213], v[194:197], v[86:89]
	v_mfma_f32_16x16x32_bf16 v[82:85], v[218:221], v[194:197], v[82:85]
	v_mfma_f32_16x16x32_bf16 v[70:73], v[210:213], v[202:205], v[70:73]
	v_mfma_f32_16x16x32_bf16 v[66:69], v[218:221], v[202:205], v[66:69]
	v_mfma_f32_16x16x32_bf16 v[118:121], v[214:217], v[168:171], v[118:121]
	v_mfma_f32_16x16x32_bf16 v[114:117], v[222:225], v[168:171], v[114:117]
	v_mfma_f32_16x16x32_bf16 v[102:105], v[214:217], v[190:193], v[102:105]
	v_mfma_f32_16x16x32_bf16 v[98:101], v[222:225], v[190:193], v[98:101]
	v_mfma_f32_16x16x32_bf16 v[86:89], v[214:217], v[198:201], v[86:89]
	v_mfma_f32_16x16x32_bf16 v[82:85], v[222:225], v[198:201], v[82:85]
	v_mfma_f32_16x16x32_bf16 v[70:73], v[214:217], v[206:209], v[70:73]
	v_mfma_f32_16x16x32_bf16 v[66:69], v[222:225], v[206:209], v[66:69]
	s_barrier
	s_mov_b32 m0, s38
	ds_read_b128 v[158:161], v166 offset:49152
	ds_read_b128 v[168:171], v166 offset:50176
	ds_read_b128 v[172:175], v166 offset:51200
	ds_read_b128 v[190:193], v166 offset:52224
	ds_read_b128 v[194:197], v166 offset:53248
	ds_read_b128 v[198:201], v166 offset:54272
	ds_read_b128 v[202:205], v166 offset:55296
	ds_read_b128 v[206:209], v166 offset:56320
	global_load_lds_dwordx4 v130, s[62:63]
	s_mov_b32 m0, s39
	s_nop 0
	global_load_lds_dwordx4 v134, s[62:63]
	s_waitcnt vmcnt(10)
	s_barrier
	s_waitcnt lgkmcnt(0)
	s_waitcnt lgkmcnt(0)
	v_mfma_f32_16x16x32_bf16 v[62:65], v[142:145], v[158:161], v[62:65]
	v_mfma_f32_16x16x32_bf16 v[58:61], v[150:153], v[158:161], v[58:61]
	v_mfma_f32_16x16x32_bf16 v[46:49], v[142:145], v[172:175], v[46:49]
	v_mfma_f32_16x16x32_bf16 v[42:45], v[150:153], v[172:175], v[42:45]
	v_mfma_f32_16x16x32_bf16 v[30:33], v[142:145], v[194:197], v[30:33]
	v_mfma_f32_16x16x32_bf16 v[26:29], v[150:153], v[194:197], v[26:29]
	v_mfma_f32_16x16x32_bf16 v[14:17], v[142:145], v[202:205], v[14:17]
	v_mfma_f32_16x16x32_bf16 v[10:13], v[150:153], v[202:205], v[10:13]
	v_mfma_f32_16x16x32_bf16 v[62:65], v[146:149], v[168:171], v[62:65]
	v_mfma_f32_16x16x32_bf16 v[58:61], v[154:157], v[168:171], v[58:61]
	v_mfma_f32_16x16x32_bf16 v[46:49], v[146:149], v[190:193], v[46:49]
	v_mfma_f32_16x16x32_bf16 v[42:45], v[154:157], v[190:193], v[42:45]
	v_mfma_f32_16x16x32_bf16 v[30:33], v[146:149], v[198:201], v[30:33]
	v_mfma_f32_16x16x32_bf16 v[26:29], v[154:157], v[198:201], v[26:29]
	v_mfma_f32_16x16x32_bf16 v[14:17], v[146:149], v[206:209], v[14:17]
	v_mfma_f32_16x16x32_bf16 v[10:13], v[154:157], v[206:209], v[10:13]
	s_barrier
	v_add_u32_e32 v154, 0x10000, v164
	ds_read_b128 v[142:145], v154
	ds_read_b128 v[146:149], v154 offset:1024
	ds_read_b128 v[150:153], v154 offset:2048
	ds_read_b128 v[154:157], v154 offset:3072
	s_add_u32 s14, s18, 0xb0080
	s_addc_u32 s15, s19, 0
	s_add_i32 s18, s20, s33
	s_mov_b32 m0, s18
	s_nop 0
	global_load_lds_dwordx4 v132, s[14:15]
	s_add_i32 m0, s18, 0x2000
	s_nop 0
	global_load_lds_dwordx4 v136, s[14:15]
	s_waitcnt vmcnt(6)
	s_barrier
	v_mfma_f32_16x16x32_bf16 v[54:57], v[210:213], v[158:161], v[54:57]
	v_mfma_f32_16x16x32_bf16 v[50:53], v[218:221], v[158:161], v[50:53]
	v_mfma_f32_16x16x32_bf16 v[38:41], v[210:213], v[172:175], v[38:41]
	v_mfma_f32_16x16x32_bf16 v[34:37], v[218:221], v[172:175], v[34:37]
	v_mfma_f32_16x16x32_bf16 v[22:25], v[210:213], v[194:197], v[22:25]
	v_mfma_f32_16x16x32_bf16 v[18:21], v[218:221], v[194:197], v[18:21]
	v_mfma_f32_16x16x32_bf16 v[6:9], v[210:213], v[202:205], v[6:9]
	v_mfma_f32_16x16x32_bf16 v[2:5], v[218:221], v[202:205], v[2:5]
	v_mfma_f32_16x16x32_bf16 v[54:57], v[214:217], v[168:171], v[54:57]
	v_mfma_f32_16x16x32_bf16 v[50:53], v[222:225], v[168:171], v[50:53]
	v_mfma_f32_16x16x32_bf16 v[38:41], v[214:217], v[190:193], v[38:41]
	v_mfma_f32_16x16x32_bf16 v[34:37], v[222:225], v[190:193], v[34:37]
	v_mfma_f32_16x16x32_bf16 v[22:25], v[214:217], v[198:201], v[22:25]
	v_mfma_f32_16x16x32_bf16 v[18:21], v[222:225], v[198:201], v[18:21]
	v_mfma_f32_16x16x32_bf16 v[6:9], v[214:217], v[206:209], v[6:9]
	v_mfma_f32_16x16x32_bf16 v[2:5], v[222:225], v[206:209], v[2:5]
	s_barrier
	s_add_i32 s48, s48, 2
	s_add_u32 s46, s46, 0x100
	s_addc_u32 s47, s47, 0
	s_cmp_gt_u32 s48, 41
	s_mov_b64 s[14:15], s[16:17]
	s_cbranch_scc0 .LBB0_400
	s_waitcnt lgkmcnt(0)
	s_ashr_i32 s14, s44, 5
	v_lshl_or_b32 v176, s45, 8, v165
	s_mul_hi_i32 s15, s14, 0x9000
	s_mul_i32 s14, s14, 0x9000
	s_add_u32 s14, s26, s14
	v_ashrrev_i32_e32 v177, 31, v176
	s_addc_u32 s15, s27, s15
	v_lshlrev_b64 v[158:159], 2, v[176:177]
	v_lshl_add_u64 v[160:161], s[14:15], 0, v[158:159]
	global_load_dwordx4 v[142:145], v[160:161], off offset:16
	global_load_dwordx4 v[146:149], v[160:161], off
	v_lshl_add_u32 v162, s44, 8, v1
	v_ashrrev_i32_e32 v163, 31, v162
	v_lshl_add_u32 v131, v162, 12, v158
	global_load_dwordx4 v[188:191], v131, s[2:3] offset:16
	global_load_dwordx4 v[192:195], v131, s[2:3]
	global_load_dwordx4 v[196:199], v131, s[2:3] offset:528
	global_load_dwordx4 v[200:203], v131, s[2:3] offset:512
	v_add_u32_e32 v131, 0x10000, v131
	global_load_dwordx4 v[204:207], v131, s[2:3] offset:16
	global_load_dwordx4 v[208:211], v131, s[2:3]
	global_load_dwordx4 v[212:215], v131, s[2:3] offset:528
	global_load_dwordx4 v[216:219], v131, s[2:3] offset:512
	v_add_u32_e32 v131, 0x10000, v131
	global_load_dwordx4 v[220:223], v131, s[2:3] offset:16
	global_load_dwordx4 v[224:227], v131, s[2:3]
	global_load_dwordx4 v[228:231], v131, s[2:3] offset:528
	global_load_dwordx4 v[236:239], v131, s[2:3] offset:512
	v_add_u32_e32 v131, 0x10000, v131
	global_load_dwordx4 v[246:249], v131, s[2:3] offset:16
	global_load_dwordx4 v[250:253], v131, s[2:3]
	v_mov_b32_e32 v133, v131
	s_mov_b64 s[14:15], 0x80000
	s_and_b64 vcc, exec, s[4:5]
	s_mov_b32 s45, s42
	s_mov_b32 s44, s43
	s_mov_b64 s[16:17], s[8:9]
	s_waitcnt vmcnt(0)
	v_pk_add_f32 v[144:145], v[144:145], 1.0 op_sel_hi:[1,0]
	v_pk_add_f32 v[148:149], v[148:149], 1.0 op_sel_hi:[1,0]
	v_pk_add_f32 v[146:147], v[146:147], 1.0 op_sel_hi:[1,0]
	v_pk_add_f32 v[142:143], v[142:143], 1.0 op_sel_hi:[1,0]
	v_pk_mul_f32 v[150:151], v[148:149], 0.5 op_sel_hi:[1,0]
	v_pk_mul_f32 v[152:153], v[146:147], 0.5 op_sel_hi:[1,0]
	v_pk_mul_f32 v[154:155], v[144:145], 0.5 op_sel_hi:[1,0]
	v_pk_mul_f32 v[156:157], v[142:143], 0.5 op_sel_hi:[1,0]
	global_load_dwordx4 v[146:149], v[160:161], off offset:528
	global_load_dwordx4 v[142:145], v[160:161], off offset:512
	s_waitcnt vmcnt(0)
	v_pk_add_f32 v[148:149], v[148:149], 1.0 op_sel_hi:[1,0]
	v_pk_add_f32 v[144:145], v[144:145], 1.0 op_sel_hi:[1,0]
	v_pk_add_f32 v[160:161], v[142:143], 1.0 op_sel_hi:[1,0]
	v_pk_mul_f32 v[142:143], v[144:145], 0.5 op_sel_hi:[1,0]
	v_pk_mul_f32 v[144:145], v[160:161], 0.5 op_sel_hi:[1,0]
	v_pk_add_f32 v[160:161], v[146:147], 1.0 op_sel_hi:[1,0]
	v_pk_mul_f32 v[146:147], v[148:149], 0.5 op_sel_hi:[1,0]
	v_pk_mul_f32 v[148:149], v[160:161], 0.5 op_sel_hi:[1,0]
	v_lshlrev_b64 v[160:161], 12, v[162:163]
	v_lshl_add_u64 v[168:169], s[2:3], 0, v[160:161]
	v_lshl_add_u64 v[186:187], v[168:169], 0, v[158:159]
	v_mov_b32_e32 v168, v188
	v_mov_b32_e32 v169, v189
	v_mov_b32_e32 v170, v190
	v_mov_b32_e32 v171, v191
	v_mov_b32_e32 v172, v192
	v_mov_b32_e32 v173, v193
	v_mov_b32_e32 v174, v194
	v_mov_b32_e32 v175, v195
	global_load_dwordx4 v[188:191], v133, s[2:3] offset:528
	global_load_dwordx4 v[192:195], v133, s[2:3] offset:512
	v_pk_fma_f32 v[122:123], v[122:123], v[156:157], v[168:169]
	v_pk_fma_f32 v[128:129], v[128:129], v[150:151], v[174:175]
	v_pk_fma_f32 v[126:127], v[126:127], v[152:153], v[172:173]
	v_pk_fma_f32 v[170:171], v[124:125], v[154:155], v[170:171]
	v_cvt_pk_bf16_f32 v124, v126, v127
	v_cvt_pk_bf16_f32 v125, v128, v129
	v_cvt_pk_bf16_f32 v126, v122, v123
	v_lshl_add_u64 v[128:129], s[12:13], 0, v[160:161]
	v_lshlrev_b64 v[122:123], 1, v[176:177]
	v_cvt_pk_bf16_f32 v127, v170, v171
	v_lshl_add_u64 v[128:129], v[128:129], 0, v[122:123]
	global_store_dwordx4 v[128:129], v[124:127], off offset:2048
	s_nop 1
	v_mov_b32_e32 v124, v196
	v_mov_b32_e32 v125, v197
	v_mov_b32_e32 v126, v198
	v_mov_b32_e32 v127, v199
	s_nop 0
	v_mov_b32_e32 v168, v200
	v_mov_b32_e32 v169, v201
	v_mov_b32_e32 v170, v202
	v_mov_b32_e32 v171, v203
	v_add_u32_e32 v133, 0x50000, v133
	global_load_dwordx4 v[196:199], v133, s[2:3] offset:16
	global_load_dwordx4 v[200:203], v133, s[2:3]
	v_pk_fma_f32 v[126:127], v[116:117], v[146:147], v[126:127]
	v_pk_fma_f32 v[120:121], v[120:121], v[142:143], v[170:171]
	v_pk_fma_f32 v[118:119], v[118:119], v[144:145], v[168:169]
	v_pk_fma_f32 v[116:117], v[114:115], v[148:149], v[124:125]
	v_cvt_pk_bf16_f32 v114, v118, v119
	v_cvt_pk_bf16_f32 v115, v120, v121
	v_cvt_pk_bf16_f32 v116, v116, v117
	v_cvt_pk_bf16_f32 v117, v126, v127
	global_store_dwordx4 v[128:129], v[114:117], off offset:2304
	s_nop 1
	v_or_b32_e32 v114, 16, v162
	v_ashrrev_i32_e32 v115, 31, v114
	v_lshlrev_b64 v[124:125], 12, v[114:115]
	v_lshl_add_u64 v[114:115], s[2:3], 0, v[124:125]
	v_lshl_add_u64 v[126:127], v[114:115], 0, v[158:159]
	v_mov_b32_e32 v114, v204
	v_mov_b32_e32 v115, v205
	v_mov_b32_e32 v116, v206
	v_mov_b32_e32 v117, v207
	v_mov_b32_e32 v118, v208
	v_mov_b32_e32 v119, v209
	v_mov_b32_e32 v120, v210
	v_mov_b32_e32 v121, v211
	global_load_dwordx4 v[204:207], v133, s[2:3] offset:528
	global_load_dwordx4 v[208:211], v133, s[2:3] offset:512
	v_pk_fma_f32 v[116:117], v[108:109], v[154:155], v[116:117]
	v_pk_fma_f32 v[110:111], v[110:111], v[152:153], v[118:119]
	v_pk_fma_f32 v[112:113], v[112:113], v[150:151], v[120:121]
	v_pk_fma_f32 v[108:109], v[106:107], v[156:157], v[114:115]
	v_cvt_pk_bf16_f32 v106, v110, v111
	v_lshl_add_u64 v[110:111], s[12:13], 0, v[124:125]
	v_cvt_pk_bf16_f32 v107, v112, v113
	v_cvt_pk_bf16_f32 v108, v108, v109
	v_cvt_pk_bf16_f32 v109, v116, v117
	v_lshl_add_u64 v[114:115], v[110:111], 0, v[122:123]
	global_store_dwordx4 v[114:115], v[106:109], off offset:2048
	s_nop 1
	v_mov_b32_e32 v106, v212
	v_mov_b32_e32 v107, v213
	v_mov_b32_e32 v108, v214
	v_mov_b32_e32 v109, v215
	s_nop 0
	v_mov_b32_e32 v110, v216
	v_mov_b32_e32 v111, v217
	v_mov_b32_e32 v112, v218
	v_mov_b32_e32 v113, v219
	v_add_u32_e32 v133, 0x10000, v133
	global_load_dwordx4 v[212:215], v133, s[2:3] offset:16
	global_load_dwordx4 v[216:219], v133, s[2:3]
	v_pk_fma_f32 v[108:109], v[100:101], v[146:147], v[108:109]
	v_pk_fma_f32 v[104:105], v[104:105], v[142:143], v[112:113]
	v_pk_fma_f32 v[102:103], v[102:103], v[144:145], v[110:111]
	v_pk_fma_f32 v[100:101], v[98:99], v[148:149], v[106:107]
	v_cvt_pk_bf16_f32 v98, v102, v103
	v_cvt_pk_bf16_f32 v99, v104, v105
	v_cvt_pk_bf16_f32 v100, v100, v101
	v_cvt_pk_bf16_f32 v101, v108, v109
	global_store_dwordx4 v[114:115], v[98:101], off offset:2304
	s_nop 1
	v_or_b32_e32 v98, 32, v162
	v_ashrrev_i32_e32 v99, 31, v98
	v_lshlrev_b64 v[106:107], 12, v[98:99]
	v_lshl_add_u64 v[98:99], s[2:3], 0, v[106:107]
	v_lshl_add_u64 v[108:109], v[98:99], 0, v[158:159]
	v_mov_b32_e32 v98, v220
	v_mov_b32_e32 v99, v221
	v_mov_b32_e32 v100, v222
	v_mov_b32_e32 v101, v223
	v_mov_b32_e32 v102, v224
	v_mov_b32_e32 v103, v225
	v_mov_b32_e32 v104, v226
	v_mov_b32_e32 v105, v227
	global_load_dwordx4 v[220:223], v133, s[2:3] offset:528
	global_load_dwordx4 v[224:227], v133, s[2:3] offset:512
	v_pk_fma_f32 v[100:101], v[92:93], v[154:155], v[100:101]
	v_pk_fma_f32 v[94:95], v[94:95], v[152:153], v[102:103]
	v_pk_fma_f32 v[96:97], v[96:97], v[150:151], v[104:105]
	v_pk_fma_f32 v[92:93], v[90:91], v[156:157], v[98:99]
	v_cvt_pk_bf16_f32 v90, v94, v95
	v_lshl_add_u64 v[94:95], s[12:13], 0, v[106:107]
	v_cvt_pk_bf16_f32 v91, v96, v97
	v_cvt_pk_bf16_f32 v92, v92, v93
	v_cvt_pk_bf16_f32 v93, v100, v101
	v_lshl_add_u64 v[98:99], v[94:95], 0, v[122:123]
	global_store_dwordx4 v[98:99], v[90:93], off offset:2048
	s_nop 1
	v_mov_b32_e32 v90, v228
	v_mov_b32_e32 v91, v229
	v_mov_b32_e32 v92, v230
	v_mov_b32_e32 v93, v231
	s_nop 0
	v_mov_b32_e32 v94, v236
	v_mov_b32_e32 v95, v237
	v_mov_b32_e32 v96, v238
	v_mov_b32_e32 v97, v239
	v_add_u32_e32 v133, 0x10000, v133
	global_load_dwordx4 v[228:231], v133, s[2:3] offset:16
	global_load_dwordx4 v[236:239], v133, s[2:3]
	v_pk_fma_f32 v[92:93], v[84:85], v[146:147], v[92:93]
	v_pk_fma_f32 v[88:89], v[88:89], v[142:143], v[96:97]
	v_pk_fma_f32 v[86:87], v[86:87], v[144:145], v[94:95]
	v_pk_fma_f32 v[84:85], v[82:83], v[148:149], v[90:91]
	v_cvt_pk_bf16_f32 v82, v86, v87
	v_cvt_pk_bf16_f32 v83, v88, v89
	v_cvt_pk_bf16_f32 v84, v84, v85
	v_cvt_pk_bf16_f32 v85, v92, v93
	global_store_dwordx4 v[98:99], v[82:85], off offset:2304
	s_nop 1
	v_or_b32_e32 v82, 48, v162
	v_ashrrev_i32_e32 v83, 31, v82
	v_lshlrev_b64 v[90:91], 12, v[82:83]
	v_lshl_add_u64 v[82:83], s[2:3], 0, v[90:91]
	v_lshl_add_u64 v[92:93], v[82:83], 0, v[158:159]
	v_mov_b32_e32 v82, v246
	v_mov_b32_e32 v83, v247
	v_mov_b32_e32 v84, v248
	v_mov_b32_e32 v85, v249
	v_mov_b32_e32 v86, v250
	v_mov_b32_e32 v87, v251
	v_mov_b32_e32 v88, v252
	v_mov_b32_e32 v89, v253
	global_load_dwordx4 v[246:249], v133, s[2:3] offset:528
	global_load_dwordx4 v[250:253], v133, s[2:3] offset:512
	v_pk_fma_f32 v[84:85], v[76:77], v[154:155], v[84:85]
	v_pk_fma_f32 v[78:79], v[78:79], v[152:153], v[86:87]
	v_pk_fma_f32 v[80:81], v[80:81], v[150:151], v[88:89]
	v_pk_fma_f32 v[76:77], v[74:75], v[156:157], v[82:83]
	v_cvt_pk_bf16_f32 v74, v78, v79
	v_lshl_add_u64 v[78:79], s[12:13], 0, v[90:91]
	v_cvt_pk_bf16_f32 v75, v80, v81
	v_cvt_pk_bf16_f32 v76, v76, v77
	v_cvt_pk_bf16_f32 v77, v84, v85
	v_lshl_add_u64 v[82:83], v[78:79], 0, v[122:123]
	global_store_dwordx4 v[82:83], v[74:77], off offset:2048
	s_nop 1
	s_waitcnt vmcnt(19)
	v_mov_b32_e32 v74, v188
	v_mov_b32_e32 v75, v189
	v_mov_b32_e32 v76, v190
	v_mov_b32_e32 v77, v191
	s_nop 0
	v_mov_b32_e32 v78, v192
	v_mov_b32_e32 v79, v193
	v_mov_b32_e32 v80, v194
	v_mov_b32_e32 v81, v195
	v_add_u32_e32 v133, 0x10000, v133
	global_load_dwordx4 v[188:191], v133, s[2:3] offset:16
	global_load_dwordx4 v[192:195], v133, s[2:3]
	v_pk_fma_f32 v[76:77], v[68:69], v[146:147], v[76:77]
	v_pk_fma_f32 v[72:73], v[72:73], v[142:143], v[80:81]
	v_pk_fma_f32 v[70:71], v[70:71], v[144:145], v[78:79]
	v_pk_fma_f32 v[68:69], v[66:67], v[148:149], v[74:75]
	v_cvt_pk_bf16_f32 v66, v70, v71
	v_cvt_pk_bf16_f32 v67, v72, v73
	v_cvt_pk_bf16_f32 v68, v68, v69
	v_cvt_pk_bf16_f32 v69, v76, v77
	v_lshl_add_u64 v[74:75], v[160:161], 0, s[14:15]
	global_store_dwordx4 v[82:83], v[66:69], off offset:2304
	s_mov_b64 s[14:15], 0x90000
	s_nop 0
	v_lshl_add_u64 v[66:67], s[2:3], 0, v[74:75]
	v_lshl_add_u64 v[76:77], v[66:67], 0, v[158:159]
	s_waitcnt vmcnt(19)
	v_mov_b32_e32 v66, v196
	v_mov_b32_e32 v67, v197
	v_mov_b32_e32 v68, v198
	v_mov_b32_e32 v69, v199
	v_mov_b32_e32 v70, v200
	v_mov_b32_e32 v71, v201
	v_mov_b32_e32 v72, v202
	v_mov_b32_e32 v73, v203
	global_load_dwordx4 v[196:199], v133, s[2:3] offset:528
	global_load_dwordx4 v[200:203], v133, s[2:3] offset:512
	v_pk_fma_f32 v[68:69], v[60:61], v[154:155], v[68:69]
	v_pk_fma_f32 v[62:63], v[62:63], v[152:153], v[70:71]
	v_pk_fma_f32 v[64:65], v[64:65], v[150:151], v[72:73]
	v_pk_fma_f32 v[60:61], v[58:59], v[156:157], v[66:67]
	v_cvt_pk_bf16_f32 v58, v62, v63
	v_lshl_add_u64 v[62:63], s[12:13], 0, v[74:75]
	v_cvt_pk_bf16_f32 v59, v64, v65
	v_cvt_pk_bf16_f32 v60, v60, v61
	v_cvt_pk_bf16_f32 v61, v68, v69
	v_lshl_add_u64 v[66:67], v[62:63], 0, v[122:123]
	global_store_dwordx4 v[66:67], v[58:61], off offset:2048
	s_nop 1
	s_waitcnt vmcnt(19)
	v_mov_b32_e32 v58, v204
	v_mov_b32_e32 v59, v205
	v_mov_b32_e32 v60, v206
	v_mov_b32_e32 v61, v207
	s_nop 0
	v_mov_b32_e32 v62, v208
	v_mov_b32_e32 v63, v209
	v_mov_b32_e32 v64, v210
	v_mov_b32_e32 v65, v211
	s_nop 0
	v_pk_fma_f32 v[60:61], v[52:53], v[146:147], v[60:61]
	v_pk_fma_f32 v[56:57], v[56:57], v[142:143], v[64:65]
	v_pk_fma_f32 v[54:55], v[54:55], v[144:145], v[62:63]
	v_pk_fma_f32 v[52:53], v[50:51], v[148:149], v[58:59]
	v_cvt_pk_bf16_f32 v50, v54, v55
	v_cvt_pk_bf16_f32 v51, v56, v57
	v_cvt_pk_bf16_f32 v52, v52, v53
	v_cvt_pk_bf16_f32 v53, v60, v61
	v_lshl_add_u64 v[58:59], v[160:161], 0, s[14:15]
	global_store_dwordx4 v[66:67], v[50:53], off offset:2304
	s_mov_b64 s[14:15], 0xa0000
	s_nop 0
	v_lshl_add_u64 v[50:51], s[2:3], 0, v[58:59]
	v_lshl_add_u64 v[60:61], v[50:51], 0, v[158:159]
	s_waitcnt vmcnt(17)
	v_mov_b32_e32 v50, v212
	v_mov_b32_e32 v51, v213
	v_mov_b32_e32 v52, v214
	v_mov_b32_e32 v53, v215
	v_mov_b32_e32 v54, v216
	v_mov_b32_e32 v55, v217
	v_mov_b32_e32 v56, v218
	v_mov_b32_e32 v57, v219
	s_nop 0
	v_pk_fma_f32 v[52:53], v[44:45], v[154:155], v[52:53]
	v_pk_fma_f32 v[46:47], v[46:47], v[152:153], v[54:55]
	v_pk_fma_f32 v[48:49], v[48:49], v[150:151], v[56:57]
	v_pk_fma_f32 v[44:45], v[42:43], v[156:157], v[50:51]
	v_cvt_pk_bf16_f32 v42, v46, v47
	v_lshl_add_u64 v[46:47], s[12:13], 0, v[58:59]
	v_cvt_pk_bf16_f32 v43, v48, v49
	v_cvt_pk_bf16_f32 v44, v44, v45
	v_cvt_pk_bf16_f32 v45, v52, v53
	v_lshl_add_u64 v[50:51], v[46:47], 0, v[122:123]
	global_store_dwordx4 v[50:51], v[42:45], off offset:2048
	s_nop 1
	s_waitcnt vmcnt(15)
	v_mov_b32_e32 v42, v220
	v_mov_b32_e32 v43, v221
	v_mov_b32_e32 v44, v222
	v_mov_b32_e32 v45, v223
	s_nop 0
	v_mov_b32_e32 v46, v224
	v_mov_b32_e32 v47, v225
	v_mov_b32_e32 v48, v226
	v_mov_b32_e32 v49, v227
	s_nop 0
	v_pk_fma_f32 v[44:45], v[36:37], v[146:147], v[44:45]
	v_pk_fma_f32 v[40:41], v[40:41], v[142:143], v[48:49]
	v_pk_fma_f32 v[38:39], v[38:39], v[144:145], v[46:47]
	v_pk_fma_f32 v[36:37], v[34:35], v[148:149], v[42:43]
	v_cvt_pk_bf16_f32 v34, v38, v39
	v_cvt_pk_bf16_f32 v35, v40, v41
	v_cvt_pk_bf16_f32 v36, v36, v37
	v_cvt_pk_bf16_f32 v37, v44, v45
	v_lshl_add_u64 v[42:43], v[160:161], 0, s[14:15]
	global_store_dwordx4 v[50:51], v[34:37], off offset:2304
	s_mov_b64 s[14:15], 0xb0000
	s_nop 0
	v_lshl_add_u64 v[34:35], s[2:3], 0, v[42:43]
	v_lshl_add_u64 v[44:45], v[34:35], 0, v[158:159]
	s_waitcnt vmcnt(13)
	v_mov_b32_e32 v34, v228
	v_mov_b32_e32 v35, v229
	v_mov_b32_e32 v36, v230
	v_mov_b32_e32 v37, v231
	v_mov_b32_e32 v38, v236
	v_mov_b32_e32 v39, v237
	v_mov_b32_e32 v40, v238
	v_mov_b32_e32 v41, v239
	s_nop 0
	v_pk_fma_f32 v[36:37], v[28:29], v[154:155], v[36:37]
	v_pk_fma_f32 v[30:31], v[30:31], v[152:153], v[38:39]
	v_pk_fma_f32 v[32:33], v[32:33], v[150:151], v[40:41]
	v_pk_fma_f32 v[28:29], v[26:27], v[156:157], v[34:35]
	v_cvt_pk_bf16_f32 v26, v30, v31
	v_lshl_add_u64 v[30:31], s[12:13], 0, v[42:43]
	v_cvt_pk_bf16_f32 v27, v32, v33
	v_cvt_pk_bf16_f32 v28, v28, v29
	v_cvt_pk_bf16_f32 v29, v36, v37
	v_lshl_add_u64 v[34:35], v[30:31], 0, v[122:123]
	global_store_dwordx4 v[34:35], v[26:29], off offset:2048
	s_nop 1
	s_waitcnt vmcnt(11)
	v_mov_b32_e32 v26, v246
	v_mov_b32_e32 v27, v247
	v_mov_b32_e32 v28, v248
	v_mov_b32_e32 v29, v249
	s_nop 0
	v_mov_b32_e32 v30, v250
	v_mov_b32_e32 v31, v251
	v_mov_b32_e32 v32, v252
	v_mov_b32_e32 v33, v253
	s_nop 0
	v_pk_fma_f32 v[28:29], v[20:21], v[146:147], v[28:29]
	v_pk_fma_f32 v[24:25], v[24:25], v[142:143], v[32:33]
	v_pk_fma_f32 v[22:23], v[22:23], v[144:145], v[30:31]
	v_pk_fma_f32 v[20:21], v[18:19], v[148:149], v[26:27]
	v_cvt_pk_bf16_f32 v18, v22, v23
	v_cvt_pk_bf16_f32 v19, v24, v25
	v_cvt_pk_bf16_f32 v20, v20, v21
	v_cvt_pk_bf16_f32 v21, v28, v29
	v_lshl_add_u64 v[26:27], v[160:161], 0, s[14:15]
	global_store_dwordx4 v[34:35], v[18:21], off offset:2304
	s_mov_b64 s[14:15], s[6:7]
	s_nop 0
	v_lshl_add_u64 v[18:19], s[2:3], 0, v[26:27]
	v_lshl_add_u64 v[28:29], v[18:19], 0, v[158:159]
	s_waitcnt vmcnt(9)
	v_mov_b32_e32 v18, v188
	v_mov_b32_e32 v19, v189
	v_mov_b32_e32 v20, v190
	v_mov_b32_e32 v21, v191
	v_mov_b32_e32 v22, v192
	v_mov_b32_e32 v23, v193
	v_mov_b32_e32 v24, v194
	v_mov_b32_e32 v25, v195
	s_nop 0
	v_pk_fma_f32 v[20:21], v[12:13], v[154:155], v[20:21]
	v_pk_fma_f32 v[14:15], v[14:15], v[152:153], v[22:23]
	v_pk_fma_f32 v[16:17], v[16:17], v[150:151], v[24:25]
	v_pk_fma_f32 v[12:13], v[10:11], v[156:157], v[18:19]
	v_cvt_pk_bf16_f32 v10, v14, v15
	v_lshl_add_u64 v[14:15], s[12:13], 0, v[26:27]
	v_cvt_pk_bf16_f32 v11, v16, v17
	v_cvt_pk_bf16_f32 v12, v12, v13
	v_cvt_pk_bf16_f32 v13, v20, v21
	v_lshl_add_u64 v[18:19], v[14:15], 0, v[122:123]
	global_store_dwordx4 v[18:19], v[10:13], off offset:2048
	s_nop 1
	s_waitcnt vmcnt(7)
	v_mov_b32_e32 v10, v196
	v_mov_b32_e32 v11, v197
	v_mov_b32_e32 v12, v198
	v_mov_b32_e32 v13, v199
	s_nop 0
	v_mov_b32_e32 v14, v200
	v_mov_b32_e32 v15, v201
	v_mov_b32_e32 v16, v202
	v_mov_b32_e32 v17, v203
	s_nop 0
	v_pk_fma_f32 v[12:13], v[4:5], v[146:147], v[12:13]
	v_pk_fma_f32 v[8:9], v[8:9], v[142:143], v[16:17]
	v_pk_fma_f32 v[6:7], v[6:7], v[144:145], v[14:15]
	v_pk_fma_f32 v[4:5], v[2:3], v[148:149], v[10:11]
	v_cvt_pk_bf16_f32 v2, v6, v7
	v_cvt_pk_bf16_f32 v3, v8, v9
	v_cvt_pk_bf16_f32 v4, v4, v5
	v_cvt_pk_bf16_f32 v5, v12, v13
	global_store_dwordx4 v[18:19], v[2:5], off offset:2304
	s_cbranch_vccz .LBB0_389
	s_waitcnt vmcnt(0)
	s_cmpk_gt_u32 s30, 0xff
	s_cbranch_scc1 .LBB0_404
	s_barrier

.LBB0_527:
	v_mov_b64_e32 v[2:3], s[80:81]
	s_ashr_i32 s15, s14, 31
	v_cmp_lt_i64_e32 vcc, s[16:17], v[2:3]
	s_lshl_b64 s[16:17], s[14:15], 19
	s_add_u32 s16, s29, s16
	s_addc_u32 s17, s30, s17
	s_and_b64 s[18:19], vcc, exec
	s_cselect_b32 s11, s17, s21
	s_cselect_b32 s15, s16, s20
	s_ashr_i32 s13, s12, 31
	s_lshl_b64 s[18:19], s[12:13], 19
	s_add_u32 s18, s31, s18
	s_addc_u32 s19, s33, s19
	s_and_b64 s[24:25], vcc, exec
	s_cselect_b32 s13, s19, s23
	s_cselect_b32 s51, s18, s22
	s_add_u32 s20, s20, 0x40080
	s_addc_u32 s21, s21, 0
	s_add_u32 s52, s22, 0x100
	s_addc_u32 s53, s23, 0
	s_mov_b32 s54, -2
	s_add_u32 s22, s20, 0xfffc0080
	s_addc_u32 s23, s21, -1
	s_add_i32 s55, 0, 0x10000
	v_add_u32_e32 v144, s55, v146
	ds_read_b128 v[150:153], v144
	ds_read_b128 v[154:157], v144 offset:1024
	ds_read_b128 v[158:161], v144 offset:2048
	ds_read_b128 v[162:165], v144 offset:3072
	s_cmp_eq_u32 s54, 12
	s_cselect_b32 s25, s11, s23
	s_cselect_b32 s24, s15, s22
	s_cselect_b32 s23, s13, s53
	s_cselect_b32 s22, s51, s52
	s_add_i32 m0, s41, 0xc000
	ds_read_b128 v[166:169], v148
	ds_read_b128 v[170:173], v148 offset:1024
	ds_read_b128 v[174:177], v148 offset:2048
	ds_read_b128 v[190:193], v148 offset:3072
	ds_read_b128 v[194:197], v148 offset:4096
	ds_read_b128 v[198:201], v148 offset:5120
	ds_read_b128 v[202:205], v148 offset:6144
	ds_read_b128 v[206:209], v148 offset:7168
	global_load_lds_dwordx4 v140, s[20:21]
	v_lshl_add_u64 v[144:145], s[20:21], 0, v[142:143]
	s_add_i32 m0, s41, 0xe000
	s_nop 0
	global_load_lds_dwordx4 v[144:145], off
	s_waitcnt lgkmcnt(8)
	s_barrier
	s_waitcnt lgkmcnt(0)
	s_waitcnt lgkmcnt(0)
	v_mfma_f32_16x16x32_bf16 v[86:89], v[150:153], v[166:169], 0
	v_mfma_f32_16x16x32_bf16 v[82:85], v[158:161], v[166:169], 0
	v_mfma_f32_16x16x32_bf16 v[78:81], v[150:153], v[174:177], 0
	v_mfma_f32_16x16x32_bf16 v[74:77], v[158:161], v[174:177], 0
	v_mfma_f32_16x16x32_bf16 v[62:65], v[150:153], v[194:197], 0
	v_mfma_f32_16x16x32_bf16 v[58:61], v[158:161], v[194:197], 0
	v_mfma_f32_16x16x32_bf16 v[54:57], v[150:153], v[202:205], 0
	v_mfma_f32_16x16x32_bf16 v[50:53], v[158:161], v[202:205], 0
	v_mfma_f32_16x16x32_bf16 v[86:89], v[154:157], v[170:173], v[86:89]
	v_mfma_f32_16x16x32_bf16 v[82:85], v[162:165], v[170:173], v[82:85]
	v_mfma_f32_16x16x32_bf16 v[78:81], v[154:157], v[190:193], v[78:81]
	v_mfma_f32_16x16x32_bf16 v[74:77], v[162:165], v[190:193], v[74:77]
	v_mfma_f32_16x16x32_bf16 v[62:65], v[154:157], v[198:201], v[62:65]
	v_mfma_f32_16x16x32_bf16 v[58:61], v[162:165], v[198:201], v[58:61]
	v_mfma_f32_16x16x32_bf16 v[54:57], v[154:157], v[206:209], v[54:57]
	v_mfma_f32_16x16x32_bf16 v[50:53], v[162:165], v[206:209], v[50:53]
	s_barrier
	s_add_i32 s58, 0, 0x14000
	v_add_u32_e32 v144, s58, v146
	s_add_i32 s55, s55, s35
	ds_read_b128 v[210:213], v144
	ds_read_b128 v[214:217], v144 offset:1024
	ds_read_b128 v[218:221], v144 offset:2048
	ds_read_b128 v[222:225], v144 offset:3072
	s_add_u32 s64, s22, 0x80
	s_addc_u32 s65, s23, 0
	s_mov_b32 m0, s55
	s_nop 0
	global_load_lds_dwordx4 v134, s[22:23]
	s_add_i32 m0, s55, 0x2000
	s_nop 0
	global_load_lds_dwordx4 v130, s[22:23]
	s_barrier
	s_waitcnt lgkmcnt(0)
	s_waitcnt lgkmcnt(0)
	v_mfma_f32_16x16x32_bf16 v[126:129], v[210:213], v[166:169], 0
	v_mfma_f32_16x16x32_bf16 v[122:125], v[218:221], v[166:169], 0
	v_mfma_f32_16x16x32_bf16 v[118:121], v[210:213], v[174:177], 0
	v_mfma_f32_16x16x32_bf16 v[114:117], v[218:221], v[174:177], 0
	v_mfma_f32_16x16x32_bf16 v[110:113], v[210:213], v[194:197], 0
	v_mfma_f32_16x16x32_bf16 v[106:109], v[218:221], v[194:197], 0
	v_mfma_f32_16x16x32_bf16 v[102:105], v[210:213], v[202:205], 0
	v_mfma_f32_16x16x32_bf16 v[98:101], v[218:221], v[202:205], 0
	v_mfma_f32_16x16x32_bf16 v[126:129], v[214:217], v[170:173], v[126:129]
	v_mfma_f32_16x16x32_bf16 v[122:125], v[222:225], v[170:173], v[122:125]
	v_mfma_f32_16x16x32_bf16 v[118:121], v[214:217], v[190:193], v[118:121]
	v_mfma_f32_16x16x32_bf16 v[114:117], v[222:225], v[190:193], v[114:117]
	v_mfma_f32_16x16x32_bf16 v[110:113], v[214:217], v[198:201], v[110:113]
	v_mfma_f32_16x16x32_bf16 v[106:109], v[222:225], v[198:201], v[106:109]
	v_mfma_f32_16x16x32_bf16 v[102:105], v[214:217], v[206:209], v[102:105]
	v_mfma_f32_16x16x32_bf16 v[98:101], v[222:225], v[206:209], v[98:101]
	s_barrier
	s_mov_b32 m0, s41
	s_add_u32 s62, s24, 0x80
	s_addc_u32 s63, s25, 0
	ds_read_b128 v[166:169], v148 offset:16384
	ds_read_b128 v[170:173], v148 offset:17408
	ds_read_b128 v[174:177], v148 offset:18432
	ds_read_b128 v[190:193], v148 offset:19456
	ds_read_b128 v[194:197], v148 offset:20480
	ds_read_b128 v[198:201], v148 offset:21504
	ds_read_b128 v[202:205], v148 offset:22528
	ds_read_b128 v[206:209], v148 offset:23552
	global_load_lds_dwordx4 v136, s[24:25]
	s_mov_b32 m0, s42
	s_nop 0
	global_load_lds_dwordx4 v132, s[24:25]
	s_waitcnt vmcnt(10)
	s_barrier
	s_waitcnt lgkmcnt(0)
	s_waitcnt lgkmcnt(0)
	v_mfma_f32_16x16x32_bf16 v[34:37], v[150:153], v[166:169], 0
	v_mfma_f32_16x16x32_bf16 v[26:29], v[158:161], v[166:169], 0
	v_mfma_f32_16x16x32_bf16 v[22:25], v[150:153], v[174:177], 0
	v_mfma_f32_16x16x32_bf16 v[18:21], v[158:161], v[174:177], 0
	v_mfma_f32_16x16x32_bf16 v[14:17], v[150:153], v[194:197], 0
	v_mfma_f32_16x16x32_bf16 v[10:13], v[158:161], v[194:197], 0
	v_mfma_f32_16x16x32_bf16 v[6:9], v[150:153], v[202:205], 0
	v_mfma_f32_16x16x32_bf16 v[2:5], v[158:161], v[202:205], 0
	v_mfma_f32_16x16x32_bf16 v[34:37], v[154:157], v[170:173], v[34:37]
	v_mfma_f32_16x16x32_bf16 v[26:29], v[162:165], v[170:173], v[26:29]
	v_mfma_f32_16x16x32_bf16 v[22:25], v[154:157], v[190:193], v[22:25]
	v_mfma_f32_16x16x32_bf16 v[18:21], v[162:165], v[190:193], v[18:21]
	v_mfma_f32_16x16x32_bf16 v[14:17], v[154:157], v[198:201], v[14:17]
	v_mfma_f32_16x16x32_bf16 v[10:13], v[162:165], v[198:201], v[10:13]
	v_mfma_f32_16x16x32_bf16 v[6:9], v[154:157], v[206:209], v[6:9]
	v_mfma_f32_16x16x32_bf16 v[2:5], v[162:165], v[206:209], v[2:5]
	s_barrier
	v_add_u32_e32 v162, 0x18000, v146
	ds_read_b128 v[150:153], v162
	ds_read_b128 v[154:157], v162 offset:1024
	ds_read_b128 v[158:161], v162 offset:2048
	ds_read_b128 v[162:165], v162 offset:3072
	s_add_u32 s56, s22, 0x40000
	s_addc_u32 s57, s23, 0
	s_add_i32 s55, s58, s35
	s_mov_b32 m0, s55
	s_nop 0
	global_load_lds_dwordx4 v134, s[56:57]
	s_add_i32 m0, s55, 0x2000
	s_nop 0
	global_load_lds_dwordx4 v130, s[56:57]
	s_waitcnt vmcnt(6)
	s_barrier
	v_mfma_f32_16x16x32_bf16 v[94:97], v[210:213], v[166:169], 0
	v_mfma_f32_16x16x32_bf16 v[90:93], v[218:221], v[166:169], 0
	v_mfma_f32_16x16x32_bf16 v[70:73], v[210:213], v[174:177], 0
	v_mfma_f32_16x16x32_bf16 v[66:69], v[218:221], v[174:177], 0
	v_mfma_f32_16x16x32_bf16 v[46:49], v[210:213], v[194:197], 0
	v_mfma_f32_16x16x32_bf16 v[42:45], v[218:221], v[194:197], 0
	v_mfma_f32_16x16x32_bf16 v[38:41], v[210:213], v[202:205], 0
	v_mfma_f32_16x16x32_bf16 v[30:33], v[218:221], v[202:205], 0
	v_mfma_f32_16x16x32_bf16 v[94:97], v[214:217], v[170:173], v[94:97]
	v_mfma_f32_16x16x32_bf16 v[90:93], v[222:225], v[170:173], v[90:93]
	v_mfma_f32_16x16x32_bf16 v[70:73], v[214:217], v[190:193], v[70:73]
	v_mfma_f32_16x16x32_bf16 v[66:69], v[222:225], v[190:193], v[66:69]
	v_mfma_f32_16x16x32_bf16 v[46:49], v[214:217], v[198:201], v[46:49]
	v_mfma_f32_16x16x32_bf16 v[42:45], v[222:225], v[198:201], v[42:45]
	v_mfma_f32_16x16x32_bf16 v[38:41], v[214:217], v[206:209], v[38:41]
	v_mfma_f32_16x16x32_bf16 v[30:33], v[222:225], v[206:209], v[30:33]
	s_barrier
	s_add_i32 s55, 0, 0x18000
	v_add_u32_e32 v149, s55, v146
	s_add_u32 s24, s24, 0x40000
	s_addc_u32 s25, s25, 0
	s_mov_b32 m0, s43
	ds_read_b128 v[166:169], v148 offset:32768
	ds_read_b128 v[170:173], v148 offset:33792
	ds_read_b128 v[174:177], v148 offset:34816
	ds_read_b128 v[190:193], v148 offset:35840
	ds_read_b128 v[194:197], v148 offset:36864
	ds_read_b128 v[198:201], v148 offset:37888
	ds_read_b128 v[202:205], v148 offset:38912
	ds_read_b128 v[206:209], v148 offset:39936
	global_load_lds_dwordx4 v136, s[24:25]
	s_mov_b32 m0, s44
	s_nop 0
	global_load_lds_dwordx4 v132, s[24:25]
	s_waitcnt lgkmcnt(8)
	s_barrier
	s_waitcnt lgkmcnt(0)
	s_waitcnt lgkmcnt(0)
	v_mfma_f32_16x16x32_bf16 v[86:89], v[150:153], v[166:169], v[86:89]
	v_mfma_f32_16x16x32_bf16 v[82:85], v[158:161], v[166:169], v[82:85]
	v_mfma_f32_16x16x32_bf16 v[78:81], v[150:153], v[174:177], v[78:81]
	v_mfma_f32_16x16x32_bf16 v[74:77], v[158:161], v[174:177], v[74:77]
	v_mfma_f32_16x16x32_bf16 v[62:65], v[150:153], v[194:197], v[62:65]
	v_mfma_f32_16x16x32_bf16 v[58:61], v[158:161], v[194:197], v[58:61]
	v_mfma_f32_16x16x32_bf16 v[54:57], v[150:153], v[202:205], v[54:57]
	v_mfma_f32_16x16x32_bf16 v[50:53], v[158:161], v[202:205], v[50:53]
	v_mfma_f32_16x16x32_bf16 v[86:89], v[154:157], v[170:173], v[86:89]
	v_mfma_f32_16x16x32_bf16 v[82:85], v[162:165], v[170:173], v[82:85]
	v_mfma_f32_16x16x32_bf16 v[78:81], v[154:157], v[190:193], v[78:81]
	v_mfma_f32_16x16x32_bf16 v[74:77], v[162:165], v[190:193], v[74:77]
	v_mfma_f32_16x16x32_bf16 v[62:65], v[154:157], v[198:201], v[62:65]
	v_mfma_f32_16x16x32_bf16 v[58:61], v[162:165], v[198:201], v[58:61]
	v_mfma_f32_16x16x32_bf16 v[54:57], v[154:157], v[206:209], v[54:57]
	v_mfma_f32_16x16x32_bf16 v[50:53], v[162:165], v[206:209], v[50:53]
	s_barrier
	s_add_i32 s24, 0, 0x1c000
	s_add_i32 s25, s55, s35
	v_add_u32_e32 v149, s24, v146
	s_mov_b32 m0, s25
	ds_read_b128 v[210:213], v149
	ds_read_b128 v[214:217], v149 offset:1024
	ds_read_b128 v[218:221], v149 offset:2048
	ds_read_b128 v[222:225], v149 offset:3072
	global_load_lds_dwordx4 v134, s[64:65]
	s_add_i32 m0, s25, 0x2000
	s_nop 0
	global_load_lds_dwordx4 v130, s[64:65]
	s_barrier
	s_waitcnt lgkmcnt(0)
	s_waitcnt lgkmcnt(0)
	v_mfma_f32_16x16x32_bf16 v[126:129], v[210:213], v[166:169], v[126:129]
	v_mfma_f32_16x16x32_bf16 v[122:125], v[218:221], v[166:169], v[122:125]
	v_mfma_f32_16x16x32_bf16 v[118:121], v[210:213], v[174:177], v[118:121]
	v_mfma_f32_16x16x32_bf16 v[114:117], v[218:221], v[174:177], v[114:117]
	v_mfma_f32_16x16x32_bf16 v[110:113], v[210:213], v[194:197], v[110:113]
	v_mfma_f32_16x16x32_bf16 v[106:109], v[218:221], v[194:197], v[106:109]
	v_mfma_f32_16x16x32_bf16 v[102:105], v[210:213], v[202:205], v[102:105]
	v_mfma_f32_16x16x32_bf16 v[98:101], v[218:221], v[202:205], v[98:101]
	v_mfma_f32_16x16x32_bf16 v[126:129], v[214:217], v[170:173], v[126:129]
	v_mfma_f32_16x16x32_bf16 v[122:125], v[222:225], v[170:173], v[122:125]
	v_mfma_f32_16x16x32_bf16 v[118:121], v[214:217], v[190:193], v[118:121]
	v_mfma_f32_16x16x32_bf16 v[114:117], v[222:225], v[190:193], v[114:117]
	v_mfma_f32_16x16x32_bf16 v[110:113], v[214:217], v[198:201], v[110:113]
	v_mfma_f32_16x16x32_bf16 v[106:109], v[222:225], v[198:201], v[106:109]
	v_mfma_f32_16x16x32_bf16 v[102:105], v[214:217], v[206:209], v[102:105]
	v_mfma_f32_16x16x32_bf16 v[98:101], v[222:225], v[206:209], v[98:101]
	s_barrier
	s_mov_b32 m0, s46
	ds_read_b128 v[166:169], v148 offset:49152
	ds_read_b128 v[170:173], v148 offset:50176
	ds_read_b128 v[174:177], v148 offset:51200
	ds_read_b128 v[190:193], v148 offset:52224
	ds_read_b128 v[194:197], v148 offset:53248
	ds_read_b128 v[198:201], v148 offset:54272
	ds_read_b128 v[202:205], v148 offset:55296
	ds_read_b128 v[206:209], v148 offset:56320
	global_load_lds_dwordx4 v136, s[62:63]
	s_mov_b32 m0, s47
	s_nop 0
	global_load_lds_dwordx4 v132, s[62:63]
	s_waitcnt vmcnt(10)
	s_barrier
	s_waitcnt lgkmcnt(0)
	s_waitcnt lgkmcnt(0)
	v_mfma_f32_16x16x32_bf16 v[34:37], v[150:153], v[166:169], v[34:37]
	v_mfma_f32_16x16x32_bf16 v[26:29], v[158:161], v[166:169], v[26:29]
	v_mfma_f32_16x16x32_bf16 v[22:25], v[150:153], v[174:177], v[22:25]
	v_mfma_f32_16x16x32_bf16 v[18:21], v[158:161], v[174:177], v[18:21]
	v_mfma_f32_16x16x32_bf16 v[14:17], v[150:153], v[194:197], v[14:17]
	v_mfma_f32_16x16x32_bf16 v[10:13], v[158:161], v[194:197], v[10:13]
	v_mfma_f32_16x16x32_bf16 v[6:9], v[150:153], v[202:205], v[6:9]
	v_mfma_f32_16x16x32_bf16 v[2:5], v[158:161], v[202:205], v[2:5]
	v_mfma_f32_16x16x32_bf16 v[34:37], v[154:157], v[170:173], v[34:37]
	v_mfma_f32_16x16x32_bf16 v[26:29], v[162:165], v[170:173], v[26:29]
	v_mfma_f32_16x16x32_bf16 v[22:25], v[154:157], v[190:193], v[22:25]
	v_mfma_f32_16x16x32_bf16 v[18:21], v[162:165], v[190:193], v[18:21]
	v_mfma_f32_16x16x32_bf16 v[14:17], v[154:157], v[198:201], v[14:17]
	v_mfma_f32_16x16x32_bf16 v[10:13], v[162:165], v[198:201], v[10:13]
	v_mfma_f32_16x16x32_bf16 v[6:9], v[154:157], v[206:209], v[6:9]
	v_mfma_f32_16x16x32_bf16 v[2:5], v[162:165], v[206:209], v[2:5]
	s_barrier
	v_add_u32_e32 v162, 0x10000, v146
	ds_read_b128 v[150:153], v162
	ds_read_b128 v[154:157], v162 offset:1024
	ds_read_b128 v[158:161], v162 offset:2048
	ds_read_b128 v[162:165], v162 offset:3072
	s_add_u32 s22, s22, 0x40080
	s_addc_u32 s23, s23, 0
	s_add_i32 s24, s24, s35
	s_mov_b32 m0, s24
	s_nop 0
	global_load_lds_dwordx4 v134, s[22:23]
	v_lshl_add_u64 v[144:145], s[22:23], 0, v[130:131]
	s_add_i32 m0, s24, 0x2000
	s_nop 0
	global_load_lds_dwordx4 v[144:145], off
	s_waitcnt vmcnt(6)
	s_barrier
	v_mfma_f32_16x16x32_bf16 v[94:97], v[210:213], v[166:169], v[94:97]
	v_mfma_f32_16x16x32_bf16 v[90:93], v[218:221], v[166:169], v[90:93]
	v_mfma_f32_16x16x32_bf16 v[70:73], v[210:213], v[174:177], v[70:73]
	v_mfma_f32_16x16x32_bf16 v[66:69], v[218:221], v[174:177], v[66:69]
	v_mfma_f32_16x16x32_bf16 v[46:49], v[210:213], v[194:197], v[46:49]
	v_mfma_f32_16x16x32_bf16 v[42:45], v[218:221], v[194:197], v[42:45]
	v_mfma_f32_16x16x32_bf16 v[38:41], v[210:213], v[202:205], v[38:41]
	v_mfma_f32_16x16x32_bf16 v[30:33], v[218:221], v[202:205], v[30:33]
	v_mfma_f32_16x16x32_bf16 v[94:97], v[214:217], v[170:173], v[94:97]
	v_mfma_f32_16x16x32_bf16 v[90:93], v[222:225], v[170:173], v[90:93]
	v_mfma_f32_16x16x32_bf16 v[70:73], v[214:217], v[190:193], v[70:73]
	v_mfma_f32_16x16x32_bf16 v[66:69], v[222:225], v[190:193], v[66:69]
	v_mfma_f32_16x16x32_bf16 v[46:49], v[214:217], v[198:201], v[46:49]
	v_mfma_f32_16x16x32_bf16 v[42:45], v[222:225], v[198:201], v[42:45]
	v_mfma_f32_16x16x32_bf16 v[38:41], v[214:217], v[206:209], v[38:41]
	v_mfma_f32_16x16x32_bf16 v[30:33], v[222:225], v[206:209], v[30:33]
	s_barrier
	s_add_i32 s54, s54, 2
	s_add_u32 s20, s20, 0x100
	s_addc_u32 s21, s21, 0
	s_add_u32 s52, s52, 0x100
	s_addc_u32 s53, s53, 0
.LBB0_528:
	s_add_u32 s22, s20, 0xfffc0080
	s_addc_u32 s23, s21, -1
	s_add_i32 s55, 0, 0x10000
	v_add_u32_e32 v144, s55, v146
	s_cmp_eq_u32 s54, 12
	s_cselect_b32 s25, s11, s23
	s_cselect_b32 s24, s15, s22
	s_cselect_b32 s23, s13, s53
	s_cselect_b32 s22, s51, s52
	s_add_i32 m0, s41, 0xc000
	ds_read_b128 v[166:169], v148
	ds_read_b128 v[170:173], v148 offset:1024
	ds_read_b128 v[174:177], v148 offset:2048
	ds_read_b128 v[190:193], v148 offset:3072
	ds_read_b128 v[194:197], v148 offset:4096
	ds_read_b128 v[198:201], v148 offset:5120
	ds_read_b128 v[202:205], v148 offset:6144
	ds_read_b128 v[206:209], v148 offset:7168
	global_load_lds_dwordx4 v140, s[20:21]
	v_lshl_add_u64 v[144:145], s[20:21], 0, v[142:143]
	s_add_i32 m0, s41, 0xe000
	s_nop 0
	global_load_lds_dwordx4 v[144:145], off
	s_waitcnt lgkmcnt(8)
	s_barrier
	s_waitcnt lgkmcnt(0)
	s_waitcnt lgkmcnt(0)
	v_mfma_f32_16x16x32_bf16 v[86:89], v[150:153], v[166:169], v[86:89]
	v_mfma_f32_16x16x32_bf16 v[82:85], v[158:161], v[166:169], v[82:85]
	v_mfma_f32_16x16x32_bf16 v[78:81], v[150:153], v[174:177], v[78:81]
	v_mfma_f32_16x16x32_bf16 v[74:77], v[158:161], v[174:177], v[74:77]
	v_mfma_f32_16x16x32_bf16 v[62:65], v[150:153], v[194:197], v[62:65]
	v_mfma_f32_16x16x32_bf16 v[58:61], v[158:161], v[194:197], v[58:61]
	v_mfma_f32_16x16x32_bf16 v[54:57], v[150:153], v[202:205], v[54:57]
	v_mfma_f32_16x16x32_bf16 v[50:53], v[158:161], v[202:205], v[50:53]
	v_mfma_f32_16x16x32_bf16 v[86:89], v[154:157], v[170:173], v[86:89]
	v_mfma_f32_16x16x32_bf16 v[82:85], v[162:165], v[170:173], v[82:85]
	v_mfma_f32_16x16x32_bf16 v[78:81], v[154:157], v[190:193], v[78:81]
	v_mfma_f32_16x16x32_bf16 v[74:77], v[162:165], v[190:193], v[74:77]
	v_mfma_f32_16x16x32_bf16 v[62:65], v[154:157], v[198:201], v[62:65]
	v_mfma_f32_16x16x32_bf16 v[58:61], v[162:165], v[198:201], v[58:61]
	v_mfma_f32_16x16x32_bf16 v[54:57], v[154:157], v[206:209], v[54:57]
	v_mfma_f32_16x16x32_bf16 v[50:53], v[162:165], v[206:209], v[50:53]
	s_barrier
	s_add_i32 s58, 0, 0x14000
	v_add_u32_e32 v144, s58, v146
	s_add_i32 s55, s55, s35
	ds_read_b128 v[210:213], v144
	ds_read_b128 v[214:217], v144 offset:1024
	ds_read_b128 v[218:221], v144 offset:2048
	ds_read_b128 v[222:225], v144 offset:3072
	s_add_u32 s64, s22, 0x80
	s_addc_u32 s65, s23, 0
	s_mov_b32 m0, s55
	s_nop 0
	global_load_lds_dwordx4 v134, s[22:23]
	s_add_i32 m0, s55, 0x2000
	s_nop 0
	global_load_lds_dwordx4 v130, s[22:23]
	s_barrier
	s_waitcnt lgkmcnt(0)
	s_waitcnt lgkmcnt(0)
	v_mfma_f32_16x16x32_bf16 v[126:129], v[210:213], v[166:169], v[126:129]
	v_mfma_f32_16x16x32_bf16 v[122:125], v[218:221], v[166:169], v[122:125]
	v_mfma_f32_16x16x32_bf16 v[118:121], v[210:213], v[174:177], v[118:121]
	v_mfma_f32_16x16x32_bf16 v[114:117], v[218:221], v[174:177], v[114:117]
	v_mfma_f32_16x16x32_bf16 v[110:113], v[210:213], v[194:197], v[110:113]
	v_mfma_f32_16x16x32_bf16 v[106:109], v[218:221], v[194:197], v[106:109]
	v_mfma_f32_16x16x32_bf16 v[102:105], v[210:213], v[202:205], v[102:105]
	v_mfma_f32_16x16x32_bf16 v[98:101], v[218:221], v[202:205], v[98:101]
	v_mfma_f32_16x16x32_bf16 v[126:129], v[214:217], v[170:173], v[126:129]
	v_mfma_f32_16x16x32_bf16 v[122:125], v[222:225], v[170:173], v[122:125]
	v_mfma_f32_16x16x32_bf16 v[118:121], v[214:217], v[190:193], v[118:121]
	v_mfma_f32_16x16x32_bf16 v[114:117], v[222:225], v[190:193], v[114:117]
	v_mfma_f32_16x16x32_bf16 v[110:113], v[214:217], v[198:201], v[110:113]
	v_mfma_f32_16x16x32_bf16 v[106:109], v[222:225], v[198:201], v[106:109]
	v_mfma_f32_16x16x32_bf16 v[102:105], v[214:217], v[206:209], v[102:105]
	v_mfma_f32_16x16x32_bf16 v[98:101], v[222:225], v[206:209], v[98:101]
	s_barrier
	s_mov_b32 m0, s41
	s_add_u32 s62, s24, 0x80
	s_addc_u32 s63, s25, 0
	ds_read_b128 v[166:169], v148 offset:16384
	ds_read_b128 v[170:173], v148 offset:17408
	ds_read_b128 v[174:177], v148 offset:18432
	ds_read_b128 v[190:193], v148 offset:19456
	ds_read_b128 v[194:197], v148 offset:20480
	ds_read_b128 v[198:201], v148 offset:21504
	ds_read_b128 v[202:205], v148 offset:22528
	ds_read_b128 v[206:209], v148 offset:23552
	global_load_lds_dwordx4 v136, s[24:25]
	s_mov_b32 m0, s42
	s_nop 0
	global_load_lds_dwordx4 v132, s[24:25]
	s_waitcnt vmcnt(10)
	s_barrier
	s_waitcnt lgkmcnt(0)
	s_waitcnt lgkmcnt(0)
	v_mfma_f32_16x16x32_bf16 v[34:37], v[150:153], v[166:169], v[34:37]
	v_mfma_f32_16x16x32_bf16 v[26:29], v[158:161], v[166:169], v[26:29]
	v_mfma_f32_16x16x32_bf16 v[22:25], v[150:153], v[174:177], v[22:25]
	v_mfma_f32_16x16x32_bf16 v[18:21], v[158:161], v[174:177], v[18:21]
	v_mfma_f32_16x16x32_bf16 v[14:17], v[150:153], v[194:197], v[14:17]
	v_mfma_f32_16x16x32_bf16 v[10:13], v[158:161], v[194:197], v[10:13]
	v_mfma_f32_16x16x32_bf16 v[6:9], v[150:153], v[202:205], v[6:9]
	v_mfma_f32_16x16x32_bf16 v[2:5], v[158:161], v[202:205], v[2:5]
	v_mfma_f32_16x16x32_bf16 v[34:37], v[154:157], v[170:173], v[34:37]
	v_mfma_f32_16x16x32_bf16 v[26:29], v[162:165], v[170:173], v[26:29]
	v_mfma_f32_16x16x32_bf16 v[22:25], v[154:157], v[190:193], v[22:25]
	v_mfma_f32_16x16x32_bf16 v[18:21], v[162:165], v[190:193], v[18:21]
	v_mfma_f32_16x16x32_bf16 v[14:17], v[154:157], v[198:201], v[14:17]
	v_mfma_f32_16x16x32_bf16 v[10:13], v[162:165], v[198:201], v[10:13]
	v_mfma_f32_16x16x32_bf16 v[6:9], v[154:157], v[206:209], v[6:9]
	v_mfma_f32_16x16x32_bf16 v[2:5], v[162:165], v[206:209], v[2:5]
	s_barrier
	v_add_u32_e32 v162, 0x18000, v146
	ds_read_b128 v[150:153], v162
	ds_read_b128 v[154:157], v162 offset:1024
	ds_read_b128 v[158:161], v162 offset:2048
	ds_read_b128 v[162:165], v162 offset:3072
	s_add_u32 s56, s22, 0x40000
	s_addc_u32 s57, s23, 0
	s_add_i32 s55, s58, s35
	s_mov_b32 m0, s55
	s_nop 0
	global_load_lds_dwordx4 v134, s[56:57]
	s_add_i32 m0, s55, 0x2000
	s_nop 0
	global_load_lds_dwordx4 v130, s[56:57]
	s_waitcnt vmcnt(6)
	s_barrier
	v_mfma_f32_16x16x32_bf16 v[94:97], v[210:213], v[166:169], v[94:97]
	v_mfma_f32_16x16x32_bf16 v[90:93], v[218:221], v[166:169], v[90:93]
	v_mfma_f32_16x16x32_bf16 v[70:73], v[210:213], v[174:177], v[70:73]
	v_mfma_f32_16x16x32_bf16 v[66:69], v[218:221], v[174:177], v[66:69]
	v_mfma_f32_16x16x32_bf16 v[46:49], v[210:213], v[194:197], v[46:49]
	v_mfma_f32_16x16x32_bf16 v[42:45], v[218:221], v[194:197], v[42:45]
	v_mfma_f32_16x16x32_bf16 v[38:41], v[210:213], v[202:205], v[38:41]
	v_mfma_f32_16x16x32_bf16 v[30:33], v[218:221], v[202:205], v[30:33]
	v_mfma_f32_16x16x32_bf16 v[94:97], v[214:217], v[170:173], v[94:97]
	v_mfma_f32_16x16x32_bf16 v[90:93], v[222:225], v[170:173], v[90:93]
	v_mfma_f32_16x16x32_bf16 v[70:73], v[214:217], v[190:193], v[70:73]
	v_mfma_f32_16x16x32_bf16 v[66:69], v[222:225], v[190:193], v[66:69]
	v_mfma_f32_16x16x32_bf16 v[46:49], v[214:217], v[198:201], v[46:49]
	v_mfma_f32_16x16x32_bf16 v[42:45], v[222:225], v[198:201], v[42:45]
	v_mfma_f32_16x16x32_bf16 v[38:41], v[214:217], v[206:209], v[38:41]
	v_mfma_f32_16x16x32_bf16 v[30:33], v[222:225], v[206:209], v[30:33]
	s_barrier
	s_add_i32 s55, 0, 0x18000
	v_add_u32_e32 v149, s55, v146
	s_add_u32 s24, s24, 0x40000
	s_addc_u32 s25, s25, 0
	s_mov_b32 m0, s43
	ds_read_b128 v[166:169], v148 offset:32768
	ds_read_b128 v[170:173], v148 offset:33792
	ds_read_b128 v[174:177], v148 offset:34816
	ds_read_b128 v[190:193], v148 offset:35840
	ds_read_b128 v[194:197], v148 offset:36864
	ds_read_b128 v[198:201], v148 offset:37888
	ds_read_b128 v[202:205], v148 offset:38912
	ds_read_b128 v[206:209], v148 offset:39936
	global_load_lds_dwordx4 v136, s[24:25]
	s_mov_b32 m0, s44
	s_nop 0
	global_load_lds_dwordx4 v132, s[24:25]
	s_waitcnt lgkmcnt(8)
	s_barrier
	s_waitcnt lgkmcnt(0)
	s_waitcnt lgkmcnt(0)
	v_mfma_f32_16x16x32_bf16 v[86:89], v[150:153], v[166:169], v[86:89]
	v_mfma_f32_16x16x32_bf16 v[82:85], v[158:161], v[166:169], v[82:85]
	v_mfma_f32_16x16x32_bf16 v[78:81], v[150:153], v[174:177], v[78:81]
	v_mfma_f32_16x16x32_bf16 v[74:77], v[158:161], v[174:177], v[74:77]
	v_mfma_f32_16x16x32_bf16 v[62:65], v[150:153], v[194:197], v[62:65]
	v_mfma_f32_16x16x32_bf16 v[58:61], v[158:161], v[194:197], v[58:61]
	v_mfma_f32_16x16x32_bf16 v[54:57], v[150:153], v[202:205], v[54:57]
	v_mfma_f32_16x16x32_bf16 v[50:53], v[158:161], v[202:205], v[50:53]
	v_mfma_f32_16x16x32_bf16 v[86:89], v[154:157], v[170:173], v[86:89]
	v_mfma_f32_16x16x32_bf16 v[82:85], v[162:165], v[170:173], v[82:85]
	v_mfma_f32_16x16x32_bf16 v[78:81], v[154:157], v[190:193], v[78:81]
	v_mfma_f32_16x16x32_bf16 v[74:77], v[162:165], v[190:193], v[74:77]
	v_mfma_f32_16x16x32_bf16 v[62:65], v[154:157], v[198:201], v[62:65]
	v_mfma_f32_16x16x32_bf16 v[58:61], v[162:165], v[198:201], v[58:61]
	v_mfma_f32_16x16x32_bf16 v[54:57], v[154:157], v[206:209], v[54:57]
	v_mfma_f32_16x16x32_bf16 v[50:53], v[162:165], v[206:209], v[50:53]
	s_barrier
	s_add_i32 s24, 0, 0x1c000
	s_add_i32 s25, s55, s35
	v_add_u32_e32 v149, s24, v146
	s_mov_b32 m0, s25
	ds_read_b128 v[210:213], v149
	ds_read_b128 v[214:217], v149 offset:1024
	ds_read_b128 v[218:221], v149 offset:2048
	ds_read_b128 v[222:225], v149 offset:3072
	global_load_lds_dwordx4 v134, s[64:65]
	s_add_i32 m0, s25, 0x2000
	s_nop 0
	global_load_lds_dwordx4 v130, s[64:65]
	s_barrier
	s_waitcnt lgkmcnt(0)
	s_waitcnt lgkmcnt(0)
	v_mfma_f32_16x16x32_bf16 v[126:129], v[210:213], v[166:169], v[126:129]
	v_mfma_f32_16x16x32_bf16 v[122:125], v[218:221], v[166:169], v[122:125]
	v_mfma_f32_16x16x32_bf16 v[118:121], v[210:213], v[174:177], v[118:121]
	v_mfma_f32_16x16x32_bf16 v[114:117], v[218:221], v[174:177], v[114:117]
	v_mfma_f32_16x16x32_bf16 v[110:113], v[210:213], v[194:197], v[110:113]
	v_mfma_f32_16x16x32_bf16 v[106:109], v[218:221], v[194:197], v[106:109]
	v_mfma_f32_16x16x32_bf16 v[102:105], v[210:213], v[202:205], v[102:105]
	v_mfma_f32_16x16x32_bf16 v[98:101], v[218:221], v[202:205], v[98:101]
	v_mfma_f32_16x16x32_bf16 v[126:129], v[214:217], v[170:173], v[126:129]
	v_mfma_f32_16x16x32_bf16 v[122:125], v[222:225], v[170:173], v[122:125]
	v_mfma_f32_16x16x32_bf16 v[118:121], v[214:217], v[190:193], v[118:121]
	v_mfma_f32_16x16x32_bf16 v[114:117], v[222:225], v[190:193], v[114:117]
	v_mfma_f32_16x16x32_bf16 v[110:113], v[214:217], v[198:201], v[110:113]
	v_mfma_f32_16x16x32_bf16 v[106:109], v[222:225], v[198:201], v[106:109]
	v_mfma_f32_16x16x32_bf16 v[102:105], v[214:217], v[206:209], v[102:105]
	v_mfma_f32_16x16x32_bf16 v[98:101], v[222:225], v[206:209], v[98:101]
	s_barrier
	s_mov_b32 m0, s46
	ds_read_b128 v[166:169], v148 offset:49152
	ds_read_b128 v[170:173], v148 offset:50176
	ds_read_b128 v[174:177], v148 offset:51200
	ds_read_b128 v[190:193], v148 offset:52224
	ds_read_b128 v[194:197], v148 offset:53248
	ds_read_b128 v[198:201], v148 offset:54272
	ds_read_b128 v[202:205], v148 offset:55296
	ds_read_b128 v[206:209], v148 offset:56320
	global_load_lds_dwordx4 v136, s[62:63]
	s_mov_b32 m0, s47
	s_nop 0
	global_load_lds_dwordx4 v132, s[62:63]
	s_waitcnt vmcnt(10)
	s_barrier
	s_waitcnt lgkmcnt(0)
	s_waitcnt lgkmcnt(0)
	v_mfma_f32_16x16x32_bf16 v[34:37], v[150:153], v[166:169], v[34:37]
	v_mfma_f32_16x16x32_bf16 v[26:29], v[158:161], v[166:169], v[26:29]
	v_mfma_f32_16x16x32_bf16 v[22:25], v[150:153], v[174:177], v[22:25]
	v_mfma_f32_16x16x32_bf16 v[18:21], v[158:161], v[174:177], v[18:21]
	v_mfma_f32_16x16x32_bf16 v[14:17], v[150:153], v[194:197], v[14:17]
	v_mfma_f32_16x16x32_bf16 v[10:13], v[158:161], v[194:197], v[10:13]
	v_mfma_f32_16x16x32_bf16 v[6:9], v[150:153], v[202:205], v[6:9]
	v_mfma_f32_16x16x32_bf16 v[2:5], v[158:161], v[202:205], v[2:5]
	v_mfma_f32_16x16x32_bf16 v[34:37], v[154:157], v[170:173], v[34:37]
	v_mfma_f32_16x16x32_bf16 v[26:29], v[162:165], v[170:173], v[26:29]
	v_mfma_f32_16x16x32_bf16 v[22:25], v[154:157], v[190:193], v[22:25]
	v_mfma_f32_16x16x32_bf16 v[18:21], v[162:165], v[190:193], v[18:21]
	v_mfma_f32_16x16x32_bf16 v[14:17], v[154:157], v[198:201], v[14:17]
	v_mfma_f32_16x16x32_bf16 v[10:13], v[162:165], v[198:201], v[10:13]
	v_mfma_f32_16x16x32_bf16 v[6:9], v[154:157], v[206:209], v[6:9]
	v_mfma_f32_16x16x32_bf16 v[2:5], v[162:165], v[206:209], v[2:5]
	s_barrier
	v_add_u32_e32 v162, 0x10000, v146
	ds_read_b128 v[150:153], v162
	ds_read_b128 v[154:157], v162 offset:1024
	ds_read_b128 v[158:161], v162 offset:2048
	ds_read_b128 v[162:165], v162 offset:3072
	s_add_u32 s22, s22, 0x40080
	s_addc_u32 s23, s23, 0
	s_add_i32 s24, s24, s35
	s_mov_b32 m0, s24
	s_nop 0
	global_load_lds_dwordx4 v134, s[22:23]
	v_lshl_add_u64 v[144:145], s[22:23], 0, v[130:131]
	s_add_i32 m0, s24, 0x2000
	s_nop 0
	global_load_lds_dwordx4 v[144:145], off
	s_waitcnt vmcnt(6)
	s_barrier
	v_mfma_f32_16x16x32_bf16 v[94:97], v[210:213], v[166:169], v[94:97]
	v_mfma_f32_16x16x32_bf16 v[90:93], v[218:221], v[166:169], v[90:93]
	v_mfma_f32_16x16x32_bf16 v[70:73], v[210:213], v[174:177], v[70:73]
	v_mfma_f32_16x16x32_bf16 v[66:69], v[218:221], v[174:177], v[66:69]
	v_mfma_f32_16x16x32_bf16 v[46:49], v[210:213], v[194:197], v[46:49]
	v_mfma_f32_16x16x32_bf16 v[42:45], v[218:221], v[194:197], v[42:45]
	v_mfma_f32_16x16x32_bf16 v[38:41], v[210:213], v[202:205], v[38:41]
	v_mfma_f32_16x16x32_bf16 v[30:33], v[218:221], v[202:205], v[30:33]
	v_mfma_f32_16x16x32_bf16 v[94:97], v[214:217], v[170:173], v[94:97]
	v_mfma_f32_16x16x32_bf16 v[90:93], v[222:225], v[170:173], v[90:93]
	v_mfma_f32_16x16x32_bf16 v[70:73], v[214:217], v[190:193], v[70:73]
	v_mfma_f32_16x16x32_bf16 v[66:69], v[222:225], v[190:193], v[66:69]
	v_mfma_f32_16x16x32_bf16 v[46:49], v[214:217], v[198:201], v[46:49]
	v_mfma_f32_16x16x32_bf16 v[42:45], v[222:225], v[198:201], v[42:45]
	v_mfma_f32_16x16x32_bf16 v[38:41], v[214:217], v[206:209], v[38:41]
	v_mfma_f32_16x16x32_bf16 v[30:33], v[222:225], v[206:209], v[30:33]
	s_barrier
	s_add_i32 s54, s54, 2
	s_add_u32 s20, s20, 0x100
	s_addc_u32 s21, s21, 0
	s_add_u32 s52, s52, 0x100
	s_addc_u32 s53, s53, 0
	s_cmp_gt_u32 s54, 13
	s_cbranch_scc0 .LBB0_528
	s_waitcnt lgkmcnt(0)
	v_lshl_add_u32 v144, s10, 8, v1
	s_cmp_lg_u32 s50, s45
	s_mov_b64 s[10:11], -1
	s_cbranch_scc0 .LBB0_531
	v_lshl_or_b32 v154, s50, 8, v147
	v_readlane_b32 s13, v255, 32
	v_ashrrev_i32_e32 v155, 31, v154
	v_lshlrev_b64 v[154:155], 1, v[154:155]
	v_mad_i64_i32 v[156:157], s[10:11], v144, s13, 0
	v_lshl_add_u64 v[156:157], v[156:157], 1, s[6:7]
	v_lshl_add_u64 v[156:157], v[156:157], 0, v[154:155]
	v_cvt_pk_bf16_f32 v126, v126, v127
	v_cvt_pk_bf16_f32 v127, v128, v129
	v_cvt_pk_bf16_f32 v128, v122, v123
	v_cvt_pk_bf16_f32 v129, v124, v125
	global_store_dwordx4 v[156:157], v[126:129], off offset:256
	v_cvt_pk_bf16_f32 v150, v86, v87
	v_cvt_pk_bf16_f32 v151, v88, v89
	v_or_b32_e32 v126, 16, v144
	v_mad_i64_i32 v[126:127], s[10:11], v126, s13, 0
	v_lshl_add_u64 v[126:127], v[126:127], 1, s[6:7]
	v_cvt_pk_bf16_f32 v152, v82, v83
	v_cvt_pk_bf16_f32 v153, v84, v85
	v_lshl_add_u64 v[126:127], v[126:127], 0, v[154:155]
	v_cvt_pk_bf16_f32 v118, v118, v119
	v_cvt_pk_bf16_f32 v119, v120, v121
	v_cvt_pk_bf16_f32 v120, v114, v115
	v_cvt_pk_bf16_f32 v121, v116, v117
	global_store_dwordx4 v[156:157], v[150:153], off
	global_store_dwordx4 v[126:127], v[118:121], off offset:256
	v_cvt_pk_bf16_f32 v122, v78, v79
	v_cvt_pk_bf16_f32 v123, v80, v81
	v_or_b32_e32 v118, 32, v144
	v_mad_i64_i32 v[118:119], s[10:11], v118, s13, 0
	v_lshl_add_u64 v[118:119], v[118:119], 1, s[6:7]
	v_cvt_pk_bf16_f32 v124, v74, v75
	v_cvt_pk_bf16_f32 v125, v76, v77
	v_lshl_add_u64 v[118:119], v[118:119], 0, v[154:155]
	v_cvt_pk_bf16_f32 v110, v110, v111
	v_cvt_pk_bf16_f32 v111, v112, v113
	v_cvt_pk_bf16_f32 v112, v106, v107
	v_cvt_pk_bf16_f32 v113, v108, v109
	global_store_dwordx4 v[126:127], v[122:125], off
	global_store_dwordx4 v[118:119], v[110:113], off offset:256
	v_cvt_pk_bf16_f32 v114, v62, v63
	v_cvt_pk_bf16_f32 v115, v64, v65
	v_or_b32_e32 v110, 48, v144
	v_mad_i64_i32 v[110:111], s[10:11], v110, s13, 0
	v_lshl_add_u64 v[110:111], v[110:111], 1, s[6:7]
	v_cvt_pk_bf16_f32 v116, v58, v59
	v_cvt_pk_bf16_f32 v117, v60, v61
	v_lshl_add_u64 v[110:111], v[110:111], 0, v[154:155]
	v_cvt_pk_bf16_f32 v102, v102, v103
	v_cvt_pk_bf16_f32 v103, v104, v105
	v_cvt_pk_bf16_f32 v104, v98, v99
	v_cvt_pk_bf16_f32 v105, v100, v101
	global_store_dwordx4 v[118:119], v[114:117], off
	global_store_dwordx4 v[110:111], v[102:105], off offset:256
	v_cvt_pk_bf16_f32 v106, v54, v55
	v_cvt_pk_bf16_f32 v107, v56, v57
	v_add_u32_e32 v102, 0x80, v144
	v_mad_i64_i32 v[102:103], s[10:11], v102, s13, 0
	v_lshl_add_u64 v[102:103], v[102:103], 1, s[6:7]
	v_cvt_pk_bf16_f32 v108, v50, v51
	v_cvt_pk_bf16_f32 v109, v52, v53
	v_lshl_add_u64 v[102:103], v[102:103], 0, v[154:155]
	v_cvt_pk_bf16_f32 v94, v94, v95
	v_cvt_pk_bf16_f32 v95, v96, v97
	v_cvt_pk_bf16_f32 v96, v90, v91
	v_cvt_pk_bf16_f32 v97, v92, v93
	global_store_dwordx4 v[110:111], v[106:109], off
	global_store_dwordx4 v[102:103], v[94:97], off offset:256
	v_cvt_pk_bf16_f32 v98, v34, v35
	v_cvt_pk_bf16_f32 v99, v36, v37
	v_add_u32_e32 v94, 0x90, v144
	v_mad_i64_i32 v[94:95], s[10:11], v94, s13, 0
	v_lshl_add_u64 v[94:95], v[94:95], 1, s[6:7]
	v_cvt_pk_bf16_f32 v100, v26, v27
	v_cvt_pk_bf16_f32 v101, v28, v29
	v_lshl_add_u64 v[94:95], v[94:95], 0, v[154:155]
	v_cvt_pk_bf16_f32 v70, v70, v71
	v_cvt_pk_bf16_f32 v71, v72, v73
	v_cvt_pk_bf16_f32 v72, v66, v67
	v_cvt_pk_bf16_f32 v73, v68, v69
	global_store_dwordx4 v[102:103], v[98:101], off
	global_store_dwordx4 v[94:95], v[70:73], off offset:256
	v_cvt_pk_bf16_f32 v90, v22, v23
	v_cvt_pk_bf16_f32 v91, v24, v25
	v_add_u32_e32 v70, 0xa0, v144
	v_mad_i64_i32 v[70:71], s[10:11], v70, s13, 0
	v_lshl_add_u64 v[70:71], v[70:71], 1, s[6:7]
	v_cvt_pk_bf16_f32 v92, v18, v19
	v_cvt_pk_bf16_f32 v93, v20, v21
	v_lshl_add_u64 v[70:71], v[70:71], 0, v[154:155]
	v_cvt_pk_bf16_f32 v46, v46, v47
	v_cvt_pk_bf16_f32 v47, v48, v49
	v_cvt_pk_bf16_f32 v48, v42, v43
	v_cvt_pk_bf16_f32 v49, v44, v45
	global_store_dwordx4 v[94:95], v[90:93], off
	global_store_dwordx4 v[70:71], v[46:49], off offset:256
	v_cvt_pk_bf16_f32 v66, v14, v15
	v_cvt_pk_bf16_f32 v67, v16, v17
	v_add_u32_e32 v46, 0xb0, v144
	v_mad_i64_i32 v[46:47], s[10:11], v46, s13, 0
	v_lshl_add_u64 v[46:47], v[46:47], 1, s[6:7]
	v_cvt_pk_bf16_f32 v68, v10, v11
	v_cvt_pk_bf16_f32 v69, v12, v13
	v_cvt_pk_bf16_f32 v42, v6, v7
	v_cvt_pk_bf16_f32 v43, v8, v9
	v_cvt_pk_bf16_f32 v44, v2, v3
	v_cvt_pk_bf16_f32 v45, v4, v5
	v_lshl_add_u64 v[46:47], v[46:47], 0, v[154:155]
	v_cvt_pk_bf16_f32 v38, v38, v39
	v_cvt_pk_bf16_f32 v39, v40, v41
	v_cvt_pk_bf16_f32 v40, v30, v31
	v_cvt_pk_bf16_f32 v41, v32, v33
	global_store_dwordx4 v[70:71], v[66:69], off
	global_store_dwordx4 v[46:47], v[42:45], off
	global_store_dwordx4 v[46:47], v[38:41], off offset:256
	s_mov_b64 s[10:11], 0

.LBB0_1407:
	s_ashr_i32 s3, s2, 31
	s_lshl_b64 s[12:13], s[2:3], 20
	s_add_u32 s12, s24, s12
	s_addc_u32 s13, s25, s13
	s_and_b64 s[6:7], s[6:7], exec
	s_cselect_b32 s3, s13, s17
	s_cselect_b32 s44, s12, s16
	s_add_u32 s45, s16, 0x100
	s_addc_u32 s46, s17, 0
	s_add_u32 s6, s14, 0x80
	s_addc_u32 s7, s15, 0
	v_lshl_add_u64 v[142:143], s[6:7], 0, v[138:139]
	v_lshl_add_u64 v[144:145], s[6:7], 0, v[140:141]
	s_mov_b32 s47, -2
	s_mov_b64 s[6:7], 0
	s_add_u32 s16, s14, s6
	s_addc_u32 s17, s15, s7
	s_add_u32 s16, s16, 0x100
	s_addc_u32 s17, s17, 0
	s_add_u32 s48, s45, s6
	s_addc_u32 s49, s46, s7
	s_add_i32 s50, 0, 0x10000
	v_add_u32_e32 v158, s50, v164
	ds_read_b128 v[146:149], v158
	ds_read_b128 v[150:153], v158 offset:1024
	ds_read_b128 v[154:157], v158 offset:2048
	ds_read_b128 v[158:161], v158 offset:3072
	s_cmpk_eq_i32 s6, 0xf00
	s_cselect_b32 s19, s11, s17
	s_cselect_b32 s18, s10, s16
	s_cselect_b32 s17, s3, s49
	s_cselect_b32 s16, s44, s48
	v_lshl_add_u64 v[162:163], v[142:143], 0, s[6:7]
	s_add_i32 m0, s30, 0xc000
	ds_read_b128 v[168:171], v166
	ds_read_b128 v[172:175], v166 offset:1024
	ds_read_b128 v[186:189], v166 offset:2048
	ds_read_b128 v[190:193], v166 offset:3072
	ds_read_b128 v[194:197], v166 offset:4096
	ds_read_b128 v[198:201], v166 offset:5120
	ds_read_b128 v[202:205], v166 offset:6144
	ds_read_b128 v[206:209], v166 offset:7168
	global_load_lds_dwordx4 v[162:163], off
	v_lshl_add_u64 v[162:163], v[144:145], 0, s[6:7]
	s_add_i32 m0, s30, 0xe000
	s_nop 0
	global_load_lds_dwordx4 v[162:163], off
	s_waitcnt lgkmcnt(8)
	s_barrier
	s_waitcnt lgkmcnt(0)
	s_waitcnt lgkmcnt(0)
	v_mfma_f32_16x16x32_bf16 v[126:129], v[146:149], v[168:171], 0
	v_mfma_f32_16x16x32_bf16 v[122:125], v[154:157], v[168:171], 0
	v_mfma_f32_16x16x32_bf16 v[110:113], v[146:149], v[186:189], 0
	v_mfma_f32_16x16x32_bf16 v[106:109], v[154:157], v[186:189], 0
	v_mfma_f32_16x16x32_bf16 v[94:97], v[146:149], v[194:197], 0
	v_mfma_f32_16x16x32_bf16 v[90:93], v[154:157], v[194:197], 0
	v_mfma_f32_16x16x32_bf16 v[78:81], v[146:149], v[202:205], 0
	v_mfma_f32_16x16x32_bf16 v[74:77], v[154:157], v[202:205], 0
	v_mfma_f32_16x16x32_bf16 v[126:129], v[150:153], v[172:175], v[126:129]
	v_mfma_f32_16x16x32_bf16 v[122:125], v[158:161], v[172:175], v[122:125]
	v_mfma_f32_16x16x32_bf16 v[110:113], v[150:153], v[190:193], v[110:113]
	v_mfma_f32_16x16x32_bf16 v[106:109], v[158:161], v[190:193], v[106:109]
	v_mfma_f32_16x16x32_bf16 v[94:97], v[150:153], v[198:201], v[94:97]
	v_mfma_f32_16x16x32_bf16 v[90:93], v[158:161], v[198:201], v[90:93]
	v_mfma_f32_16x16x32_bf16 v[78:81], v[150:153], v[206:209], v[78:81]
	v_mfma_f32_16x16x32_bf16 v[74:77], v[158:161], v[206:209], v[74:77]
	s_barrier
	s_add_i32 s51, 0, 0x14000
	v_add_u32_e32 v162, s51, v164
	s_add_i32 s48, s50, s29
	ds_read_b128 v[210:213], v162
	ds_read_b128 v[214:217], v162 offset:1024
	ds_read_b128 v[218:221], v162 offset:2048
	ds_read_b128 v[222:225], v162 offset:3072
	s_add_u32 s64, s16, 0x80
	s_addc_u32 s65, s17, 0
	s_mov_b32 m0, s48
	s_nop 0
	global_load_lds_dwordx4 v132, s[16:17]
	s_add_i32 m0, s48, 0x2000
	s_nop 0
	global_load_lds_dwordx4 v136, s[16:17]
	s_barrier
	s_waitcnt lgkmcnt(0)
	s_waitcnt lgkmcnt(0)
	v_mfma_f32_16x16x32_bf16 v[118:121], v[210:213], v[168:171], 0
	v_mfma_f32_16x16x32_bf16 v[114:117], v[218:221], v[168:171], 0
	v_mfma_f32_16x16x32_bf16 v[102:105], v[210:213], v[186:189], 0
	v_mfma_f32_16x16x32_bf16 v[98:101], v[218:221], v[186:189], 0
	v_mfma_f32_16x16x32_bf16 v[86:89], v[210:213], v[194:197], 0
	v_mfma_f32_16x16x32_bf16 v[82:85], v[218:221], v[194:197], 0
	v_mfma_f32_16x16x32_bf16 v[70:73], v[210:213], v[202:205], 0
	v_mfma_f32_16x16x32_bf16 v[66:69], v[218:221], v[202:205], 0
	v_mfma_f32_16x16x32_bf16 v[118:121], v[214:217], v[172:175], v[118:121]
	v_mfma_f32_16x16x32_bf16 v[114:117], v[222:225], v[172:175], v[114:117]
	v_mfma_f32_16x16x32_bf16 v[102:105], v[214:217], v[190:193], v[102:105]
	v_mfma_f32_16x16x32_bf16 v[98:101], v[222:225], v[190:193], v[98:101]
	v_mfma_f32_16x16x32_bf16 v[86:89], v[214:217], v[198:201], v[86:89]
	v_mfma_f32_16x16x32_bf16 v[82:85], v[222:225], v[198:201], v[82:85]
	v_mfma_f32_16x16x32_bf16 v[70:73], v[214:217], v[206:209], v[70:73]
	v_mfma_f32_16x16x32_bf16 v[66:69], v[222:225], v[206:209], v[66:69]
	s_barrier
	s_mov_b32 m0, s30
	s_add_u32 s62, s18, 0x80
	s_addc_u32 s63, s19, 0
	ds_read_b128 v[168:171], v166 offset:16384
	ds_read_b128 v[172:175], v166 offset:17408
	ds_read_b128 v[186:189], v166 offset:18432
	ds_read_b128 v[190:193], v166 offset:19456
	ds_read_b128 v[194:197], v166 offset:20480
	ds_read_b128 v[198:201], v166 offset:21504
	ds_read_b128 v[202:205], v166 offset:22528
	ds_read_b128 v[206:209], v166 offset:23552
	global_load_lds_dwordx4 v130, s[18:19]
	s_mov_b32 m0, s31
	s_nop 0
	global_load_lds_dwordx4 v134, s[18:19]
	s_waitcnt vmcnt(10)
	s_barrier
	s_waitcnt lgkmcnt(0)
	s_waitcnt lgkmcnt(0)
	v_mfma_f32_16x16x32_bf16 v[62:65], v[146:149], v[168:171], 0
	v_mfma_f32_16x16x32_bf16 v[58:61], v[154:157], v[168:171], 0
	v_mfma_f32_16x16x32_bf16 v[46:49], v[146:149], v[186:189], 0
	v_mfma_f32_16x16x32_bf16 v[42:45], v[154:157], v[186:189], 0
	v_mfma_f32_16x16x32_bf16 v[30:33], v[146:149], v[194:197], 0
	v_mfma_f32_16x16x32_bf16 v[26:29], v[154:157], v[194:197], 0
	v_mfma_f32_16x16x32_bf16 v[14:17], v[146:149], v[202:205], 0
	v_mfma_f32_16x16x32_bf16 v[10:13], v[154:157], v[202:205], 0
	v_mfma_f32_16x16x32_bf16 v[62:65], v[150:153], v[172:175], v[62:65]
	v_mfma_f32_16x16x32_bf16 v[58:61], v[158:161], v[172:175], v[58:61]
	v_mfma_f32_16x16x32_bf16 v[46:49], v[150:153], v[190:193], v[46:49]
	v_mfma_f32_16x16x32_bf16 v[42:45], v[158:161], v[190:193], v[42:45]
	v_mfma_f32_16x16x32_bf16 v[30:33], v[150:153], v[198:201], v[30:33]
	v_mfma_f32_16x16x32_bf16 v[26:29], v[158:161], v[198:201], v[26:29]
	v_mfma_f32_16x16x32_bf16 v[14:17], v[150:153], v[206:209], v[14:17]
	v_mfma_f32_16x16x32_bf16 v[10:13], v[158:161], v[206:209], v[10:13]
	s_barrier
	v_add_u32_e32 v158, 0x18000, v164
	ds_read_b128 v[146:149], v158
	ds_read_b128 v[150:153], v158 offset:1024
	ds_read_b128 v[154:157], v158 offset:2048
	ds_read_b128 v[158:161], v158 offset:3072
	s_add_u32 s48, s16, 0x80000
	s_addc_u32 s49, s17, 0
	s_add_i32 s50, s51, s29
	s_mov_b32 m0, s50
	s_nop 0
	global_load_lds_dwordx4 v132, s[48:49]
	s_add_i32 m0, s50, 0x2000
	s_nop 0
	global_load_lds_dwordx4 v136, s[48:49]
	s_waitcnt vmcnt(6)
	s_barrier
	v_mfma_f32_16x16x32_bf16 v[54:57], v[210:213], v[168:171], 0
	v_mfma_f32_16x16x32_bf16 v[50:53], v[218:221], v[168:171], 0
	v_mfma_f32_16x16x32_bf16 v[38:41], v[210:213], v[186:189], 0
	v_mfma_f32_16x16x32_bf16 v[34:37], v[218:221], v[186:189], 0
	v_mfma_f32_16x16x32_bf16 v[22:25], v[210:213], v[194:197], 0
	v_mfma_f32_16x16x32_bf16 v[18:21], v[218:221], v[194:197], 0
	v_mfma_f32_16x16x32_bf16 v[6:9], v[210:213], v[202:205], 0
	v_mfma_f32_16x16x32_bf16 v[2:5], v[218:221], v[202:205], 0
	v_mfma_f32_16x16x32_bf16 v[54:57], v[214:217], v[172:175], v[54:57]
	v_mfma_f32_16x16x32_bf16 v[50:53], v[222:225], v[172:175], v[50:53]
	v_mfma_f32_16x16x32_bf16 v[38:41], v[214:217], v[190:193], v[38:41]
	v_mfma_f32_16x16x32_bf16 v[34:37], v[222:225], v[190:193], v[34:37]
	v_mfma_f32_16x16x32_bf16 v[22:25], v[214:217], v[198:201], v[22:25]
	v_mfma_f32_16x16x32_bf16 v[18:21], v[222:225], v[198:201], v[18:21]
	v_mfma_f32_16x16x32_bf16 v[6:9], v[214:217], v[206:209], v[6:9]
	v_mfma_f32_16x16x32_bf16 v[2:5], v[222:225], v[206:209], v[2:5]
	s_barrier
	s_add_i32 s48, 0, 0x18000
	s_add_u32 s18, s18, s80
	s_addc_u32 s19, s19, 0
	s_mov_b32 m0, s34
	ds_read_b128 v[168:171], v166 offset:32768
	ds_read_b128 v[172:175], v166 offset:33792
	ds_read_b128 v[186:189], v166 offset:34816
	ds_read_b128 v[190:193], v166 offset:35840
	ds_read_b128 v[194:197], v166 offset:36864
	ds_read_b128 v[198:201], v166 offset:37888
	ds_read_b128 v[202:205], v166 offset:38912
	ds_read_b128 v[206:209], v166 offset:39936
	global_load_lds_dwordx4 v130, s[18:19]
	s_mov_b32 m0, s35
	s_nop 0
	global_load_lds_dwordx4 v134, s[18:19]
	s_waitcnt lgkmcnt(8)
	s_barrier
	s_waitcnt lgkmcnt(0)
	s_waitcnt lgkmcnt(0)
	v_mfma_f32_16x16x32_bf16 v[126:129], v[146:149], v[168:171], v[126:129]
	v_mfma_f32_16x16x32_bf16 v[122:125], v[154:157], v[168:171], v[122:125]
	v_mfma_f32_16x16x32_bf16 v[110:113], v[146:149], v[186:189], v[110:113]
	v_mfma_f32_16x16x32_bf16 v[106:109], v[154:157], v[186:189], v[106:109]
	v_mfma_f32_16x16x32_bf16 v[94:97], v[146:149], v[194:197], v[94:97]
	v_mfma_f32_16x16x32_bf16 v[90:93], v[154:157], v[194:197], v[90:93]
	v_mfma_f32_16x16x32_bf16 v[78:81], v[146:149], v[202:205], v[78:81]
	v_mfma_f32_16x16x32_bf16 v[74:77], v[154:157], v[202:205], v[74:77]
	v_mfma_f32_16x16x32_bf16 v[126:129], v[150:153], v[172:175], v[126:129]
	v_mfma_f32_16x16x32_bf16 v[122:125], v[158:161], v[172:175], v[122:125]
	v_mfma_f32_16x16x32_bf16 v[110:113], v[150:153], v[190:193], v[110:113]
	v_mfma_f32_16x16x32_bf16 v[106:109], v[158:161], v[190:193], v[106:109]
	v_mfma_f32_16x16x32_bf16 v[94:97], v[150:153], v[198:201], v[94:97]
	v_mfma_f32_16x16x32_bf16 v[90:93], v[158:161], v[198:201], v[90:93]
	v_mfma_f32_16x16x32_bf16 v[78:81], v[150:153], v[206:209], v[78:81]
	v_mfma_f32_16x16x32_bf16 v[74:77], v[158:161], v[206:209], v[74:77]
	s_barrier
	s_add_i32 s18, 0, 0x1c000
	s_add_i32 s19, s48, s29
	v_add_u32_e32 v167, s18, v164
	s_mov_b32 m0, s19
	ds_read_b128 v[210:213], v167
	ds_read_b128 v[214:217], v167 offset:1024
	ds_read_b128 v[218:221], v167 offset:2048
	ds_read_b128 v[222:225], v167 offset:3072
	global_load_lds_dwordx4 v132, s[64:65]
	s_add_i32 m0, s19, 0x2000
	s_nop 0
	global_load_lds_dwordx4 v136, s[64:65]
	s_barrier
	s_waitcnt lgkmcnt(0)
	s_waitcnt lgkmcnt(0)
	v_mfma_f32_16x16x32_bf16 v[118:121], v[210:213], v[168:171], v[118:121]
	v_mfma_f32_16x16x32_bf16 v[114:117], v[218:221], v[168:171], v[114:117]
	v_mfma_f32_16x16x32_bf16 v[102:105], v[210:213], v[186:189], v[102:105]
	v_mfma_f32_16x16x32_bf16 v[98:101], v[218:221], v[186:189], v[98:101]
	v_mfma_f32_16x16x32_bf16 v[86:89], v[210:213], v[194:197], v[86:89]
	v_mfma_f32_16x16x32_bf16 v[82:85], v[218:221], v[194:197], v[82:85]
	v_mfma_f32_16x16x32_bf16 v[70:73], v[210:213], v[202:205], v[70:73]
	v_mfma_f32_16x16x32_bf16 v[66:69], v[218:221], v[202:205], v[66:69]
	v_mfma_f32_16x16x32_bf16 v[118:121], v[214:217], v[172:175], v[118:121]
	v_mfma_f32_16x16x32_bf16 v[114:117], v[222:225], v[172:175], v[114:117]
	v_mfma_f32_16x16x32_bf16 v[102:105], v[214:217], v[190:193], v[102:105]
	v_mfma_f32_16x16x32_bf16 v[98:101], v[222:225], v[190:193], v[98:101]
	v_mfma_f32_16x16x32_bf16 v[86:89], v[214:217], v[198:201], v[86:89]
	v_mfma_f32_16x16x32_bf16 v[82:85], v[222:225], v[198:201], v[82:85]
	v_mfma_f32_16x16x32_bf16 v[70:73], v[214:217], v[206:209], v[70:73]
	v_mfma_f32_16x16x32_bf16 v[66:69], v[222:225], v[206:209], v[66:69]
	s_barrier
	s_mov_b32 m0, s38
	ds_read_b128 v[168:171], v166 offset:49152
	ds_read_b128 v[172:175], v166 offset:50176
	ds_read_b128 v[186:189], v166 offset:51200
	ds_read_b128 v[190:193], v166 offset:52224
	ds_read_b128 v[194:197], v166 offset:53248
	ds_read_b128 v[198:201], v166 offset:54272
	ds_read_b128 v[202:205], v166 offset:55296
	ds_read_b128 v[206:209], v166 offset:56320
	global_load_lds_dwordx4 v130, s[62:63]
	s_mov_b32 m0, s39
	s_nop 0
	global_load_lds_dwordx4 v134, s[62:63]
	s_waitcnt vmcnt(10)
	s_barrier
	s_waitcnt lgkmcnt(0)
	s_waitcnt lgkmcnt(0)
	v_mfma_f32_16x16x32_bf16 v[62:65], v[146:149], v[168:171], v[62:65]
	v_mfma_f32_16x16x32_bf16 v[58:61], v[154:157], v[168:171], v[58:61]
	v_mfma_f32_16x16x32_bf16 v[46:49], v[146:149], v[186:189], v[46:49]
	v_mfma_f32_16x16x32_bf16 v[42:45], v[154:157], v[186:189], v[42:45]
	v_mfma_f32_16x16x32_bf16 v[30:33], v[146:149], v[194:197], v[30:33]
	v_mfma_f32_16x16x32_bf16 v[26:29], v[154:157], v[194:197], v[26:29]
	v_mfma_f32_16x16x32_bf16 v[14:17], v[146:149], v[202:205], v[14:17]
	v_mfma_f32_16x16x32_bf16 v[10:13], v[154:157], v[202:205], v[10:13]
	v_mfma_f32_16x16x32_bf16 v[62:65], v[150:153], v[172:175], v[62:65]
	v_mfma_f32_16x16x32_bf16 v[58:61], v[158:161], v[172:175], v[58:61]
	v_mfma_f32_16x16x32_bf16 v[46:49], v[150:153], v[190:193], v[46:49]
	v_mfma_f32_16x16x32_bf16 v[42:45], v[158:161], v[190:193], v[42:45]
	v_mfma_f32_16x16x32_bf16 v[30:33], v[150:153], v[198:201], v[30:33]
	v_mfma_f32_16x16x32_bf16 v[26:29], v[158:161], v[198:201], v[26:29]
	v_mfma_f32_16x16x32_bf16 v[14:17], v[150:153], v[206:209], v[14:17]
	v_mfma_f32_16x16x32_bf16 v[10:13], v[158:161], v[206:209], v[10:13]
	s_barrier
	v_add_u32_e32 v158, 0x10000, v164
	ds_read_b128 v[146:149], v158
	ds_read_b128 v[150:153], v158 offset:1024
	ds_read_b128 v[154:157], v158 offset:2048
	ds_read_b128 v[158:161], v158 offset:3072
	s_add_u32 s16, s16, 0x80080
	s_addc_u32 s17, s17, 0
	s_add_i32 s18, s18, s29
	s_mov_b32 m0, s18
	s_nop 0
	global_load_lds_dwordx4 v132, s[16:17]
	s_add_i32 m0, s18, 0x2000
	s_nop 0
	global_load_lds_dwordx4 v136, s[16:17]
	s_waitcnt vmcnt(6)
	s_barrier
	v_mfma_f32_16x16x32_bf16 v[54:57], v[210:213], v[168:171], v[54:57]
	v_mfma_f32_16x16x32_bf16 v[50:53], v[218:221], v[168:171], v[50:53]
	v_mfma_f32_16x16x32_bf16 v[38:41], v[210:213], v[186:189], v[38:41]
	v_mfma_f32_16x16x32_bf16 v[34:37], v[218:221], v[186:189], v[34:37]
	v_mfma_f32_16x16x32_bf16 v[22:25], v[210:213], v[194:197], v[22:25]
	v_mfma_f32_16x16x32_bf16 v[18:21], v[218:221], v[194:197], v[18:21]
	v_mfma_f32_16x16x32_bf16 v[6:9], v[210:213], v[202:205], v[6:9]
	v_mfma_f32_16x16x32_bf16 v[2:5], v[218:221], v[202:205], v[2:5]
	v_mfma_f32_16x16x32_bf16 v[54:57], v[214:217], v[172:175], v[54:57]
	v_mfma_f32_16x16x32_bf16 v[50:53], v[222:225], v[172:175], v[50:53]
	v_mfma_f32_16x16x32_bf16 v[38:41], v[214:217], v[190:193], v[38:41]
	v_mfma_f32_16x16x32_bf16 v[34:37], v[222:225], v[190:193], v[34:37]
	v_mfma_f32_16x16x32_bf16 v[22:25], v[214:217], v[198:201], v[22:25]
	v_mfma_f32_16x16x32_bf16 v[18:21], v[222:225], v[198:201], v[18:21]
	v_mfma_f32_16x16x32_bf16 v[6:9], v[214:217], v[206:209], v[6:9]
	v_mfma_f32_16x16x32_bf16 v[2:5], v[222:225], v[206:209], v[2:5]
	s_barrier
	s_add_i32 s47, s47, 2
	s_add_u32 s6, s6, 0x100
	s_addc_u32 s7, s7, 0
.LBB0_1408:
	s_add_u32 s16, s14, s6
	s_addc_u32 s17, s15, s7
	s_add_u32 s16, s16, 0x100
	s_addc_u32 s17, s17, 0
	s_add_u32 s48, s45, s6
	s_addc_u32 s49, s46, s7
	s_add_i32 s50, 0, 0x10000
	s_cmpk_eq_i32 s6, 0xf00
	s_cselect_b32 s19, s11, s17
	s_cselect_b32 s18, s10, s16
	s_cselect_b32 s17, s3, s49
	s_cselect_b32 s16, s44, s48
	v_lshl_add_u64 v[162:163], v[142:143], 0, s[6:7]
	s_add_i32 m0, s30, 0xc000
	ds_read_b128 v[168:171], v166
	ds_read_b128 v[172:175], v166 offset:1024
	ds_read_b128 v[186:189], v166 offset:2048
	ds_read_b128 v[190:193], v166 offset:3072
	ds_read_b128 v[194:197], v166 offset:4096
	ds_read_b128 v[198:201], v166 offset:5120
	ds_read_b128 v[202:205], v166 offset:6144
	ds_read_b128 v[206:209], v166 offset:7168
	global_load_lds_dwordx4 v[162:163], off
	v_lshl_add_u64 v[162:163], v[144:145], 0, s[6:7]
	s_add_i32 m0, s30, 0xe000
	s_nop 0
	global_load_lds_dwordx4 v[162:163], off
	s_waitcnt lgkmcnt(8)
	s_barrier
	s_waitcnt lgkmcnt(0)
	s_waitcnt lgkmcnt(0)
	v_mfma_f32_16x16x32_bf16 v[126:129], v[146:149], v[168:171], v[126:129]
	v_mfma_f32_16x16x32_bf16 v[122:125], v[154:157], v[168:171], v[122:125]
	v_mfma_f32_16x16x32_bf16 v[110:113], v[146:149], v[186:189], v[110:113]
	v_mfma_f32_16x16x32_bf16 v[106:109], v[154:157], v[186:189], v[106:109]
	v_mfma_f32_16x16x32_bf16 v[94:97], v[146:149], v[194:197], v[94:97]
	v_mfma_f32_16x16x32_bf16 v[90:93], v[154:157], v[194:197], v[90:93]
	v_mfma_f32_16x16x32_bf16 v[78:81], v[146:149], v[202:205], v[78:81]
	v_mfma_f32_16x16x32_bf16 v[74:77], v[154:157], v[202:205], v[74:77]
	v_mfma_f32_16x16x32_bf16 v[126:129], v[150:153], v[172:175], v[126:129]
	v_mfma_f32_16x16x32_bf16 v[122:125], v[158:161], v[172:175], v[122:125]
	v_mfma_f32_16x16x32_bf16 v[110:113], v[150:153], v[190:193], v[110:113]
	v_mfma_f32_16x16x32_bf16 v[106:109], v[158:161], v[190:193], v[106:109]
	v_mfma_f32_16x16x32_bf16 v[94:97], v[150:153], v[198:201], v[94:97]
	v_mfma_f32_16x16x32_bf16 v[90:93], v[158:161], v[198:201], v[90:93]
	v_mfma_f32_16x16x32_bf16 v[78:81], v[150:153], v[206:209], v[78:81]
	v_mfma_f32_16x16x32_bf16 v[74:77], v[158:161], v[206:209], v[74:77]
	s_barrier
	s_add_i32 s51, 0, 0x14000
	v_add_u32_e32 v162, s51, v164
	s_add_i32 s48, s50, s29
	ds_read_b128 v[210:213], v162
	ds_read_b128 v[214:217], v162 offset:1024
	ds_read_b128 v[218:221], v162 offset:2048
	ds_read_b128 v[222:225], v162 offset:3072
	s_add_u32 s64, s16, 0x80
	s_addc_u32 s65, s17, 0
	s_mov_b32 m0, s48
	s_nop 0
	global_load_lds_dwordx4 v132, s[16:17]
	s_add_i32 m0, s48, 0x2000
	s_nop 0
	global_load_lds_dwordx4 v136, s[16:17]
	s_barrier
	s_waitcnt lgkmcnt(0)
	s_waitcnt lgkmcnt(0)
	v_mfma_f32_16x16x32_bf16 v[118:121], v[210:213], v[168:171], v[118:121]
	v_mfma_f32_16x16x32_bf16 v[114:117], v[218:221], v[168:171], v[114:117]
	v_mfma_f32_16x16x32_bf16 v[102:105], v[210:213], v[186:189], v[102:105]
	v_mfma_f32_16x16x32_bf16 v[98:101], v[218:221], v[186:189], v[98:101]
	v_mfma_f32_16x16x32_bf16 v[86:89], v[210:213], v[194:197], v[86:89]
	v_mfma_f32_16x16x32_bf16 v[82:85], v[218:221], v[194:197], v[82:85]
	v_mfma_f32_16x16x32_bf16 v[70:73], v[210:213], v[202:205], v[70:73]
	v_mfma_f32_16x16x32_bf16 v[66:69], v[218:221], v[202:205], v[66:69]
	v_mfma_f32_16x16x32_bf16 v[118:121], v[214:217], v[172:175], v[118:121]
	v_mfma_f32_16x16x32_bf16 v[114:117], v[222:225], v[172:175], v[114:117]
	v_mfma_f32_16x16x32_bf16 v[102:105], v[214:217], v[190:193], v[102:105]
	v_mfma_f32_16x16x32_bf16 v[98:101], v[222:225], v[190:193], v[98:101]
	v_mfma_f32_16x16x32_bf16 v[86:89], v[214:217], v[198:201], v[86:89]
	v_mfma_f32_16x16x32_bf16 v[82:85], v[222:225], v[198:201], v[82:85]
	v_mfma_f32_16x16x32_bf16 v[70:73], v[214:217], v[206:209], v[70:73]
	v_mfma_f32_16x16x32_bf16 v[66:69], v[222:225], v[206:209], v[66:69]
	s_barrier
	s_mov_b32 m0, s30
	s_add_u32 s62, s18, 0x80
	s_addc_u32 s63, s19, 0
	ds_read_b128 v[168:171], v166 offset:16384
	ds_read_b128 v[172:175], v166 offset:17408
	ds_read_b128 v[186:189], v166 offset:18432
	ds_read_b128 v[190:193], v166 offset:19456
	ds_read_b128 v[194:197], v166 offset:20480
	ds_read_b128 v[198:201], v166 offset:21504
	ds_read_b128 v[202:205], v166 offset:22528
	ds_read_b128 v[206:209], v166 offset:23552
	global_load_lds_dwordx4 v130, s[18:19]
	s_mov_b32 m0, s31
	s_nop 0
	global_load_lds_dwordx4 v134, s[18:19]
	s_waitcnt vmcnt(10)
	s_barrier
	s_waitcnt lgkmcnt(0)
	s_waitcnt lgkmcnt(0)
	v_mfma_f32_16x16x32_bf16 v[62:65], v[146:149], v[168:171], v[62:65]
	v_mfma_f32_16x16x32_bf16 v[58:61], v[154:157], v[168:171], v[58:61]
	v_mfma_f32_16x16x32_bf16 v[46:49], v[146:149], v[186:189], v[46:49]
	v_mfma_f32_16x16x32_bf16 v[42:45], v[154:157], v[186:189], v[42:45]
	v_mfma_f32_16x16x32_bf16 v[30:33], v[146:149], v[194:197], v[30:33]
	v_mfma_f32_16x16x32_bf16 v[26:29], v[154:157], v[194:197], v[26:29]
	v_mfma_f32_16x16x32_bf16 v[14:17], v[146:149], v[202:205], v[14:17]
	v_mfma_f32_16x16x32_bf16 v[10:13], v[154:157], v[202:205], v[10:13]
	v_mfma_f32_16x16x32_bf16 v[62:65], v[150:153], v[172:175], v[62:65]
	v_mfma_f32_16x16x32_bf16 v[58:61], v[158:161], v[172:175], v[58:61]
	v_mfma_f32_16x16x32_bf16 v[46:49], v[150:153], v[190:193], v[46:49]
	v_mfma_f32_16x16x32_bf16 v[42:45], v[158:161], v[190:193], v[42:45]
	v_mfma_f32_16x16x32_bf16 v[30:33], v[150:153], v[198:201], v[30:33]
	v_mfma_f32_16x16x32_bf16 v[26:29], v[158:161], v[198:201], v[26:29]
	v_mfma_f32_16x16x32_bf16 v[14:17], v[150:153], v[206:209], v[14:17]
	v_mfma_f32_16x16x32_bf16 v[10:13], v[158:161], v[206:209], v[10:13]
	s_barrier
	v_add_u32_e32 v158, 0x18000, v164
	ds_read_b128 v[146:149], v158
	ds_read_b128 v[150:153], v158 offset:1024
	ds_read_b128 v[154:157], v158 offset:2048
	ds_read_b128 v[158:161], v158 offset:3072
	s_add_u32 s48, s16, 0x80000
	s_addc_u32 s49, s17, 0
	s_add_i32 s50, s51, s29
	s_mov_b32 m0, s50
	s_nop 0
	global_load_lds_dwordx4 v132, s[48:49]
	s_add_i32 m0, s50, 0x2000
	s_nop 0
	global_load_lds_dwordx4 v136, s[48:49]
	s_waitcnt vmcnt(6)
	s_barrier
	v_mfma_f32_16x16x32_bf16 v[54:57], v[210:213], v[168:171], v[54:57]
	v_mfma_f32_16x16x32_bf16 v[50:53], v[218:221], v[168:171], v[50:53]
	v_mfma_f32_16x16x32_bf16 v[38:41], v[210:213], v[186:189], v[38:41]
	v_mfma_f32_16x16x32_bf16 v[34:37], v[218:221], v[186:189], v[34:37]
	v_mfma_f32_16x16x32_bf16 v[22:25], v[210:213], v[194:197], v[22:25]
	v_mfma_f32_16x16x32_bf16 v[18:21], v[218:221], v[194:197], v[18:21]
	v_mfma_f32_16x16x32_bf16 v[6:9], v[210:213], v[202:205], v[6:9]
	v_mfma_f32_16x16x32_bf16 v[2:5], v[218:221], v[202:205], v[2:5]
	v_mfma_f32_16x16x32_bf16 v[54:57], v[214:217], v[172:175], v[54:57]
	v_mfma_f32_16x16x32_bf16 v[50:53], v[222:225], v[172:175], v[50:53]
	v_mfma_f32_16x16x32_bf16 v[38:41], v[214:217], v[190:193], v[38:41]
	v_mfma_f32_16x16x32_bf16 v[34:37], v[222:225], v[190:193], v[34:37]
	v_mfma_f32_16x16x32_bf16 v[22:25], v[214:217], v[198:201], v[22:25]
	v_mfma_f32_16x16x32_bf16 v[18:21], v[222:225], v[198:201], v[18:21]
	v_mfma_f32_16x16x32_bf16 v[6:9], v[214:217], v[206:209], v[6:9]
	v_mfma_f32_16x16x32_bf16 v[2:5], v[222:225], v[206:209], v[2:5]
	s_barrier
	s_add_i32 s48, 0, 0x18000
	s_add_u32 s18, s18, s80
	s_addc_u32 s19, s19, 0
	s_mov_b32 m0, s34
	ds_read_b128 v[168:171], v166 offset:32768
	ds_read_b128 v[172:175], v166 offset:33792
	ds_read_b128 v[186:189], v166 offset:34816
	ds_read_b128 v[190:193], v166 offset:35840
	ds_read_b128 v[194:197], v166 offset:36864
	ds_read_b128 v[198:201], v166 offset:37888
	ds_read_b128 v[202:205], v166 offset:38912
	ds_read_b128 v[206:209], v166 offset:39936
	global_load_lds_dwordx4 v130, s[18:19]
	s_mov_b32 m0, s35
	s_nop 0
	global_load_lds_dwordx4 v134, s[18:19]
	s_waitcnt lgkmcnt(8)
	s_barrier
	s_waitcnt lgkmcnt(0)
	s_waitcnt lgkmcnt(0)
	v_mfma_f32_16x16x32_bf16 v[126:129], v[146:149], v[168:171], v[126:129]
	v_mfma_f32_16x16x32_bf16 v[122:125], v[154:157], v[168:171], v[122:125]
	v_mfma_f32_16x16x32_bf16 v[110:113], v[146:149], v[186:189], v[110:113]
	v_mfma_f32_16x16x32_bf16 v[106:109], v[154:157], v[186:189], v[106:109]
	v_mfma_f32_16x16x32_bf16 v[94:97], v[146:149], v[194:197], v[94:97]
	v_mfma_f32_16x16x32_bf16 v[90:93], v[154:157], v[194:197], v[90:93]
	v_mfma_f32_16x16x32_bf16 v[78:81], v[146:149], v[202:205], v[78:81]
	v_mfma_f32_16x16x32_bf16 v[74:77], v[154:157], v[202:205], v[74:77]
	v_mfma_f32_16x16x32_bf16 v[126:129], v[150:153], v[172:175], v[126:129]
	v_mfma_f32_16x16x32_bf16 v[122:125], v[158:161], v[172:175], v[122:125]
	v_mfma_f32_16x16x32_bf16 v[110:113], v[150:153], v[190:193], v[110:113]
	v_mfma_f32_16x16x32_bf16 v[106:109], v[158:161], v[190:193], v[106:109]
	v_mfma_f32_16x16x32_bf16 v[94:97], v[150:153], v[198:201], v[94:97]
	v_mfma_f32_16x16x32_bf16 v[90:93], v[158:161], v[198:201], v[90:93]
	v_mfma_f32_16x16x32_bf16 v[78:81], v[150:153], v[206:209], v[78:81]
	v_mfma_f32_16x16x32_bf16 v[74:77], v[158:161], v[206:209], v[74:77]
	s_barrier
	s_add_i32 s18, 0, 0x1c000
	s_add_i32 s19, s48, s29
	v_add_u32_e32 v167, s18, v164
	s_mov_b32 m0, s19
	ds_read_b128 v[210:213], v167
	ds_read_b128 v[214:217], v167 offset:1024
	ds_read_b128 v[218:221], v167 offset:2048
	ds_read_b128 v[222:225], v167 offset:3072
	global_load_lds_dwordx4 v132, s[64:65]
	s_add_i32 m0, s19, 0x2000
	s_nop 0
	global_load_lds_dwordx4 v136, s[64:65]
	s_barrier
	s_waitcnt lgkmcnt(0)
	s_waitcnt lgkmcnt(0)
	v_mfma_f32_16x16x32_bf16 v[118:121], v[210:213], v[168:171], v[118:121]
	v_mfma_f32_16x16x32_bf16 v[114:117], v[218:221], v[168:171], v[114:117]
	v_mfma_f32_16x16x32_bf16 v[102:105], v[210:213], v[186:189], v[102:105]
	v_mfma_f32_16x16x32_bf16 v[98:101], v[218:221], v[186:189], v[98:101]
	v_mfma_f32_16x16x32_bf16 v[86:89], v[210:213], v[194:197], v[86:89]
	v_mfma_f32_16x16x32_bf16 v[82:85], v[218:221], v[194:197], v[82:85]
	v_mfma_f32_16x16x32_bf16 v[70:73], v[210:213], v[202:205], v[70:73]
	v_mfma_f32_16x16x32_bf16 v[66:69], v[218:221], v[202:205], v[66:69]
	v_mfma_f32_16x16x32_bf16 v[118:121], v[214:217], v[172:175], v[118:121]
	v_mfma_f32_16x16x32_bf16 v[114:117], v[222:225], v[172:175], v[114:117]
	v_mfma_f32_16x16x32_bf16 v[102:105], v[214:217], v[190:193], v[102:105]
	v_mfma_f32_16x16x32_bf16 v[98:101], v[222:225], v[190:193], v[98:101]
	v_mfma_f32_16x16x32_bf16 v[86:89], v[214:217], v[198:201], v[86:89]
	v_mfma_f32_16x16x32_bf16 v[82:85], v[222:225], v[198:201], v[82:85]
	v_mfma_f32_16x16x32_bf16 v[70:73], v[214:217], v[206:209], v[70:73]
	v_mfma_f32_16x16x32_bf16 v[66:69], v[222:225], v[206:209], v[66:69]
	s_barrier
	s_mov_b32 m0, s38
	ds_read_b128 v[168:171], v166 offset:49152
	ds_read_b128 v[172:175], v166 offset:50176
	ds_read_b128 v[186:189], v166 offset:51200
	ds_read_b128 v[190:193], v166 offset:52224
	ds_read_b128 v[194:197], v166 offset:53248
	ds_read_b128 v[198:201], v166 offset:54272
	ds_read_b128 v[202:205], v166 offset:55296
	ds_read_b128 v[206:209], v166 offset:56320
	global_load_lds_dwordx4 v130, s[62:63]
	s_mov_b32 m0, s39
	s_nop 0
	global_load_lds_dwordx4 v134, s[62:63]
	s_waitcnt vmcnt(10)
	s_barrier
	s_waitcnt lgkmcnt(0)
	s_waitcnt lgkmcnt(0)
	v_mfma_f32_16x16x32_bf16 v[62:65], v[146:149], v[168:171], v[62:65]
	v_mfma_f32_16x16x32_bf16 v[58:61], v[154:157], v[168:171], v[58:61]
	v_mfma_f32_16x16x32_bf16 v[46:49], v[146:149], v[186:189], v[46:49]
	v_mfma_f32_16x16x32_bf16 v[42:45], v[154:157], v[186:189], v[42:45]
	v_mfma_f32_16x16x32_bf16 v[30:33], v[146:149], v[194:197], v[30:33]
	v_mfma_f32_16x16x32_bf16 v[26:29], v[154:157], v[194:197], v[26:29]
	v_mfma_f32_16x16x32_bf16 v[14:17], v[146:149], v[202:205], v[14:17]
	v_mfma_f32_16x16x32_bf16 v[10:13], v[154:157], v[202:205], v[10:13]
	v_mfma_f32_16x16x32_bf16 v[62:65], v[150:153], v[172:175], v[62:65]
	v_mfma_f32_16x16x32_bf16 v[58:61], v[158:161], v[172:175], v[58:61]
	v_mfma_f32_16x16x32_bf16 v[46:49], v[150:153], v[190:193], v[46:49]
	v_mfma_f32_16x16x32_bf16 v[42:45], v[158:161], v[190:193], v[42:45]
	v_mfma_f32_16x16x32_bf16 v[30:33], v[150:153], v[198:201], v[30:33]
	v_mfma_f32_16x16x32_bf16 v[26:29], v[158:161], v[198:201], v[26:29]
	v_mfma_f32_16x16x32_bf16 v[14:17], v[150:153], v[206:209], v[14:17]
	v_mfma_f32_16x16x32_bf16 v[10:13], v[158:161], v[206:209], v[10:13]
	s_barrier
	v_add_u32_e32 v158, 0x10000, v164
	ds_read_b128 v[146:149], v158
	ds_read_b128 v[150:153], v158 offset:1024
	ds_read_b128 v[154:157], v158 offset:2048
	ds_read_b128 v[158:161], v158 offset:3072
	s_add_u32 s16, s16, 0x80080
	s_addc_u32 s17, s17, 0
	s_add_i32 s18, s18, s29
	s_mov_b32 m0, s18
	s_nop 0
	global_load_lds_dwordx4 v132, s[16:17]
	s_add_i32 m0, s18, 0x2000
	s_nop 0
	global_load_lds_dwordx4 v136, s[16:17]
	s_waitcnt vmcnt(6)
	s_barrier
	v_mfma_f32_16x16x32_bf16 v[54:57], v[210:213], v[168:171], v[54:57]
	v_mfma_f32_16x16x32_bf16 v[50:53], v[218:221], v[168:171], v[50:53]
	v_mfma_f32_16x16x32_bf16 v[38:41], v[210:213], v[186:189], v[38:41]
	v_mfma_f32_16x16x32_bf16 v[34:37], v[218:221], v[186:189], v[34:37]
	v_mfma_f32_16x16x32_bf16 v[22:25], v[210:213], v[194:197], v[22:25]
	v_mfma_f32_16x16x32_bf16 v[18:21], v[218:221], v[194:197], v[18:21]
	v_mfma_f32_16x16x32_bf16 v[6:9], v[210:213], v[202:205], v[6:9]
	v_mfma_f32_16x16x32_bf16 v[2:5], v[218:221], v[202:205], v[2:5]
	v_mfma_f32_16x16x32_bf16 v[54:57], v[214:217], v[172:175], v[54:57]
	v_mfma_f32_16x16x32_bf16 v[50:53], v[222:225], v[172:175], v[50:53]
	v_mfma_f32_16x16x32_bf16 v[38:41], v[214:217], v[190:193], v[38:41]
	v_mfma_f32_16x16x32_bf16 v[34:37], v[222:225], v[190:193], v[34:37]
	v_mfma_f32_16x16x32_bf16 v[22:25], v[214:217], v[198:201], v[22:25]
	v_mfma_f32_16x16x32_bf16 v[18:21], v[222:225], v[198:201], v[18:21]
	v_mfma_f32_16x16x32_bf16 v[6:9], v[214:217], v[206:209], v[6:9]
	v_mfma_f32_16x16x32_bf16 v[2:5], v[222:225], v[206:209], v[2:5]
	s_barrier
	s_add_i32 s47, s47, 2
	s_add_u32 s6, s6, 0x100
	s_addc_u32 s7, s7, 0
	s_cmp_gt_u32 s47, 29
	s_cbranch_scc0 .LBB0_1408
	s_waitcnt lgkmcnt(0)
	s_ashr_i32 s3, s33, 5
	s_mul_hi_i32 s7, s3, 0x9000
	s_mul_i32 s3, s3, 0x9000
	v_lshl_or_b32 v168, s43, 8, v165
	s_add_u32 s6, s36, s3
	s_addc_u32 s7, s37, s7
	v_ashrrev_i32_e32 v169, 31, v168
	v_lshl_add_u64 v[162:163], v[168:169], 2, s[6:7]
	global_load_dwordx4 v[142:145], v[162:163], off offset:16
	global_load_dwordx4 v[146:149], v[162:163], off
	s_mov_b64 s[6:7], 0x80000
	s_and_b64 vcc, exec, s[4:5]
	s_mov_b32 s43, s2
	s_mov_b64 s[16:17], s[12:13]
	s_mov_b64 s[14:15], s[10:11]
	s_waitcnt vmcnt(0)
	v_pk_add_f32 v[150:151], v[144:145], 1.0 op_sel_hi:[1,0]
	v_pk_add_f32 v[154:155], v[142:143], 1.0 op_sel_hi:[1,0]
	global_load_dwordx4 v[158:161], v[162:163], off offset:528
	global_load_dwordx4 v[142:145], v[162:163], off offset:512
	v_lshl_add_u32 v162, s33, 8, v1
	v_ashrrev_i32_e32 v163, 31, v162
	v_lshlrev_b64 v[152:153], 12, v[162:163]
	v_lshl_add_u64 v[152:153], s[8:9], 0, v[152:153]
	v_lshl_add_u64 v[152:153], v[168:169], 1, v[152:153]
	v_mov_b32_e32 v156, 0x10000
	v_mov_b32_e32 v157, 0
	global_load_dwordx4 v[174:177], v[152:153], off offset:2048
	global_load_dwordx4 v[186:189], v[152:153], off offset:2304
	v_lshl_add_u64 v[152:153], v[152:153], 0, v[156:157]
	global_load_dwordx4 v[190:193], v[152:153], off offset:2048
	global_load_dwordx4 v[194:197], v[152:153], off offset:2304
	v_lshl_add_u64 v[152:153], v[152:153], 0, v[156:157]
	global_load_dwordx4 v[198:201], v[152:153], off offset:2048
	global_load_dwordx4 v[202:205], v[152:153], off offset:2304
	v_lshl_add_u64 v[152:153], v[152:153], 0, v[156:157]
	global_load_dwordx4 v[206:209], v[152:153], off offset:2048
	global_load_dwordx4 v[210:213], v[152:153], off offset:2304
	v_mov_b32_e32 v156, 0x50000
	v_lshl_add_u64 v[152:153], v[152:153], 0, v[156:157]
	v_mov_b32_e32 v156, 0x10000
	global_load_dwordx4 v[214:217], v[152:153], off offset:2048
	global_load_dwordx4 v[218:221], v[152:153], off offset:2304
	v_lshl_add_u64 v[152:153], v[152:153], 0, v[156:157]
	global_load_dwordx4 v[222:225], v[152:153], off offset:2048
	global_load_dwordx4 v[226:229], v[152:153], off offset:2304
	v_lshl_add_u64 v[152:153], v[152:153], 0, v[156:157]
	global_load_dwordx4 v[230:233], v[152:153], off offset:2048
	global_load_dwordx4 v[236:239], v[152:153], off offset:2304
	v_lshl_add_u64 v[152:153], v[152:153], 0, v[156:157]
	global_load_dwordx4 v[246:249], v[152:153], off offset:2048
	global_load_dwordx4 v[250:253], v[152:153], off offset:2304
	v_pk_add_f32 v[156:157], v[146:147], 1.0 op_sel_hi:[1,0]
	v_pk_add_f32 v[152:153], v[148:149], 1.0 op_sel_hi:[1,0]
	s_mov_b32 s33, s42
	s_waitcnt vmcnt(0)
	v_pk_add_f32 v[146:147], v[144:145], 1.0 op_sel_hi:[1,0]
	v_pk_add_f32 v[144:145], v[158:159], 1.0 op_sel_hi:[1,0]
	v_lshlrev_b64 v[158:159], 12, v[162:163]
	v_pk_add_f32 v[148:149], v[142:143], 1.0 op_sel_hi:[1,0]
	v_pk_add_f32 v[142:143], v[160:161], 1.0 op_sel_hi:[1,0]
	v_lshl_add_u64 v[158:159], s[8:9], 0, v[158:159]
	v_lshlrev_b64 v[160:161], 1, v[168:169]
	v_lshl_add_u64 v[158:159], v[158:159], 0, v[160:161]
	v_mov_b32_e32 v168, v174
	v_mov_b32_e32 v169, v175
	v_mov_b32_e32 v170, v176
	v_mov_b32_e32 v171, v177
	s_nop 0
	v_lshlrev_b32_e32 v172, 16, v168
	v_and_b32_e32 v173, 0xffff0000, v168
	v_lshlrev_b32_e32 v168, 16, v169
	v_and_b32_e32 v169, 0xffff0000, v169
	v_pk_fma_f32 v[128:129], v[128:129], v[152:153], v[168:169]
	v_lshlrev_b32_e32 v168, 16, v170
	v_and_b32_e32 v169, 0xffff0000, v170
	v_pk_fma_f32 v[168:169], v[122:123], v[154:155], v[168:169]
	v_lshlrev_b32_e32 v122, 16, v171
	v_and_b32_e32 v123, 0xffff0000, v171
	v_pk_fma_f32 v[126:127], v[126:127], v[156:157], v[172:173]
	v_pk_fma_f32 v[170:171], v[124:125], v[150:151], v[122:123]
	v_cvt_pk_bf16_f32 v122, v126, v127
	v_cvt_pk_bf16_f32 v123, v128, v129
	v_cvt_pk_bf16_f32 v124, v168, v169
	v_cvt_pk_bf16_f32 v125, v170, v171
	global_store_dwordx4 v[158:159], v[122:125], off offset:2048
	s_nop 1
	v_mov_b32_e32 v122, v186
	v_mov_b32_e32 v123, v187
	v_mov_b32_e32 v124, v188
	v_mov_b32_e32 v125, v189
	s_nop 0
	v_lshlrev_b32_e32 v126, 16, v122
	v_and_b32_e32 v127, 0xffff0000, v122
	v_lshlrev_b32_e32 v122, 16, v123
	v_and_b32_e32 v123, 0xffff0000, v123
	v_pk_fma_f32 v[120:121], v[120:121], v[146:147], v[122:123]
	v_lshlrev_b32_e32 v122, 16, v124
	v_and_b32_e32 v123, 0xffff0000, v124
	v_pk_fma_f32 v[122:123], v[114:115], v[144:145], v[122:123]
	v_lshlrev_b32_e32 v114, 16, v125
	v_and_b32_e32 v115, 0xffff0000, v125
	v_pk_fma_f32 v[118:119], v[118:119], v[148:149], v[126:127]
	v_pk_fma_f32 v[124:125], v[116:117], v[142:143], v[114:115]
	v_cvt_pk_bf16_f32 v114, v118, v119
	v_cvt_pk_bf16_f32 v115, v120, v121
	v_cvt_pk_bf16_f32 v116, v122, v123
	v_cvt_pk_bf16_f32 v117, v124, v125
	global_store_dwordx4 v[158:159], v[114:117], off offset:2304
	s_nop 1
	v_or_b32_e32 v114, 16, v162
	v_ashrrev_i32_e32 v115, 31, v114
	v_lshlrev_b64 v[114:115], 12, v[114:115]
	v_lshl_add_u64 v[114:115], s[8:9], 0, v[114:115]
	v_lshl_add_u64 v[118:119], v[114:115], 0, v[160:161]
	v_mov_b32_e32 v114, v190
	v_mov_b32_e32 v115, v191
	v_mov_b32_e32 v116, v192
	v_mov_b32_e32 v117, v193
	s_nop 0
	v_lshlrev_b32_e32 v120, 16, v114
	v_and_b32_e32 v121, 0xffff0000, v114
	v_lshlrev_b32_e32 v114, 16, v115
	v_and_b32_e32 v115, 0xffff0000, v115
	v_pk_fma_f32 v[112:113], v[112:113], v[152:153], v[114:115]
	v_lshlrev_b32_e32 v114, 16, v116
	v_and_b32_e32 v115, 0xffff0000, v116
	v_pk_fma_f32 v[114:115], v[106:107], v[154:155], v[114:115]
	v_lshlrev_b32_e32 v106, 16, v117
	v_and_b32_e32 v107, 0xffff0000, v117
	v_pk_fma_f32 v[110:111], v[110:111], v[156:157], v[120:121]
	v_pk_fma_f32 v[116:117], v[108:109], v[150:151], v[106:107]
	v_cvt_pk_bf16_f32 v106, v110, v111
	v_cvt_pk_bf16_f32 v107, v112, v113
	v_cvt_pk_bf16_f32 v108, v114, v115
	v_cvt_pk_bf16_f32 v109, v116, v117
	global_store_dwordx4 v[118:119], v[106:109], off offset:2048
	s_nop 1
	v_mov_b32_e32 v106, v194
	v_mov_b32_e32 v107, v195
	v_mov_b32_e32 v108, v196
	v_mov_b32_e32 v109, v197
	s_nop 0
	v_lshlrev_b32_e32 v110, 16, v106
	v_and_b32_e32 v111, 0xffff0000, v106
	v_lshlrev_b32_e32 v106, 16, v107
	v_and_b32_e32 v107, 0xffff0000, v107
	v_pk_fma_f32 v[104:105], v[104:105], v[146:147], v[106:107]
	v_lshlrev_b32_e32 v106, 16, v108
	v_and_b32_e32 v107, 0xffff0000, v108
	v_pk_fma_f32 v[106:107], v[98:99], v[144:145], v[106:107]
	v_lshlrev_b32_e32 v98, 16, v109
	v_and_b32_e32 v99, 0xffff0000, v109
	v_pk_fma_f32 v[102:103], v[102:103], v[148:149], v[110:111]
	v_pk_fma_f32 v[108:109], v[100:101], v[142:143], v[98:99]
	v_cvt_pk_bf16_f32 v98, v102, v103
	v_cvt_pk_bf16_f32 v99, v104, v105
	v_cvt_pk_bf16_f32 v100, v106, v107
	v_cvt_pk_bf16_f32 v101, v108, v109
	global_store_dwordx4 v[118:119], v[98:101], off offset:2304
	s_nop 1
	v_or_b32_e32 v98, 32, v162
	v_ashrrev_i32_e32 v99, 31, v98
	v_lshlrev_b64 v[98:99], 12, v[98:99]
	v_lshl_add_u64 v[98:99], s[8:9], 0, v[98:99]
	v_lshl_add_u64 v[102:103], v[98:99], 0, v[160:161]
	v_mov_b32_e32 v98, v198
	v_mov_b32_e32 v99, v199
	v_mov_b32_e32 v100, v200
	v_mov_b32_e32 v101, v201
	s_nop 0
	v_lshlrev_b32_e32 v104, 16, v98
	v_and_b32_e32 v105, 0xffff0000, v98
	v_lshlrev_b32_e32 v98, 16, v99
	v_and_b32_e32 v99, 0xffff0000, v99
	v_pk_fma_f32 v[96:97], v[96:97], v[152:153], v[98:99]
	v_lshlrev_b32_e32 v98, 16, v100
	v_and_b32_e32 v99, 0xffff0000, v100
	v_pk_fma_f32 v[98:99], v[90:91], v[154:155], v[98:99]
	v_lshlrev_b32_e32 v90, 16, v101
	v_and_b32_e32 v91, 0xffff0000, v101
	v_pk_fma_f32 v[94:95], v[94:95], v[156:157], v[104:105]
	v_pk_fma_f32 v[100:101], v[92:93], v[150:151], v[90:91]
	v_cvt_pk_bf16_f32 v90, v94, v95
	v_cvt_pk_bf16_f32 v91, v96, v97
	v_cvt_pk_bf16_f32 v92, v98, v99
	v_cvt_pk_bf16_f32 v93, v100, v101
	global_store_dwordx4 v[102:103], v[90:93], off offset:2048
	s_nop 1
	v_mov_b32_e32 v90, v202
	v_mov_b32_e32 v91, v203
	v_mov_b32_e32 v92, v204
	v_mov_b32_e32 v93, v205
	s_nop 0
	v_lshlrev_b32_e32 v94, 16, v90
	v_and_b32_e32 v95, 0xffff0000, v90
	v_lshlrev_b32_e32 v90, 16, v91
	v_and_b32_e32 v91, 0xffff0000, v91
	v_pk_fma_f32 v[88:89], v[88:89], v[146:147], v[90:91]
	v_lshlrev_b32_e32 v90, 16, v92
	v_and_b32_e32 v91, 0xffff0000, v92
	v_pk_fma_f32 v[90:91], v[82:83], v[144:145], v[90:91]
	v_lshlrev_b32_e32 v82, 16, v93
	v_and_b32_e32 v83, 0xffff0000, v93
	v_pk_fma_f32 v[86:87], v[86:87], v[148:149], v[94:95]
	v_pk_fma_f32 v[92:93], v[84:85], v[142:143], v[82:83]
	v_cvt_pk_bf16_f32 v82, v86, v87
	v_cvt_pk_bf16_f32 v83, v88, v89
	v_cvt_pk_bf16_f32 v84, v90, v91
	v_cvt_pk_bf16_f32 v85, v92, v93
	global_store_dwordx4 v[102:103], v[82:85], off offset:2304
	s_nop 1
	v_or_b32_e32 v82, 48, v162
	v_ashrrev_i32_e32 v83, 31, v82
	v_lshlrev_b64 v[82:83], 12, v[82:83]
	v_lshl_add_u64 v[82:83], s[8:9], 0, v[82:83]
	v_lshl_add_u64 v[82:83], v[82:83], 0, v[160:161]
	v_mov_b32_e32 v84, v206
	v_mov_b32_e32 v85, v207
	v_mov_b32_e32 v86, v208
	v_mov_b32_e32 v87, v209
	s_nop 0
	v_lshlrev_b32_e32 v88, 16, v84
	v_and_b32_e32 v89, 0xffff0000, v84
	v_lshlrev_b32_e32 v84, 16, v85
	v_and_b32_e32 v85, 0xffff0000, v85
	v_pk_fma_f32 v[80:81], v[80:81], v[152:153], v[84:85]
	v_lshlrev_b32_e32 v84, 16, v86
	v_and_b32_e32 v85, 0xffff0000, v86
	v_pk_fma_f32 v[84:85], v[74:75], v[154:155], v[84:85]
	v_lshlrev_b32_e32 v74, 16, v87
	v_and_b32_e32 v75, 0xffff0000, v87
	v_pk_fma_f32 v[78:79], v[78:79], v[156:157], v[88:89]
	v_pk_fma_f32 v[86:87], v[76:77], v[150:151], v[74:75]
	v_cvt_pk_bf16_f32 v74, v78, v79
	v_cvt_pk_bf16_f32 v75, v80, v81
	v_cvt_pk_bf16_f32 v76, v84, v85
	v_cvt_pk_bf16_f32 v77, v86, v87
	global_store_dwordx4 v[82:83], v[74:77], off offset:2048
	s_nop 1
	v_mov_b32_e32 v74, v210
	v_mov_b32_e32 v75, v211
	v_mov_b32_e32 v76, v212
	v_mov_b32_e32 v77, v213
	s_nop 0
	v_lshlrev_b32_e32 v78, 16, v74
	v_and_b32_e32 v79, 0xffff0000, v74
	v_lshlrev_b32_e32 v74, 16, v75
	v_and_b32_e32 v75, 0xffff0000, v75
	v_pk_fma_f32 v[72:73], v[72:73], v[146:147], v[74:75]
	v_lshlrev_b32_e32 v74, 16, v76
	v_and_b32_e32 v75, 0xffff0000, v76
	v_pk_fma_f32 v[74:75], v[66:67], v[144:145], v[74:75]
	v_lshlrev_b32_e32 v66, 16, v77
	v_and_b32_e32 v67, 0xffff0000, v77
	v_pk_fma_f32 v[70:71], v[70:71], v[148:149], v[78:79]
	v_pk_fma_f32 v[76:77], v[68:69], v[142:143], v[66:67]
	v_cvt_pk_bf16_f32 v66, v70, v71
	v_cvt_pk_bf16_f32 v67, v72, v73
	v_cvt_pk_bf16_f32 v68, v74, v75
	v_cvt_pk_bf16_f32 v69, v76, v77
	v_lshl_add_u64 v[70:71], v[158:159], 0, s[6:7]
	global_store_dwordx4 v[82:83], v[66:69], off offset:2304
	s_nop 1
	v_mov_b32_e32 v66, v214
	v_mov_b32_e32 v67, v215
	v_mov_b32_e32 v68, v216
	v_mov_b32_e32 v69, v217
	s_mov_b64 s[6:7], 0x90000
	s_nop 0
	v_lshlrev_b32_e32 v72, 16, v66
	v_and_b32_e32 v73, 0xffff0000, v66
	v_lshlrev_b32_e32 v66, 16, v67
	v_and_b32_e32 v67, 0xffff0000, v67
	v_pk_fma_f32 v[64:65], v[64:65], v[152:153], v[66:67]
	v_lshlrev_b32_e32 v66, 16, v68
	v_and_b32_e32 v67, 0xffff0000, v68
	v_pk_fma_f32 v[66:67], v[58:59], v[154:155], v[66:67]
	v_lshlrev_b32_e32 v58, 16, v69
	v_and_b32_e32 v59, 0xffff0000, v69
	v_pk_fma_f32 v[62:63], v[62:63], v[156:157], v[72:73]
	v_pk_fma_f32 v[68:69], v[60:61], v[150:151], v[58:59]
	v_cvt_pk_bf16_f32 v58, v62, v63
	v_cvt_pk_bf16_f32 v59, v64, v65
	v_cvt_pk_bf16_f32 v60, v66, v67
	v_cvt_pk_bf16_f32 v61, v68, v69
	global_store_dwordx4 v[70:71], v[58:61], off offset:2048
	s_nop 1
	v_mov_b32_e32 v58, v218
	v_mov_b32_e32 v59, v219
	v_mov_b32_e32 v60, v220
	v_mov_b32_e32 v61, v221
	s_nop 0
	v_lshlrev_b32_e32 v62, 16, v58
	v_and_b32_e32 v63, 0xffff0000, v58
	v_lshlrev_b32_e32 v58, 16, v59
	v_and_b32_e32 v59, 0xffff0000, v59
	v_pk_fma_f32 v[56:57], v[56:57], v[146:147], v[58:59]
	v_lshlrev_b32_e32 v58, 16, v60
	v_and_b32_e32 v59, 0xffff0000, v60
	v_pk_fma_f32 v[58:59], v[50:51], v[144:145], v[58:59]
	v_lshlrev_b32_e32 v50, 16, v61
	v_and_b32_e32 v51, 0xffff0000, v61
	v_pk_fma_f32 v[54:55], v[54:55], v[148:149], v[62:63]
	v_pk_fma_f32 v[60:61], v[52:53], v[142:143], v[50:51]
	v_cvt_pk_bf16_f32 v50, v54, v55
	v_cvt_pk_bf16_f32 v51, v56, v57
	v_cvt_pk_bf16_f32 v52, v58, v59
	v_cvt_pk_bf16_f32 v53, v60, v61
	v_lshl_add_u64 v[54:55], v[158:159], 0, s[6:7]
	global_store_dwordx4 v[70:71], v[50:53], off offset:2304
	s_nop 1
	v_mov_b32_e32 v50, v222
	v_mov_b32_e32 v51, v223
	v_mov_b32_e32 v52, v224
	v_mov_b32_e32 v53, v225
	s_mov_b64 s[6:7], 0xa0000
	s_nop 0
	v_lshlrev_b32_e32 v56, 16, v50
	v_and_b32_e32 v57, 0xffff0000, v50
	v_lshlrev_b32_e32 v50, 16, v51
	v_and_b32_e32 v51, 0xffff0000, v51
	v_pk_fma_f32 v[48:49], v[48:49], v[152:153], v[50:51]
	v_lshlrev_b32_e32 v50, 16, v52
	v_and_b32_e32 v51, 0xffff0000, v52
	v_pk_fma_f32 v[50:51], v[42:43], v[154:155], v[50:51]
	v_lshlrev_b32_e32 v42, 16, v53
	v_and_b32_e32 v43, 0xffff0000, v53
	v_pk_fma_f32 v[46:47], v[46:47], v[156:157], v[56:57]
	v_pk_fma_f32 v[52:53], v[44:45], v[150:151], v[42:43]
	v_cvt_pk_bf16_f32 v42, v46, v47
	v_cvt_pk_bf16_f32 v43, v48, v49
	v_cvt_pk_bf16_f32 v44, v50, v51
	v_cvt_pk_bf16_f32 v45, v52, v53
	global_store_dwordx4 v[54:55], v[42:45], off offset:2048
	s_nop 1
	v_mov_b32_e32 v42, v226
	v_mov_b32_e32 v43, v227
	v_mov_b32_e32 v44, v228
	v_mov_b32_e32 v45, v229
	s_nop 0
	v_lshlrev_b32_e32 v46, 16, v42
	v_and_b32_e32 v47, 0xffff0000, v42
	v_lshlrev_b32_e32 v42, 16, v43
	v_and_b32_e32 v43, 0xffff0000, v43
	v_pk_fma_f32 v[40:41], v[40:41], v[146:147], v[42:43]
	v_lshlrev_b32_e32 v42, 16, v44
	v_and_b32_e32 v43, 0xffff0000, v44
	v_pk_fma_f32 v[42:43], v[34:35], v[144:145], v[42:43]
	v_lshlrev_b32_e32 v34, 16, v45
	v_and_b32_e32 v35, 0xffff0000, v45
	v_pk_fma_f32 v[38:39], v[38:39], v[148:149], v[46:47]
	v_pk_fma_f32 v[44:45], v[36:37], v[142:143], v[34:35]
	v_cvt_pk_bf16_f32 v34, v38, v39
	v_cvt_pk_bf16_f32 v35, v40, v41
	v_cvt_pk_bf16_f32 v36, v42, v43
	v_cvt_pk_bf16_f32 v37, v44, v45
	v_lshl_add_u64 v[38:39], v[158:159], 0, s[6:7]
	global_store_dwordx4 v[54:55], v[34:37], off offset:2304
	s_nop 1
	v_mov_b32_e32 v34, v230
	v_mov_b32_e32 v35, v231
	v_mov_b32_e32 v36, v232
	v_mov_b32_e32 v37, v233
	s_mov_b64 s[6:7], 0xb0000
	s_nop 0
	v_lshlrev_b32_e32 v40, 16, v34
	v_and_b32_e32 v41, 0xffff0000, v34
	v_lshlrev_b32_e32 v34, 16, v35
	v_and_b32_e32 v35, 0xffff0000, v35
	v_pk_fma_f32 v[32:33], v[32:33], v[152:153], v[34:35]
	v_lshlrev_b32_e32 v34, 16, v36
	v_and_b32_e32 v35, 0xffff0000, v36
	v_pk_fma_f32 v[34:35], v[26:27], v[154:155], v[34:35]
	v_lshlrev_b32_e32 v26, 16, v37
	v_and_b32_e32 v27, 0xffff0000, v37
	v_pk_fma_f32 v[30:31], v[30:31], v[156:157], v[40:41]
	v_pk_fma_f32 v[36:37], v[28:29], v[150:151], v[26:27]
	v_cvt_pk_bf16_f32 v26, v30, v31
	v_cvt_pk_bf16_f32 v27, v32, v33
	v_cvt_pk_bf16_f32 v28, v34, v35
	v_cvt_pk_bf16_f32 v29, v36, v37
	global_store_dwordx4 v[38:39], v[26:29], off offset:2048
	s_nop 1
	v_mov_b32_e32 v26, v236
	v_mov_b32_e32 v27, v237
	v_mov_b32_e32 v28, v238
	v_mov_b32_e32 v29, v239
	s_nop 0
	v_lshlrev_b32_e32 v30, 16, v26
	v_and_b32_e32 v31, 0xffff0000, v26
	v_lshlrev_b32_e32 v26, 16, v27
	v_and_b32_e32 v27, 0xffff0000, v27
	v_pk_fma_f32 v[24:25], v[24:25], v[146:147], v[26:27]
	v_lshlrev_b32_e32 v26, 16, v28
	v_and_b32_e32 v27, 0xffff0000, v28
	v_pk_fma_f32 v[26:27], v[18:19], v[144:145], v[26:27]
	v_lshlrev_b32_e32 v18, 16, v29
	v_and_b32_e32 v19, 0xffff0000, v29
	v_pk_fma_f32 v[22:23], v[22:23], v[148:149], v[30:31]
	v_pk_fma_f32 v[28:29], v[20:21], v[142:143], v[18:19]
	v_cvt_pk_bf16_f32 v18, v22, v23
	v_cvt_pk_bf16_f32 v19, v24, v25
	v_cvt_pk_bf16_f32 v20, v26, v27
	v_cvt_pk_bf16_f32 v21, v28, v29
	global_store_dwordx4 v[38:39], v[18:21], off offset:2304
	s_nop 1
	v_lshl_add_u64 v[18:19], v[158:159], 0, s[6:7]
	v_mov_b32_e32 v20, v246
	v_mov_b32_e32 v21, v247
	v_mov_b32_e32 v22, v248
	v_mov_b32_e32 v23, v249
	s_nop 0
	v_lshlrev_b32_e32 v24, 16, v20
	v_and_b32_e32 v25, 0xffff0000, v20
	v_lshlrev_b32_e32 v20, 16, v21
	v_and_b32_e32 v21, 0xffff0000, v21
	v_pk_fma_f32 v[16:17], v[16:17], v[152:153], v[20:21]
	v_lshlrev_b32_e32 v20, 16, v22
	v_and_b32_e32 v21, 0xffff0000, v22
	v_pk_fma_f32 v[20:21], v[10:11], v[154:155], v[20:21]
	v_lshlrev_b32_e32 v10, 16, v23
	v_and_b32_e32 v11, 0xffff0000, v23
	v_pk_fma_f32 v[14:15], v[14:15], v[156:157], v[24:25]
	v_pk_fma_f32 v[22:23], v[12:13], v[150:151], v[10:11]
	v_cvt_pk_bf16_f32 v10, v14, v15
	v_cvt_pk_bf16_f32 v11, v16, v17
	v_cvt_pk_bf16_f32 v12, v20, v21
	v_cvt_pk_bf16_f32 v13, v22, v23
	global_store_dwordx4 v[18:19], v[10:13], off offset:2048
	s_nop 1
	v_mov_b32_e32 v10, v250
	v_mov_b32_e32 v11, v251
	v_mov_b32_e32 v12, v252
	v_mov_b32_e32 v13, v253
	s_nop 0
	v_lshlrev_b32_e32 v14, 16, v10
	v_and_b32_e32 v15, 0xffff0000, v10
	v_lshlrev_b32_e32 v10, 16, v11
	v_and_b32_e32 v11, 0xffff0000, v11
	v_pk_fma_f32 v[8:9], v[8:9], v[146:147], v[10:11]
	v_lshlrev_b32_e32 v10, 16, v12
	v_and_b32_e32 v11, 0xffff0000, v12
	v_pk_fma_f32 v[10:11], v[2:3], v[144:145], v[10:11]
	v_lshlrev_b32_e32 v2, 16, v13
	v_and_b32_e32 v3, 0xffff0000, v13
	v_pk_fma_f32 v[6:7], v[6:7], v[148:149], v[14:15]
	v_pk_fma_f32 v[12:13], v[4:5], v[142:143], v[2:3]
	v_cvt_pk_bf16_f32 v2, v6, v7
	v_cvt_pk_bf16_f32 v3, v8, v9
	v_cvt_pk_bf16_f32 v4, v10, v11
	v_cvt_pk_bf16_f32 v5, v12, v13
	global_store_dwordx4 v[18:19], v[2:5], off offset:2304
	s_cbranch_vccz .LBB0_1399
	s_waitcnt vmcnt(0)
	s_cmpk_gt_u32 s22, 0xff
	s_cbranch_scc1 .LBB0_1412
	s_barrier
